# best_v4 + GEMM k-loops with two LDS-DMA tiles in flight and ds_read/DMA interleaved into the MFMA stream
# baseline (speedup 1.0000x reference)
.Lto_j_a0:
	s_mul_i32 s98, s98, 17
	s_add_u32 s98, s98, s99
	s_lshl_b32 s99, s98, 3
	s_or_b32 s99, s99, s84
	s_mul_hi_i32 s6, s98, 0x78787879
	s_lshr_b32 s7, s6, 31
	s_ashr_i32 s6, s6, 3
	s_add_i32 s6, s6, s7
	s_mul_i32 s7, s6, 0xffffffef
	s_add_i32 s7, s7, s98
	s_lshl_b32 s7, s7, 3
	s_or_b32 s8, s7, s84
	v_mov_b32_e32 v0, v174
	s_ashr_i32 s9, s8, 31
	s_lshl_b64 s[10:11], s[8:9], 18
	v_bfe_u32 v2, v0, 1, 3
	v_lshrrev_b32_e32 v3, 4, v0
	v_bfe_u32 v4, v0, 4, 2
	v_lshlrev_b32_e32 v5, 7, v0
	v_and_b32_e32 v6, 0x780, v5
	v_bitop3_b32 v3, v3, v2, 3 bitop3:0x6c
	v_bitop3_b32 v2, v4, v2, 4 bitop3:0x36
	s_add_u32 s10, s38, s10
	v_lshl_or_b32 v7, v3, 4, v6
	v_lshl_or_b32 v6, v2, 4, v6
	v_lshlrev_b32_e32 v2, 6, v0
	s_addc_u32 s11, s39, s11
	s_ashr_i32 s7, s6, 31
	v_lshlrev_b32_e32 v1, 8, v0
	v_and_b32_e32 v8, 0xffffe000, v2
	v_lshlrev_b32_e32 v2, 4, v0
	s_lshl_b64 s[12:13], s[6:7], 18
	v_and_b32_e32 v1, 0xfffff800, v1
	v_xor_b32_e32 v0, v2, v0
	s_movk_i32 s7, 0x70
	v_add_u32_e32 v100, 0, v2
	v_and_or_b32 v64, v0, s7, v1
	v_readfirstlane_b32 s7, v100
	v_add_u32_e32 v101, 0x1000, v100
	s_mov_b32 m0, s7
	v_readfirstlane_b32 s7, v101
	v_add_u32_e32 v102, 0x2000, v100
	global_load_lds_dwordx4 v64, s[10:11]
	v_add_u32_e32 v0, 0x10000, v64
	s_mov_b32 m0, s7
	v_readfirstlane_b32 s7, v102
	v_add_u32_e32 v103, 0x3000, v100
	global_load_lds_dwordx4 v0, s[10:11]
	v_add_u32_e32 v2, 0x20000, v64
	s_mov_b32 m0, s7
	v_readfirstlane_b32 s7, v103
	v_add_u32_e32 v104, 0x4000, v100
	s_add_u32 s12, s36, s12
	global_load_lds_dwordx4 v2, s[10:11]
	v_add_u32_e32 v4, 0x30000, v64
	s_mov_b32 m0, s7
	v_readfirstlane_b32 s7, v104
	v_add_u32_e32 v105, 0x5000, v100
	s_addc_u32 s13, s37, s13
	global_load_lds_dwordx4 v4, s[10:11]
	s_mov_b32 m0, s7
	v_readfirstlane_b32 s7, v105
	v_add_u32_e32 v106, 0x6000, v100
	global_load_lds_dwordx4 v64, s[12:13]
	s_mov_b32 m0, s7
	v_readfirstlane_b32 s7, v106
	v_add_u32_e32 v107, 0x7000, v100
	global_load_lds_dwordx4 v0, s[12:13]
	s_mov_b32 m0, s7
	v_readfirstlane_b32 s7, v107
	global_load_lds_dwordx4 v2, s[12:13]
	s_mov_b32 m0, s7
	s_mul_i32 s7, s6, 0x88
	global_load_lds_dwordx4 v4, s[12:13]
	s_sub_i32 s10, s99, s7
	s_ashr_i32 s11, s10, 31
	s_lshl_b64 s[10:11], s[10:11], 18
	v_and_b32_e32 v9, 0x2000, v5
	s_add_u32 s10, s38, s10
	v_mov_b32_e32 v1, v65
	v_mov_b32_e32 v3, v65
	v_mov_b32_e32 v5, v65
	v_add_u32_e32 v8, 0, v8
	v_add_u32_e32 v9, 0, v9
	s_addc_u32 s11, s39, s11
	v_lshl_add_u64 v[66:67], s[12:13], 0, v[64:65]
	v_lshl_add_u64 v[68:69], s[12:13], 0, v[0:1]
	v_lshl_add_u64 v[70:71], s[12:13], 0, v[2:3]
	v_lshl_add_u64 v[72:73], s[12:13], 0, v[4:5]
	v_lshl_add_u64 v[74:75], s[10:11], 0, v[64:65]
	v_lshl_add_u64 v[76:77], s[10:11], 0, v[0:1]
	v_lshl_add_u64 v[78:79], s[10:11], 0, v[2:3]
	v_lshl_add_u64 v[80:81], s[10:11], 0, v[4:5]
	s_mov_b64 s[10:11], 0
	v_add_u32_e32 v64, 0x8000, v100
	v_add_u32_e32 v108, 0x9000, v100
	v_add_u32_e32 v109, 0xa000, v100
	v_add_u32_e32 v110, 0xb000, v100
	v_add_u32_e32 v111, 0xc000, v100
	v_add_u32_e32 v112, 0xd000, v100
	v_add_u32_e32 v113, 0xe000, v100
	v_add_u32_e32 v114, 0xf000, v100
	v_add_u32_e32 v115, v8, v7
	v_add_u32_e32 v116, v9, v7
	v_add_u32_e32 v117, v8, v6
	v_add_u32_e32 v118, v9, v6
	s_mov_b32 s7, 0
	v_mov_b32_e32 v0, 0
	v_mov_b32_e32 v2, v65
	v_mov_b32_e32 v4, 0
	v_mov_b32_e32 v6, v65
	v_mov_b32_e32 v7, v65
	v_mov_b32_e32 v8, 0
	v_mov_b32_e32 v9, v65
	v_mov_b32_e32 v10, v65
	v_mov_b32_e32 v11, v65
	v_mov_b32_e32 v12, 0
	v_mov_b32_e32 v13, v65
	v_mov_b32_e32 v14, v65
	v_mov_b32_e32 v15, v65
	v_mov_b32_e32 v16, 0
	v_mov_b32_e32 v17, v65
	v_mov_b32_e32 v18, v65
	v_mov_b32_e32 v19, v65
	v_mov_b32_e32 v20, 0
	v_mov_b32_e32 v21, v65
	v_mov_b32_e32 v22, v65
	v_mov_b32_e32 v23, v65
	v_mov_b32_e32 v24, 0
	v_mov_b32_e32 v25, v65
	v_mov_b32_e32 v26, v65
	v_mov_b32_e32 v27, v65
	v_mov_b32_e32 v28, 0
	v_mov_b32_e32 v29, v65
	v_mov_b32_e32 v30, v65
	v_mov_b32_e32 v31, v65
	v_mov_b32_e32 v32, 0
	v_mov_b32_e32 v33, v65
	v_mov_b32_e32 v34, v65
	v_mov_b32_e32 v35, v65
	v_mov_b32_e32 v36, 0
	v_mov_b32_e32 v37, v65
	v_mov_b32_e32 v38, v65
	v_mov_b32_e32 v39, v65
	v_mov_b32_e32 v40, 0
	v_mov_b32_e32 v41, v65
	v_mov_b32_e32 v42, v65
	v_mov_b32_e32 v43, v65
	v_mov_b32_e32 v44, 0
	v_mov_b32_e32 v45, v65
	v_mov_b32_e32 v46, v65
	v_mov_b32_e32 v47, v65
	v_mov_b32_e32 v48, 0
	v_mov_b32_e32 v49, v65
	v_mov_b32_e32 v50, v65
	v_mov_b32_e32 v51, v65
	v_mov_b32_e32 v52, 0
	v_mov_b32_e32 v53, v65
	v_mov_b32_e32 v54, v65
	v_mov_b32_e32 v55, v65
	v_mov_b32_e32 v56, 0
	v_mov_b32_e32 v57, v65
	v_mov_b32_e32 v58, v65
	v_mov_b32_e32 v59, v65
	v_mov_b32_e32 v60, 0
	v_mov_b32_e32 v61, v65
	v_mov_b32_e32 v62, v65
	v_mov_b32_e32 v63, v65
	s_mov_b64 s[98:99], s[0:1]
	v_readfirstlane_b32 s9, v64
	v_lshl_add_u64 v[250:251], v[74:75], 0, s[98:99]
	s_mov_b32 m0, s9
	v_readfirstlane_b32 s9, v108
	global_load_lds_dwordx4 v[250:251], off
	v_lshl_add_u64 v[250:251], v[76:77], 0, s[98:99]
	s_mov_b32 m0, s9
	v_readfirstlane_b32 s9, v109
	global_load_lds_dwordx4 v[250:251], off
	v_lshl_add_u64 v[250:251], v[78:79], 0, s[98:99]
	s_mov_b32 m0, s9
	v_readfirstlane_b32 s9, v110
	global_load_lds_dwordx4 v[250:251], off
	v_lshl_add_u64 v[250:251], v[80:81], 0, s[98:99]
	s_mov_b32 m0, s9
	v_readfirstlane_b32 s9, v111
	global_load_lds_dwordx4 v[250:251], off
	v_lshl_add_u64 v[250:251], v[66:67], 0, s[98:99]
	s_mov_b32 m0, s9
	v_readfirstlane_b32 s9, v112
	global_load_lds_dwordx4 v[250:251], off
	v_lshl_add_u64 v[250:251], v[68:69], 0, s[98:99]
	s_mov_b32 m0, s9
	v_readfirstlane_b32 s9, v113
	global_load_lds_dwordx4 v[250:251], off
	v_lshl_add_u64 v[250:251], v[70:71], 0, s[98:99]
	s_mov_b32 m0, s9
	v_readfirstlane_b32 s9, v114
	global_load_lds_dwordx4 v[250:251], off
	v_lshl_add_u64 v[250:251], v[72:73], 0, s[98:99]
	s_mov_b32 m0, s9
	s_nop 0
	global_load_lds_dwordx4 v[250:251], off
	s_branch .LBB0_156
.LBB0_155:
	s_and_b64 vcc, exec, s[12:13]
	s_cbranch_vccnz .Lgp_ol_0
	s_waitcnt vmcnt(8)
	s_branch .Lgp_og_0

.Lgp_og_0:
	s_barrier
	s_nop 1
	ds_read_b128 v[82:85], v115 offset:32768
	ds_read_b128 v[86:89], v115 offset:34816
	ds_read_b128 v[90:93], v115 offset:36864
	ds_read_b128 v[94:97], v115 offset:38912
	ds_read_b128 v[120:123], v116 offset:49152
	ds_read_b128 v[124:127], v116 offset:51200
	ds_read_b128 v[128:131], v116 offset:53248
	ds_read_b128 v[132:135], v116 offset:55296
	s_add_i32 s7, s7, 2
	s_waitcnt lgkmcnt(0)
	v_mfma_f32_16x16x32_f16 v[0:3], v[120:123], v[82:85], v[0:3]
	ds_read_b128 v[136:139], v117 offset:32768
	v_mfma_f32_16x16x32_f16 v[4:7], v[124:127], v[82:85], v[4:7]
	v_mfma_f32_16x16x32_f16 v[8:11], v[128:131], v[82:85], v[8:11]
	ds_read_b128 v[140:143], v117 offset:34816
	v_mfma_f32_16x16x32_f16 v[12:15], v[132:135], v[82:85], v[12:15]
	v_mfma_f32_16x16x32_f16 v[16:19], v[120:123], v[86:89], v[16:19]
	ds_read_b128 v[144:147], v117 offset:36864
	v_mfma_f32_16x16x32_f16 v[20:23], v[124:127], v[86:89], v[20:23]
	v_mfma_f32_16x16x32_f16 v[24:27], v[128:131], v[86:89], v[24:27]
	ds_read_b128 v[148:151], v117 offset:38912
	v_mfma_f32_16x16x32_f16 v[28:31], v[132:135], v[86:89], v[28:31]
	v_mfma_f32_16x16x32_f16 v[82:85], v[120:123], v[90:93], v[32:35]
	ds_read_b128 v[152:155], v118 offset:49152
	v_mfma_f32_16x16x32_f16 v[86:89], v[124:127], v[90:93], v[36:39]
	v_mfma_f32_16x16x32_f16 v[168:171], v[128:131], v[90:93], v[40:43]
	ds_read_b128 v[156:159], v118 offset:51200
	v_mfma_f32_16x16x32_f16 v[90:93], v[132:135], v[90:93], v[44:47]
	v_mfma_f32_16x16x32_f16 v[120:123], v[120:123], v[94:97], v[48:51]
	ds_read_b128 v[160:163], v118 offset:53248
	v_mfma_f32_16x16x32_f16 v[124:127], v[124:127], v[94:97], v[52:55]
	v_mfma_f32_16x16x32_f16 v[128:131], v[128:131], v[94:97], v[56:59]
	ds_read_b128 v[164:167], v118 offset:55296
	v_mfma_f32_16x16x32_f16 v[94:97], v[132:135], v[94:97], v[60:63]
	s_waitcnt lgkmcnt(0)
	s_barrier
	s_and_b64 vcc, exec, s[12:13]
	s_cbranch_vccnz .Lgp_os_0
	s_add_u32 s98, s10, s4
	s_addc_u32 s99, s11, s5
	s_add_u32 s98, s98, 0x80
	s_addc_u32 s99, s99, 0
	v_readfirstlane_b32 s9, v64
	v_mfma_f32_16x16x32_f16 v[60:63], v[152:155], v[136:139], v[0:3]
	v_lshl_add_u64 v[250:251], v[74:75], 0, s[98:99]
	s_mov_b32 m0, s9
	v_readfirstlane_b32 s9, v108
	global_load_lds_dwordx4 v[250:251], off
	v_mfma_f32_16x16x32_f16 v[56:59], v[156:159], v[136:139], v[4:7]
	v_mfma_f32_16x16x32_f16 v[52:55], v[160:163], v[136:139], v[8:11]
	v_lshl_add_u64 v[250:251], v[76:77], 0, s[98:99]
	s_mov_b32 m0, s9
	v_readfirstlane_b32 s9, v109
	global_load_lds_dwordx4 v[250:251], off
	v_mfma_f32_16x16x32_f16 v[48:51], v[164:167], v[136:139], v[12:15]
	v_mfma_f32_16x16x32_f16 v[44:47], v[152:155], v[140:143], v[16:19]
	v_lshl_add_u64 v[250:251], v[78:79], 0, s[98:99]
	s_mov_b32 m0, s9
	v_readfirstlane_b32 s9, v110
	global_load_lds_dwordx4 v[250:251], off
	v_mfma_f32_16x16x32_f16 v[40:43], v[156:159], v[140:143], v[20:23]
	v_mfma_f32_16x16x32_f16 v[36:39], v[160:163], v[140:143], v[24:27]
	v_lshl_add_u64 v[250:251], v[80:81], 0, s[98:99]
	s_mov_b32 m0, s9
	v_readfirstlane_b32 s9, v111
	global_load_lds_dwordx4 v[250:251], off
	v_mfma_f32_16x16x32_f16 v[32:35], v[164:167], v[140:143], v[28:31]
	v_mfma_f32_16x16x32_f16 v[28:31], v[152:155], v[144:147], v[82:85]
	v_lshl_add_u64 v[250:251], v[66:67], 0, s[98:99]
	s_mov_b32 m0, s9
	v_readfirstlane_b32 s9, v112
	global_load_lds_dwordx4 v[250:251], off
	v_mfma_f32_16x16x32_f16 v[24:27], v[156:159], v[144:147], v[86:89]
	v_mfma_f32_16x16x32_f16 v[20:23], v[160:163], v[144:147], v[168:171]
	v_lshl_add_u64 v[250:251], v[68:69], 0, s[98:99]
	s_mov_b32 m0, s9
	v_readfirstlane_b32 s9, v113
	global_load_lds_dwordx4 v[250:251], off
	v_mfma_f32_16x16x32_f16 v[16:19], v[164:167], v[144:147], v[90:93]
	v_mfma_f32_16x16x32_f16 v[12:15], v[152:155], v[148:151], v[120:123]
	v_lshl_add_u64 v[250:251], v[70:71], 0, s[98:99]
	s_mov_b32 m0, s9
	v_readfirstlane_b32 s9, v114
	global_load_lds_dwordx4 v[250:251], off
	v_mfma_f32_16x16x32_f16 v[8:11], v[156:159], v[148:151], v[124:127]
	v_mfma_f32_16x16x32_f16 v[4:7], v[160:163], v[148:151], v[128:131]
	v_lshl_add_u64 v[250:251], v[72:73], 0, s[98:99]
	s_mov_b32 m0, s9
	s_nop 0
	global_load_lds_dwordx4 v[250:251], off
	v_mfma_f32_16x16x32_f16 v[0:3], v[164:167], v[148:151], v[94:97]
	s_branch .Lgp_oj_0
.Lgp_os_0:
	v_mfma_f32_16x16x32_f16 v[60:63], v[152:155], v[136:139], v[0:3]
	v_mfma_f32_16x16x32_f16 v[56:59], v[156:159], v[136:139], v[4:7]
	v_mfma_f32_16x16x32_f16 v[52:55], v[160:163], v[136:139], v[8:11]
	v_mfma_f32_16x16x32_f16 v[48:51], v[164:167], v[136:139], v[12:15]
	v_mfma_f32_16x16x32_f16 v[44:47], v[152:155], v[140:143], v[16:19]
	v_mfma_f32_16x16x32_f16 v[40:43], v[156:159], v[140:143], v[20:23]
	v_mfma_f32_16x16x32_f16 v[36:39], v[160:163], v[140:143], v[24:27]
	v_mfma_f32_16x16x32_f16 v[32:35], v[164:167], v[140:143], v[28:31]
	v_mfma_f32_16x16x32_f16 v[28:31], v[152:155], v[144:147], v[82:85]
	v_mfma_f32_16x16x32_f16 v[24:27], v[156:159], v[144:147], v[86:89]
	v_mfma_f32_16x16x32_f16 v[20:23], v[160:163], v[144:147], v[168:171]
	v_mfma_f32_16x16x32_f16 v[16:19], v[164:167], v[144:147], v[90:93]
	v_mfma_f32_16x16x32_f16 v[12:15], v[152:155], v[148:151], v[120:123]
	v_mfma_f32_16x16x32_f16 v[8:11], v[156:159], v[148:151], v[124:127]
	v_mfma_f32_16x16x32_f16 v[4:7], v[160:163], v[148:151], v[128:131]
	v_mfma_f32_16x16x32_f16 v[0:3], v[164:167], v[148:151], v[94:97]
.Lgp_oj_0:
	s_add_u32 s10, s10, 0x100
	s_addc_u32 s11, s11, 0
	s_andn2_b64 vcc, exec, s[12:13]
	s_cbranch_vccz .LBB0_153
.LBB0_156:
	s_waitcnt vmcnt(8)
	s_barrier
	s_nop 1
	ds_read_b128 v[120:123], v115
	ds_read_b128 v[124:127], v115 offset:2048
	ds_read_b128 v[128:131], v115 offset:4096
	ds_read_b128 v[132:135], v115 offset:6144
	ds_read_b128 v[136:139], v116 offset:16384
	ds_read_b128 v[140:143], v116 offset:18432
	ds_read_b128 v[144:147], v116 offset:20480
	ds_read_b128 v[148:151], v116 offset:22528
	s_cmp_gt_u32 s7, 13
	s_cselect_b64 s[12:13], -1, 0
	s_waitcnt lgkmcnt(0)
	v_mfma_f32_16x16x32_f16 v[60:63], v[136:139], v[120:123], v[60:63]
	ds_read_b128 v[152:155], v117
	v_mfma_f32_16x16x32_f16 v[56:59], v[140:143], v[120:123], v[56:59]
	v_mfma_f32_16x16x32_f16 v[52:55], v[144:147], v[120:123], v[52:55]
	ds_read_b128 v[156:159], v117 offset:2048
	v_mfma_f32_16x16x32_f16 v[48:51], v[148:151], v[120:123], v[48:51]
	v_mfma_f32_16x16x32_f16 v[44:47], v[136:139], v[124:127], v[44:47]
	ds_read_b128 v[160:163], v117 offset:4096
	v_mfma_f32_16x16x32_f16 v[40:43], v[140:143], v[124:127], v[40:43]
	v_mfma_f32_16x16x32_f16 v[36:39], v[144:147], v[124:127], v[36:39]
	ds_read_b128 v[164:167], v117 offset:6144
	v_mfma_f32_16x16x32_f16 v[32:35], v[148:151], v[124:127], v[32:35]
	v_mfma_f32_16x16x32_f16 v[120:123], v[136:139], v[128:131], v[28:31]
	ds_read_b128 v[168:171], v118 offset:16384
	v_mfma_f32_16x16x32_f16 v[124:127], v[140:143], v[128:131], v[24:27]
	v_mfma_f32_16x16x32_f16 v[188:191], v[144:147], v[128:131], v[20:23]
	ds_read_b128 v[176:179], v118 offset:18432
	v_mfma_f32_16x16x32_f16 v[128:131], v[148:151], v[128:131], v[16:19]
	v_mfma_f32_16x16x32_f16 v[136:139], v[136:139], v[132:135], v[12:15]
	ds_read_b128 v[180:183], v118 offset:20480
	v_mfma_f32_16x16x32_f16 v[140:143], v[140:143], v[132:135], v[8:11]
	v_mfma_f32_16x16x32_f16 v[144:147], v[144:147], v[132:135], v[4:7]
	ds_read_b128 v[184:187], v118 offset:22528
	v_mfma_f32_16x16x32_f16 v[132:135], v[148:151], v[132:135], v[0:3]
	s_waitcnt lgkmcnt(0)
	s_barrier
	s_and_b64 vcc, exec, s[12:13]
	s_cbranch_vccnz .Lgp_es_0
	s_add_u32 s98, s10, s4
	s_addc_u32 s99, s11, s5
	v_readfirstlane_b32 s9, v100
	v_mfma_f32_16x16x32_f16 v[0:3], v[168:171], v[152:155], v[60:63]
	v_lshl_add_u64 v[250:251], v[74:75], 0, s[98:99]
	s_mov_b32 m0, s9
	v_readfirstlane_b32 s9, v101
	global_load_lds_dwordx4 v[250:251], off
	v_mfma_f32_16x16x32_f16 v[4:7], v[176:179], v[152:155], v[56:59]
	v_mfma_f32_16x16x32_f16 v[8:11], v[180:183], v[152:155], v[52:55]
	v_lshl_add_u64 v[250:251], v[76:77], 0, s[98:99]
	s_mov_b32 m0, s9
	v_readfirstlane_b32 s9, v102
	global_load_lds_dwordx4 v[250:251], off
	v_mfma_f32_16x16x32_f16 v[12:15], v[184:187], v[152:155], v[48:51]
	v_mfma_f32_16x16x32_f16 v[16:19], v[168:171], v[156:159], v[44:47]
	v_lshl_add_u64 v[250:251], v[78:79], 0, s[98:99]
	s_mov_b32 m0, s9
	v_readfirstlane_b32 s9, v103
	global_load_lds_dwordx4 v[250:251], off
	v_mfma_f32_16x16x32_f16 v[20:23], v[176:179], v[156:159], v[40:43]
	v_mfma_f32_16x16x32_f16 v[24:27], v[180:183], v[156:159], v[36:39]
	v_lshl_add_u64 v[250:251], v[80:81], 0, s[98:99]
	s_mov_b32 m0, s9
	v_readfirstlane_b32 s9, v104
	global_load_lds_dwordx4 v[250:251], off
	v_mfma_f32_16x16x32_f16 v[28:31], v[184:187], v[156:159], v[32:35]
	v_mfma_f32_16x16x32_f16 v[32:35], v[168:171], v[160:163], v[120:123]
	v_lshl_add_u64 v[250:251], v[66:67], 0, s[98:99]
	s_mov_b32 m0, s9
	v_readfirstlane_b32 s9, v105
	global_load_lds_dwordx4 v[250:251], off
	v_mfma_f32_16x16x32_f16 v[36:39], v[176:179], v[160:163], v[124:127]
	v_mfma_f32_16x16x32_f16 v[40:43], v[180:183], v[160:163], v[188:191]
	v_lshl_add_u64 v[250:251], v[68:69], 0, s[98:99]
	s_mov_b32 m0, s9
	v_readfirstlane_b32 s9, v106
	global_load_lds_dwordx4 v[250:251], off
	v_mfma_f32_16x16x32_f16 v[44:47], v[184:187], v[160:163], v[128:131]
	v_mfma_f32_16x16x32_f16 v[48:51], v[168:171], v[164:167], v[136:139]
	v_lshl_add_u64 v[250:251], v[70:71], 0, s[98:99]
	s_mov_b32 m0, s9
	v_readfirstlane_b32 s9, v107
	global_load_lds_dwordx4 v[250:251], off
	v_mfma_f32_16x16x32_f16 v[52:55], v[176:179], v[164:167], v[140:143]
	v_mfma_f32_16x16x32_f16 v[56:59], v[180:183], v[164:167], v[144:147]
	v_lshl_add_u64 v[250:251], v[72:73], 0, s[98:99]
	s_mov_b32 m0, s9
	s_nop 0
	global_load_lds_dwordx4 v[250:251], off
	v_mfma_f32_16x16x32_f16 v[60:63], v[184:187], v[164:167], v[132:135]
	s_branch .Lgp_ej_0
.Lgp_es_0:
	v_mfma_f32_16x16x32_f16 v[0:3], v[168:171], v[152:155], v[60:63]
	v_mfma_f32_16x16x32_f16 v[4:7], v[176:179], v[152:155], v[56:59]
	v_mfma_f32_16x16x32_f16 v[8:11], v[180:183], v[152:155], v[52:55]
	v_mfma_f32_16x16x32_f16 v[12:15], v[184:187], v[152:155], v[48:51]
	v_mfma_f32_16x16x32_f16 v[16:19], v[168:171], v[156:159], v[44:47]
	v_mfma_f32_16x16x32_f16 v[20:23], v[176:179], v[156:159], v[40:43]
	v_mfma_f32_16x16x32_f16 v[24:27], v[180:183], v[156:159], v[36:39]
	v_mfma_f32_16x16x32_f16 v[28:31], v[184:187], v[156:159], v[32:35]
	v_mfma_f32_16x16x32_f16 v[32:35], v[168:171], v[160:163], v[120:123]
	v_mfma_f32_16x16x32_f16 v[36:39], v[176:179], v[160:163], v[124:127]
	v_mfma_f32_16x16x32_f16 v[40:43], v[180:183], v[160:163], v[188:191]
	v_mfma_f32_16x16x32_f16 v[44:47], v[184:187], v[160:163], v[128:131]
	v_mfma_f32_16x16x32_f16 v[48:51], v[168:171], v[164:167], v[136:139]
	v_mfma_f32_16x16x32_f16 v[52:55], v[176:179], v[164:167], v[140:143]
	v_mfma_f32_16x16x32_f16 v[56:59], v[180:183], v[164:167], v[144:147]
	v_mfma_f32_16x16x32_f16 v[60:63], v[184:187], v[164:167], v[132:135]
.Lgp_ej_0:
	s_branch .LBB0_155
.LBB0_158:
	s_waitcnt vmcnt(0)
	s_barrier
	s_mov_b64 s[0:1], exec
	v_readlane_b32 s4, v254, 1
	v_readlane_b32 s5, v254, 2
	s_and_b64 s[4:5], s[0:1], s[4:5]
	s_mov_b64 exec, s[4:5]
	s_cbranch_execz .LBB0_210
	s_add_i32 s3, 0, 0x10000
	v_mov_b32_e32 v0, s3
	s_waitcnt vmcnt(0) expcnt(0) lgkmcnt(0)
	ds_read_b32 v2, v0
	s_add_i32 s3, 0, 0x10004
	v_mov_b32_e32 v0, s3
	ds_read_b32 v0, v0
	s_waitcnt lgkmcnt(1)
	v_cmp_ne_u32_e32 vcc, 0, v2
	s_cbranch_vccnz .LBB0_174
	s_add_u32 s4, s50, 0x1000
	s_addc_u32 s5, s51, 0
	s_add_u32 s6, s50, 0x1100
	s_addc_u32 s7, s51, 0
	s_add_u32 s8, s50, 0x1200
	v_readlane_b32 s3, v254, 0
	s_addc_u32 s9, s51, 0
	s_mul_i32 s3, s29, s3
	s_add_u32 s10, s50, 0x1300
	s_mul_i32 s3, s3, s28
	s_addc_u32 s11, s51, 0
	s_mov_b32 s34, 1
	v_mov_b32_e32 v16, 0
	s_branch .LBB0_162

.Lto_j_a1:
	s_mul_i32 s98, s98, 17
	s_add_u32 s98, s98, s99
	s_lshl_b32 s99, s98, 3
	s_or_b32 s99, s99, s88
	s_mul_hi_i32 s10, s98, 0x78787879
	s_lshr_b32 s11, s10, 31
	s_ashr_i32 s10, s10, 3
	s_add_i32 s10, s10, s11
	s_mul_i32 s11, s10, 0xffffffef
	s_add_i32 s11, s11, s98
	s_lshl_b32 s11, s11, 3
	s_or_b32 s12, s11, s88
	v_mov_b32_e32 v0, v174
	s_ashr_i32 s13, s12, 31
	s_lshl_b64 s[34:35], s[12:13], 18
	v_bfe_u32 v2, v0, 1, 3
	v_lshrrev_b32_e32 v3, 4, v0
	v_bfe_u32 v4, v0, 4, 2
	v_lshlrev_b32_e32 v5, 7, v0
	v_and_b32_e32 v6, 0x780, v5
	v_bitop3_b32 v3, v3, v2, 3 bitop3:0x6c
	v_bitop3_b32 v2, v4, v2, 4 bitop3:0x36
	s_add_u32 s34, s38, s34
	v_lshl_or_b32 v7, v3, 4, v6
	v_lshl_or_b32 v6, v2, 4, v6
	v_lshlrev_b32_e32 v2, 6, v0
	s_addc_u32 s35, s39, s35
	s_ashr_i32 s11, s10, 31
	v_lshlrev_b32_e32 v1, 8, v0
	v_and_b32_e32 v8, 0xffffe000, v2
	v_lshlrev_b32_e32 v2, 4, v0
	s_lshl_b64 s[84:85], s[10:11], 18
	v_and_b32_e32 v1, 0xfffff800, v1
	v_xor_b32_e32 v0, v2, v0
	s_movk_i32 s11, 0x70
	v_add_u32_e32 v100, 0, v2
	v_and_or_b32 v64, v0, s11, v1
	v_readfirstlane_b32 s11, v100
	v_add_u32_e32 v101, 0x1000, v100
	s_mov_b32 m0, s11
	v_readfirstlane_b32 s11, v101
	v_add_u32_e32 v102, 0x2000, v100
	global_load_lds_dwordx4 v64, s[34:35]
	v_add_u32_e32 v0, 0x10000, v64
	s_mov_b32 m0, s11
	v_readfirstlane_b32 s11, v102
	v_add_u32_e32 v103, 0x3000, v100
	global_load_lds_dwordx4 v0, s[34:35]
	v_add_u32_e32 v2, 0x20000, v64
	s_mov_b32 m0, s11
	v_readfirstlane_b32 s11, v103
	v_add_u32_e32 v104, 0x4000, v100
	s_add_u32 s86, s90, s84
	global_load_lds_dwordx4 v2, s[34:35]
	v_add_u32_e32 v4, 0x30000, v64
	s_mov_b32 m0, s11
	v_readfirstlane_b32 s11, v104
	v_add_u32_e32 v105, 0x5000, v100
	s_addc_u32 s87, s91, s85
	global_load_lds_dwordx4 v4, s[34:35]
	s_mov_b32 m0, s11
	v_readfirstlane_b32 s11, v105
	v_add_u32_e32 v106, 0x6000, v100
	global_load_lds_dwordx4 v64, s[86:87]
	s_mov_b32 m0, s11
	v_readfirstlane_b32 s11, v106
	v_add_u32_e32 v107, 0x7000, v100
	global_load_lds_dwordx4 v0, s[86:87]
	s_mov_b32 m0, s11
	v_readfirstlane_b32 s11, v107
	global_load_lds_dwordx4 v2, s[86:87]
	s_mov_b32 m0, s11
	s_mul_i32 s11, s10, 0x88
	global_load_lds_dwordx4 v4, s[86:87]
	s_sub_i32 s34, s99, s11
	s_ashr_i32 s35, s34, 31
	s_lshl_b64 s[34:35], s[34:35], 18
	s_add_u32 s34, s38, s34
	v_and_b32_e32 v9, 0x2000, v5
	v_mov_b32_e32 v1, v65
	v_mov_b32_e32 v3, v65
	v_mov_b32_e32 v5, v65
	s_addc_u32 s35, s39, s35
	v_lshl_add_u64 v[66:67], s[34:35], 0, v[64:65]
	v_lshl_add_u64 v[68:69], s[34:35], 0, v[0:1]
	v_lshl_add_u64 v[70:71], s[34:35], 0, v[2:3]
	v_lshl_add_u64 v[72:73], s[34:35], 0, v[4:5]
	s_add_u32 s34, s36, s84
	v_add_u32_e32 v8, 0, v8
	v_add_u32_e32 v9, 0, v9
	s_addc_u32 s35, s37, s85
	v_lshl_add_u64 v[74:75], s[34:35], 0, v[64:65]
	v_lshl_add_u64 v[76:77], s[34:35], 0, v[0:1]
	v_lshl_add_u64 v[78:79], s[34:35], 0, v[2:3]
	v_lshl_add_u64 v[80:81], s[34:35], 0, v[4:5]
	s_mov_b64 s[84:85], 0
	v_add_u32_e32 v64, 0x8000, v100
	v_add_u32_e32 v108, 0x9000, v100
	v_add_u32_e32 v109, 0xa000, v100
	v_add_u32_e32 v110, 0xb000, v100
	v_add_u32_e32 v111, 0xc000, v100
	v_add_u32_e32 v112, 0xd000, v100
	v_add_u32_e32 v113, 0xe000, v100
	v_add_u32_e32 v114, 0xf000, v100
	v_add_u32_e32 v115, v8, v7
	v_add_u32_e32 v116, v9, v7
	v_add_u32_e32 v117, v8, v6
	v_add_u32_e32 v118, v9, v6
	s_mov_b32 s11, 0
	v_mov_b32_e32 v0, 0
	v_mov_b32_e32 v2, v65
	v_mov_b32_e32 v4, 0
	v_mov_b32_e32 v6, v65
	v_mov_b32_e32 v7, v65
	v_mov_b32_e32 v8, 0
	v_mov_b32_e32 v9, v65
	v_mov_b32_e32 v10, v65
	v_mov_b32_e32 v11, v65
	v_mov_b32_e32 v12, 0
	v_mov_b32_e32 v13, v65
	v_mov_b32_e32 v14, v65
	v_mov_b32_e32 v15, v65
	v_mov_b32_e32 v16, 0
	v_mov_b32_e32 v17, v65
	v_mov_b32_e32 v18, v65
	v_mov_b32_e32 v19, v65
	v_mov_b32_e32 v20, 0
	v_mov_b32_e32 v21, v65
	v_mov_b32_e32 v22, v65
	v_mov_b32_e32 v23, v65
	v_mov_b32_e32 v24, 0
	v_mov_b32_e32 v25, v65
	v_mov_b32_e32 v26, v65
	v_mov_b32_e32 v27, v65
	v_mov_b32_e32 v28, 0
	v_mov_b32_e32 v29, v65
	v_mov_b32_e32 v30, v65
	v_mov_b32_e32 v31, v65
	v_mov_b32_e32 v32, 0
	v_mov_b32_e32 v33, v65
	v_mov_b32_e32 v34, v65
	v_mov_b32_e32 v35, v65
	v_mov_b32_e32 v36, 0
	v_mov_b32_e32 v37, v65
	v_mov_b32_e32 v38, v65
	v_mov_b32_e32 v39, v65
	v_mov_b32_e32 v40, 0
	v_mov_b32_e32 v41, v65
	v_mov_b32_e32 v42, v65
	v_mov_b32_e32 v43, v65
	v_mov_b32_e32 v44, 0
	v_mov_b32_e32 v45, v65
	v_mov_b32_e32 v46, v65
	v_mov_b32_e32 v47, v65
	v_mov_b32_e32 v48, 0
	v_mov_b32_e32 v49, v65
	v_mov_b32_e32 v50, v65
	v_mov_b32_e32 v51, v65
	v_mov_b32_e32 v52, 0
	v_mov_b32_e32 v53, v65
	v_mov_b32_e32 v54, v65
	v_mov_b32_e32 v55, v65
	v_mov_b32_e32 v56, 0
	v_mov_b32_e32 v57, v65
	v_mov_b32_e32 v58, v65
	v_mov_b32_e32 v59, v65
	v_mov_b32_e32 v60, 0
	v_mov_b32_e32 v61, v65
	v_mov_b32_e32 v62, v65
	v_mov_b32_e32 v63, v65
	s_mov_b64 s[98:99], s[0:1]
	s_mov_b64 s[100:101], s[4:5]
	v_readfirstlane_b32 s13, v64
	v_lshl_add_u64 v[250:251], v[66:67], 0, s[98:99]
	s_mov_b32 m0, s13
	v_readfirstlane_b32 s13, v108
	global_load_lds_dwordx4 v[250:251], off
	v_lshl_add_u64 v[250:251], v[68:69], 0, s[98:99]
	s_mov_b32 m0, s13
	v_readfirstlane_b32 s13, v109
	global_load_lds_dwordx4 v[250:251], off
	v_lshl_add_u64 v[250:251], v[70:71], 0, s[98:99]
	s_mov_b32 m0, s13
	v_readfirstlane_b32 s13, v110
	global_load_lds_dwordx4 v[250:251], off
	v_lshl_add_u64 v[250:251], v[72:73], 0, s[98:99]
	s_mov_b32 m0, s13
	v_readfirstlane_b32 s13, v111
	global_load_lds_dwordx4 v[250:251], off
	v_lshl_add_u64 v[250:251], v[74:75], 0, s[100:101]
	s_mov_b32 m0, s13
	v_readfirstlane_b32 s13, v112
	global_load_lds_dwordx4 v[250:251], off
	v_lshl_add_u64 v[250:251], v[76:77], 0, s[100:101]
	s_mov_b32 m0, s13
	v_readfirstlane_b32 s13, v113
	global_load_lds_dwordx4 v[250:251], off
	v_lshl_add_u64 v[250:251], v[78:79], 0, s[100:101]
	s_mov_b32 m0, s13
	v_readfirstlane_b32 s13, v114
	global_load_lds_dwordx4 v[250:251], off
	v_lshl_add_u64 v[250:251], v[80:81], 0, s[100:101]
	s_mov_b32 m0, s13
	s_nop 0
	global_load_lds_dwordx4 v[250:251], off
	s_branch .LBB0_610
.LBB0_609:
	s_and_b64 vcc, exec, s[86:87]
	s_cbranch_vccnz .Lgp_ol_1
	s_waitcnt vmcnt(8)
	s_branch .Lgp_og_1

.Lgp_og_1:
	s_barrier
	s_nop 1
	ds_read_b128 v[82:85], v115 offset:32768
	ds_read_b128 v[86:89], v115 offset:34816
	ds_read_b128 v[90:93], v115 offset:36864
	ds_read_b128 v[94:97], v115 offset:38912
	ds_read_b128 v[120:123], v116 offset:49152
	ds_read_b128 v[124:127], v116 offset:51200
	ds_read_b128 v[128:131], v116 offset:53248
	ds_read_b128 v[132:135], v116 offset:55296
	s_add_i32 s11, s11, 2
	s_waitcnt lgkmcnt(0)
	v_mfma_f32_16x16x32_f16 v[0:3], v[120:123], v[82:85], v[0:3]
	ds_read_b128 v[136:139], v117 offset:32768
	v_mfma_f32_16x16x32_f16 v[4:7], v[124:127], v[82:85], v[4:7]
	v_mfma_f32_16x16x32_f16 v[8:11], v[128:131], v[82:85], v[8:11]
	ds_read_b128 v[140:143], v117 offset:34816
	v_mfma_f32_16x16x32_f16 v[12:15], v[132:135], v[82:85], v[12:15]
	v_mfma_f32_16x16x32_f16 v[16:19], v[120:123], v[86:89], v[16:19]
	ds_read_b128 v[144:147], v117 offset:36864
	v_mfma_f32_16x16x32_f16 v[20:23], v[124:127], v[86:89], v[20:23]
	v_mfma_f32_16x16x32_f16 v[24:27], v[128:131], v[86:89], v[24:27]
	ds_read_b128 v[148:151], v117 offset:38912
	v_mfma_f32_16x16x32_f16 v[28:31], v[132:135], v[86:89], v[28:31]
	v_mfma_f32_16x16x32_f16 v[82:85], v[120:123], v[90:93], v[32:35]
	ds_read_b128 v[152:155], v118 offset:49152
	v_mfma_f32_16x16x32_f16 v[86:89], v[124:127], v[90:93], v[36:39]
	v_mfma_f32_16x16x32_f16 v[168:171], v[128:131], v[90:93], v[40:43]
	ds_read_b128 v[156:159], v118 offset:51200
	v_mfma_f32_16x16x32_f16 v[90:93], v[132:135], v[90:93], v[44:47]
	v_mfma_f32_16x16x32_f16 v[120:123], v[120:123], v[94:97], v[48:51]
	ds_read_b128 v[160:163], v118 offset:53248
	v_mfma_f32_16x16x32_f16 v[124:127], v[124:127], v[94:97], v[52:55]
	v_mfma_f32_16x16x32_f16 v[128:131], v[128:131], v[94:97], v[56:59]
	ds_read_b128 v[164:167], v118 offset:55296
	v_mfma_f32_16x16x32_f16 v[94:97], v[132:135], v[94:97], v[60:63]
	s_waitcnt lgkmcnt(0)
	s_barrier
	s_and_b64 vcc, exec, s[86:87]
	s_cbranch_vccnz .Lgp_os_1
	s_add_u32 s98, s84, s6
	s_addc_u32 s99, s85, s7
	s_add_u32 s98, s98, 0x80
	s_addc_u32 s99, s99, 0
	s_add_u32 s100, s84, s8
	s_addc_u32 s101, s85, s9
	s_add_u32 s100, s100, 0x80
	s_addc_u32 s101, s101, 0
	v_readfirstlane_b32 s13, v64
	v_mfma_f32_16x16x32_f16 v[60:63], v[152:155], v[136:139], v[0:3]
	v_lshl_add_u64 v[250:251], v[66:67], 0, s[98:99]
	s_mov_b32 m0, s13
	v_readfirstlane_b32 s13, v108
	global_load_lds_dwordx4 v[250:251], off
	v_mfma_f32_16x16x32_f16 v[56:59], v[156:159], v[136:139], v[4:7]
	v_mfma_f32_16x16x32_f16 v[52:55], v[160:163], v[136:139], v[8:11]
	v_lshl_add_u64 v[250:251], v[68:69], 0, s[98:99]
	s_mov_b32 m0, s13
	v_readfirstlane_b32 s13, v109
	global_load_lds_dwordx4 v[250:251], off
	v_mfma_f32_16x16x32_f16 v[48:51], v[164:167], v[136:139], v[12:15]
	v_mfma_f32_16x16x32_f16 v[44:47], v[152:155], v[140:143], v[16:19]
	v_lshl_add_u64 v[250:251], v[70:71], 0, s[98:99]
	s_mov_b32 m0, s13
	v_readfirstlane_b32 s13, v110
	global_load_lds_dwordx4 v[250:251], off
	v_mfma_f32_16x16x32_f16 v[40:43], v[156:159], v[140:143], v[20:23]
	v_mfma_f32_16x16x32_f16 v[36:39], v[160:163], v[140:143], v[24:27]
	v_lshl_add_u64 v[250:251], v[72:73], 0, s[98:99]
	s_mov_b32 m0, s13
	v_readfirstlane_b32 s13, v111
	global_load_lds_dwordx4 v[250:251], off
	v_mfma_f32_16x16x32_f16 v[32:35], v[164:167], v[140:143], v[28:31]
	v_mfma_f32_16x16x32_f16 v[28:31], v[152:155], v[144:147], v[82:85]
	v_lshl_add_u64 v[250:251], v[74:75], 0, s[100:101]
	s_mov_b32 m0, s13
	v_readfirstlane_b32 s13, v112
	global_load_lds_dwordx4 v[250:251], off
	v_mfma_f32_16x16x32_f16 v[24:27], v[156:159], v[144:147], v[86:89]
	v_mfma_f32_16x16x32_f16 v[20:23], v[160:163], v[144:147], v[168:171]
	v_lshl_add_u64 v[250:251], v[76:77], 0, s[100:101]
	s_mov_b32 m0, s13
	v_readfirstlane_b32 s13, v113
	global_load_lds_dwordx4 v[250:251], off
	v_mfma_f32_16x16x32_f16 v[16:19], v[164:167], v[144:147], v[90:93]
	v_mfma_f32_16x16x32_f16 v[12:15], v[152:155], v[148:151], v[120:123]
	v_lshl_add_u64 v[250:251], v[78:79], 0, s[100:101]
	s_mov_b32 m0, s13
	v_readfirstlane_b32 s13, v114
	global_load_lds_dwordx4 v[250:251], off
	v_mfma_f32_16x16x32_f16 v[8:11], v[156:159], v[148:151], v[124:127]
	v_mfma_f32_16x16x32_f16 v[4:7], v[160:163], v[148:151], v[128:131]
	v_lshl_add_u64 v[250:251], v[80:81], 0, s[100:101]
	s_mov_b32 m0, s13
	s_nop 0
	global_load_lds_dwordx4 v[250:251], off
	v_mfma_f32_16x16x32_f16 v[0:3], v[164:167], v[148:151], v[94:97]
	s_branch .Lgp_oj_1

.Lgp_oj_1:
	s_add_u32 s84, s84, 0x100
	s_addc_u32 s85, s85, 0
	s_andn2_b64 vcc, exec, s[86:87]
	s_cbranch_vccz .LBB0_607
.LBB0_610:
	s_waitcnt vmcnt(8)
	s_barrier
	s_nop 1
	ds_read_b128 v[120:123], v115
	ds_read_b128 v[124:127], v115 offset:2048
	ds_read_b128 v[128:131], v115 offset:4096
	ds_read_b128 v[132:135], v115 offset:6144
	ds_read_b128 v[136:139], v116 offset:16384
	ds_read_b128 v[140:143], v116 offset:18432
	ds_read_b128 v[144:147], v116 offset:20480
	ds_read_b128 v[148:151], v116 offset:22528
	s_cmp_gt_u32 s11, 13
	s_cselect_b64 s[86:87], -1, 0
	s_waitcnt lgkmcnt(0)
	v_mfma_f32_16x16x32_f16 v[60:63], v[136:139], v[120:123], v[60:63]
	ds_read_b128 v[152:155], v117
	v_mfma_f32_16x16x32_f16 v[56:59], v[140:143], v[120:123], v[56:59]
	v_mfma_f32_16x16x32_f16 v[52:55], v[144:147], v[120:123], v[52:55]
	ds_read_b128 v[156:159], v117 offset:2048
	v_mfma_f32_16x16x32_f16 v[48:51], v[148:151], v[120:123], v[48:51]
	v_mfma_f32_16x16x32_f16 v[44:47], v[136:139], v[124:127], v[44:47]
	ds_read_b128 v[160:163], v117 offset:4096
	v_mfma_f32_16x16x32_f16 v[40:43], v[140:143], v[124:127], v[40:43]
	v_mfma_f32_16x16x32_f16 v[36:39], v[144:147], v[124:127], v[36:39]
	ds_read_b128 v[164:167], v117 offset:6144
	v_mfma_f32_16x16x32_f16 v[32:35], v[148:151], v[124:127], v[32:35]
	v_mfma_f32_16x16x32_f16 v[120:123], v[136:139], v[128:131], v[28:31]
	ds_read_b128 v[168:171], v118 offset:16384
	v_mfma_f32_16x16x32_f16 v[124:127], v[140:143], v[128:131], v[24:27]
	v_mfma_f32_16x16x32_f16 v[188:191], v[144:147], v[128:131], v[20:23]
	ds_read_b128 v[176:179], v118 offset:18432
	v_mfma_f32_16x16x32_f16 v[128:131], v[148:151], v[128:131], v[16:19]
	v_mfma_f32_16x16x32_f16 v[136:139], v[136:139], v[132:135], v[12:15]
	ds_read_b128 v[180:183], v118 offset:20480
	v_mfma_f32_16x16x32_f16 v[140:143], v[140:143], v[132:135], v[8:11]
	v_mfma_f32_16x16x32_f16 v[144:147], v[144:147], v[132:135], v[4:7]
	ds_read_b128 v[184:187], v118 offset:22528
	v_mfma_f32_16x16x32_f16 v[132:135], v[148:151], v[132:135], v[0:3]
	s_waitcnt lgkmcnt(0)
	s_barrier
	s_and_b64 vcc, exec, s[86:87]
	s_cbranch_vccnz .Lgp_es_1
	s_add_u32 s98, s84, s6
	s_addc_u32 s99, s85, s7
	s_add_u32 s100, s84, s8
	s_addc_u32 s101, s85, s9
	v_readfirstlane_b32 s13, v100
	v_mfma_f32_16x16x32_f16 v[0:3], v[168:171], v[152:155], v[60:63]
	v_lshl_add_u64 v[250:251], v[66:67], 0, s[98:99]
	s_mov_b32 m0, s13
	v_readfirstlane_b32 s13, v101
	global_load_lds_dwordx4 v[250:251], off
	v_mfma_f32_16x16x32_f16 v[4:7], v[176:179], v[152:155], v[56:59]
	v_mfma_f32_16x16x32_f16 v[8:11], v[180:183], v[152:155], v[52:55]
	v_lshl_add_u64 v[250:251], v[68:69], 0, s[98:99]
	s_mov_b32 m0, s13
	v_readfirstlane_b32 s13, v102
	global_load_lds_dwordx4 v[250:251], off
	v_mfma_f32_16x16x32_f16 v[12:15], v[184:187], v[152:155], v[48:51]
	v_mfma_f32_16x16x32_f16 v[16:19], v[168:171], v[156:159], v[44:47]
	v_lshl_add_u64 v[250:251], v[70:71], 0, s[98:99]
	s_mov_b32 m0, s13
	v_readfirstlane_b32 s13, v103
	global_load_lds_dwordx4 v[250:251], off
	v_mfma_f32_16x16x32_f16 v[20:23], v[176:179], v[156:159], v[40:43]
	v_mfma_f32_16x16x32_f16 v[24:27], v[180:183], v[156:159], v[36:39]
	v_lshl_add_u64 v[250:251], v[72:73], 0, s[98:99]
	s_mov_b32 m0, s13
	v_readfirstlane_b32 s13, v104
	global_load_lds_dwordx4 v[250:251], off
	v_mfma_f32_16x16x32_f16 v[28:31], v[184:187], v[156:159], v[32:35]
	v_mfma_f32_16x16x32_f16 v[32:35], v[168:171], v[160:163], v[120:123]
	v_lshl_add_u64 v[250:251], v[74:75], 0, s[100:101]
	s_mov_b32 m0, s13
	v_readfirstlane_b32 s13, v105
	global_load_lds_dwordx4 v[250:251], off
	v_mfma_f32_16x16x32_f16 v[36:39], v[176:179], v[160:163], v[124:127]
	v_mfma_f32_16x16x32_f16 v[40:43], v[180:183], v[160:163], v[188:191]
	v_lshl_add_u64 v[250:251], v[76:77], 0, s[100:101]
	s_mov_b32 m0, s13
	v_readfirstlane_b32 s13, v106
	global_load_lds_dwordx4 v[250:251], off
	v_mfma_f32_16x16x32_f16 v[44:47], v[184:187], v[160:163], v[128:131]
	v_mfma_f32_16x16x32_f16 v[48:51], v[168:171], v[164:167], v[136:139]
	v_lshl_add_u64 v[250:251], v[78:79], 0, s[100:101]
	s_mov_b32 m0, s13
	v_readfirstlane_b32 s13, v107
	global_load_lds_dwordx4 v[250:251], off
	v_mfma_f32_16x16x32_f16 v[52:55], v[176:179], v[164:167], v[140:143]
	v_mfma_f32_16x16x32_f16 v[56:59], v[180:183], v[164:167], v[144:147]
	v_lshl_add_u64 v[250:251], v[80:81], 0, s[100:101]
	s_mov_b32 m0, s13
	s_nop 0
	global_load_lds_dwordx4 v[250:251], off
	v_mfma_f32_16x16x32_f16 v[60:63], v[184:187], v[164:167], v[132:135]
	s_branch .Lgp_ej_1

.Lgp_ej_1:
	s_branch .LBB0_609
.LBB0_612:
	s_waitcnt vmcnt(0)
	s_barrier
	s_mov_b64 s[0:1], exec
	v_readlane_b32 s4, v254, 1
	v_readlane_b32 s5, v254, 2
	s_and_b64 s[4:5], s[0:1], s[4:5]
	s_mov_b64 exec, s[4:5]
	s_cbranch_execz .LBB0_664
	s_add_i32 s3, 0, 0x10000
	v_mov_b32_e32 v0, s3
	s_waitcnt vmcnt(0) expcnt(0) lgkmcnt(0)
	ds_read_b32 v2, v0
	s_add_i32 s3, 0, 0x10004
	v_mov_b32_e32 v0, s3
	ds_read_b32 v0, v0
	s_waitcnt lgkmcnt(1)
	v_cmp_ne_u32_e32 vcc, 0, v2
	s_cbranch_vccnz .LBB0_628
	s_add_u32 s4, s50, 0x1000
	s_addc_u32 s5, s51, 0
	s_add_u32 s6, s50, 0x1100
	s_addc_u32 s7, s51, 0
	s_add_u32 s8, s50, 0x1200
	v_readlane_b32 s3, v254, 0
	s_addc_u32 s9, s51, 0
	s_mul_i32 s3, s29, s3
	s_add_u32 s10, s50, 0x1300
	s_mul_i32 s3, s3, s28
	s_addc_u32 s11, s51, 0
	s_mov_b32 s34, 1
	v_mov_b32_e32 v16, 0
	s_branch .LBB0_616

.Lto_j_b1:
	s_mul_i32 s98, s98, 17
	s_add_u32 s98, s98, s99
	s_lshl_b32 s99, s98, 3
	s_or_b32 s99, s99, s90
	s_mul_hi_i32 s10, s98, 0x78787879
	s_lshr_b32 s11, s10, 31
	s_ashr_i32 s10, s10, 3
	s_add_i32 s10, s10, s11
	s_mul_i32 s11, s10, 0xffffffef
	s_add_i32 s11, s11, s98
	s_lshl_b32 s11, s11, 3
	s_or_b32 s12, s11, s90
	v_mov_b32_e32 v0, v174
	s_ashr_i32 s13, s12, 31
	s_lshl_b64 s[34:35], s[12:13], 18
	v_bfe_u32 v2, v0, 1, 3
	v_lshrrev_b32_e32 v3, 4, v0
	s_waitcnt vmcnt(5)
	v_bfe_u32 v4, v0, 4, 2
	v_lshlrev_b32_e32 v5, 7, v0
	v_and_b32_e32 v6, 0x780, v5
	v_bitop3_b32 v3, v3, v2, 3 bitop3:0x6c
	v_bitop3_b32 v2, v4, v2, 4 bitop3:0x36
	s_add_u32 s34, s38, s34
	v_lshl_or_b32 v7, v3, 4, v6
	v_lshl_or_b32 v6, v2, 4, v6
	v_lshlrev_b32_e32 v2, 6, v0
	s_addc_u32 s35, s39, s35
	s_ashr_i32 s11, s10, 31
	v_lshlrev_b32_e32 v1, 8, v0
	v_and_b32_e32 v8, 0xffffe000, v2
	v_lshlrev_b32_e32 v2, 4, v0
	s_lshl_b64 s[84:85], s[10:11], 18
	v_and_b32_e32 v1, 0xfffff800, v1
	v_xor_b32_e32 v0, v2, v0
	s_movk_i32 s11, 0x70
	v_add_u32_e32 v100, 0, v2
	v_and_or_b32 v64, v0, s11, v1
	v_readfirstlane_b32 s11, v100
	v_add_u32_e32 v101, 0x1000, v100
	s_mov_b32 m0, s11
	v_readfirstlane_b32 s11, v101
	v_add_u32_e32 v102, 0x2000, v100
	global_load_lds_dwordx4 v64, s[34:35]
	v_add_u32_e32 v0, 0x10000, v64
	s_mov_b32 m0, s11
	v_readfirstlane_b32 s11, v102
	v_add_u32_e32 v103, 0x3000, v100
	global_load_lds_dwordx4 v0, s[34:35]
	v_add_u32_e32 v2, 0x20000, v64
	s_mov_b32 m0, s11
	v_readfirstlane_b32 s11, v103
	v_add_u32_e32 v104, 0x4000, v100
	s_add_u32 s88, s70, s84
	global_load_lds_dwordx4 v2, s[34:35]
	v_add_u32_e32 v4, 0x30000, v64
	s_mov_b32 m0, s11
	v_readfirstlane_b32 s11, v104
	v_add_u32_e32 v105, 0x5000, v100
	s_addc_u32 s89, s71, s85
	global_load_lds_dwordx4 v4, s[34:35]
	s_mov_b32 m0, s11
	v_readfirstlane_b32 s11, v105
	v_add_u32_e32 v106, 0x6000, v100
	global_load_lds_dwordx4 v64, s[88:89]
	s_mov_b32 m0, s11
	v_readfirstlane_b32 s11, v106
	v_add_u32_e32 v107, 0x7000, v100
	global_load_lds_dwordx4 v0, s[88:89]
	s_mov_b32 m0, s11
	v_readfirstlane_b32 s11, v107
	global_load_lds_dwordx4 v2, s[88:89]
	s_mov_b32 m0, s11
	s_mul_i32 s11, s10, 0x88
	global_load_lds_dwordx4 v4, s[88:89]
	s_sub_i32 s34, s99, s11
	s_ashr_i32 s35, s34, 31
	s_lshl_b64 s[34:35], s[34:35], 18
	s_add_u32 s34, s38, s34
	v_and_b32_e32 v9, 0x2000, v5
	v_mov_b32_e32 v1, v65
	v_mov_b32_e32 v3, v65
	v_mov_b32_e32 v5, v65
	s_addc_u32 s35, s39, s35
	v_lshl_add_u64 v[66:67], s[34:35], 0, v[64:65]
	v_lshl_add_u64 v[68:69], s[34:35], 0, v[0:1]
	v_lshl_add_u64 v[70:71], s[34:35], 0, v[2:3]
	v_lshl_add_u64 v[72:73], s[34:35], 0, v[4:5]
	s_add_u32 s34, s36, s84
	v_add_u32_e32 v8, 0, v8
	v_add_u32_e32 v9, 0, v9
	s_addc_u32 s35, s37, s85
	v_lshl_add_u64 v[74:75], s[34:35], 0, v[64:65]
	v_lshl_add_u64 v[76:77], s[34:35], 0, v[0:1]
	v_lshl_add_u64 v[78:79], s[34:35], 0, v[2:3]
	v_lshl_add_u64 v[80:81], s[34:35], 0, v[4:5]
	s_mov_b64 s[84:85], 0
	v_add_u32_e32 v64, 0x8000, v100
	v_add_u32_e32 v108, 0x9000, v100
	v_add_u32_e32 v109, 0xa000, v100
	v_add_u32_e32 v110, 0xb000, v100
	v_add_u32_e32 v111, 0xc000, v100
	v_add_u32_e32 v112, 0xd000, v100
	v_add_u32_e32 v113, 0xe000, v100
	v_add_u32_e32 v114, 0xf000, v100
	v_add_u32_e32 v115, v8, v7
	v_add_u32_e32 v116, v9, v7
	v_add_u32_e32 v117, v8, v6
	v_add_u32_e32 v118, v9, v6
	s_mov_b32 s11, 0
	v_mov_b32_e32 v0, 0
	v_mov_b32_e32 v2, v65
	v_mov_b32_e32 v4, 0
	v_mov_b32_e32 v6, v65
	v_mov_b32_e32 v7, v65
	v_mov_b32_e32 v8, 0
	v_mov_b32_e32 v9, v65
	v_mov_b32_e32 v10, v65
	v_mov_b32_e32 v11, v65
	v_mov_b32_e32 v12, 0
	v_mov_b32_e32 v13, v65
	v_mov_b32_e32 v14, v65
	v_mov_b32_e32 v15, v65
	v_mov_b32_e32 v16, 0
	v_mov_b32_e32 v17, v65
	v_mov_b32_e32 v18, v65
	v_mov_b32_e32 v19, v65
	v_mov_b32_e32 v20, 0
	v_mov_b32_e32 v21, v65
	v_mov_b32_e32 v22, v65
	v_mov_b32_e32 v23, v65
	v_mov_b32_e32 v24, 0
	v_mov_b32_e32 v25, v65
	v_mov_b32_e32 v26, v65
	v_mov_b32_e32 v27, v65
	v_mov_b32_e32 v28, 0
	v_mov_b32_e32 v29, v65
	v_mov_b32_e32 v30, v65
	v_mov_b32_e32 v31, v65
	v_mov_b32_e32 v32, 0
	v_mov_b32_e32 v33, v65
	v_mov_b32_e32 v34, v65
	v_mov_b32_e32 v35, v65
	v_mov_b32_e32 v36, 0
	v_mov_b32_e32 v37, v65
	v_mov_b32_e32 v38, v65
	v_mov_b32_e32 v39, v65
	v_mov_b32_e32 v40, 0
	v_mov_b32_e32 v41, v65
	v_mov_b32_e32 v42, v65
	v_mov_b32_e32 v43, v65
	v_mov_b32_e32 v44, 0
	v_mov_b32_e32 v45, v65
	v_mov_b32_e32 v46, v65
	v_mov_b32_e32 v47, v65
	v_mov_b32_e32 v48, 0
	v_mov_b32_e32 v49, v65
	v_mov_b32_e32 v50, v65
	v_mov_b32_e32 v51, v65
	v_mov_b32_e32 v52, 0
	v_mov_b32_e32 v53, v65
	s_waitcnt vmcnt(0)
	v_mov_b32_e32 v54, v65
	v_mov_b32_e32 v55, v65
	v_mov_b32_e32 v56, 0
	v_mov_b32_e32 v57, v65
	v_mov_b32_e32 v58, v65
	v_mov_b32_e32 v59, v65
	v_mov_b32_e32 v60, 0
	v_mov_b32_e32 v61, v65
	v_mov_b32_e32 v62, v65
	v_mov_b32_e32 v63, v65
	s_mov_b64 s[98:99], s[0:1]
	s_mov_b64 s[100:101], s[4:5]
	v_readfirstlane_b32 s13, v64
	v_lshl_add_u64 v[250:251], v[66:67], 0, s[98:99]
	s_mov_b32 m0, s13
	v_readfirstlane_b32 s13, v108
	global_load_lds_dwordx4 v[250:251], off
	v_lshl_add_u64 v[250:251], v[68:69], 0, s[98:99]
	s_mov_b32 m0, s13
	v_readfirstlane_b32 s13, v109
	global_load_lds_dwordx4 v[250:251], off
	v_lshl_add_u64 v[250:251], v[70:71], 0, s[98:99]
	s_mov_b32 m0, s13
	v_readfirstlane_b32 s13, v110
	global_load_lds_dwordx4 v[250:251], off
	v_lshl_add_u64 v[250:251], v[72:73], 0, s[98:99]
	s_mov_b32 m0, s13
	v_readfirstlane_b32 s13, v111
	global_load_lds_dwordx4 v[250:251], off
	v_lshl_add_u64 v[250:251], v[74:75], 0, s[100:101]
	s_mov_b32 m0, s13
	v_readfirstlane_b32 s13, v112
	global_load_lds_dwordx4 v[250:251], off
	v_lshl_add_u64 v[250:251], v[76:77], 0, s[100:101]
	s_mov_b32 m0, s13
	v_readfirstlane_b32 s13, v113
	global_load_lds_dwordx4 v[250:251], off
	v_lshl_add_u64 v[250:251], v[78:79], 0, s[100:101]
	s_mov_b32 m0, s13
	v_readfirstlane_b32 s13, v114
	global_load_lds_dwordx4 v[250:251], off
	v_lshl_add_u64 v[250:251], v[80:81], 0, s[100:101]
	s_mov_b32 m0, s13
	s_nop 0
	global_load_lds_dwordx4 v[250:251], off
	s_branch .LBB0_752
.LBB0_751:
	s_and_b64 vcc, exec, s[88:89]
	s_cbranch_vccnz .Lgp_ol_2
	s_waitcnt vmcnt(8)
	s_branch .Lgp_og_2

.Lgp_og_2:
	s_barrier
	s_nop 1
	ds_read_b128 v[82:85], v115 offset:32768
	ds_read_b128 v[86:89], v115 offset:34816
	ds_read_b128 v[90:93], v115 offset:36864
	ds_read_b128 v[94:97], v115 offset:38912
	ds_read_b128 v[120:123], v116 offset:49152
	ds_read_b128 v[124:127], v116 offset:51200
	ds_read_b128 v[128:131], v116 offset:53248
	ds_read_b128 v[132:135], v116 offset:55296
	s_add_i32 s11, s11, 2
	s_waitcnt lgkmcnt(0)
	v_mfma_f32_16x16x32_f16 v[0:3], v[120:123], v[82:85], v[0:3]
	ds_read_b128 v[136:139], v117 offset:32768
	v_mfma_f32_16x16x32_f16 v[4:7], v[124:127], v[82:85], v[4:7]
	v_mfma_f32_16x16x32_f16 v[8:11], v[128:131], v[82:85], v[8:11]
	ds_read_b128 v[140:143], v117 offset:34816
	v_mfma_f32_16x16x32_f16 v[12:15], v[132:135], v[82:85], v[12:15]
	v_mfma_f32_16x16x32_f16 v[16:19], v[120:123], v[86:89], v[16:19]
	ds_read_b128 v[144:147], v117 offset:36864
	v_mfma_f32_16x16x32_f16 v[20:23], v[124:127], v[86:89], v[20:23]
	v_mfma_f32_16x16x32_f16 v[24:27], v[128:131], v[86:89], v[24:27]
	ds_read_b128 v[148:151], v117 offset:38912
	v_mfma_f32_16x16x32_f16 v[28:31], v[132:135], v[86:89], v[28:31]
	v_mfma_f32_16x16x32_f16 v[82:85], v[120:123], v[90:93], v[32:35]
	ds_read_b128 v[152:155], v118 offset:49152
	v_mfma_f32_16x16x32_f16 v[86:89], v[124:127], v[90:93], v[36:39]
	v_mfma_f32_16x16x32_f16 v[168:171], v[128:131], v[90:93], v[40:43]
	ds_read_b128 v[156:159], v118 offset:51200
	v_mfma_f32_16x16x32_f16 v[90:93], v[132:135], v[90:93], v[44:47]
	v_mfma_f32_16x16x32_f16 v[120:123], v[120:123], v[94:97], v[48:51]
	ds_read_b128 v[160:163], v118 offset:53248
	v_mfma_f32_16x16x32_f16 v[124:127], v[124:127], v[94:97], v[52:55]
	v_mfma_f32_16x16x32_f16 v[128:131], v[128:131], v[94:97], v[56:59]
	ds_read_b128 v[164:167], v118 offset:55296
	v_mfma_f32_16x16x32_f16 v[94:97], v[132:135], v[94:97], v[60:63]
	s_waitcnt lgkmcnt(0)
	s_barrier
	s_and_b64 vcc, exec, s[88:89]
	s_cbranch_vccnz .Lgp_os_2
	s_add_u32 s98, s84, s6
	s_addc_u32 s99, s85, s7
	s_add_u32 s98, s98, 0x80
	s_addc_u32 s99, s99, 0
	s_add_u32 s100, s84, s8
	s_addc_u32 s101, s85, s9
	s_add_u32 s100, s100, 0x80
	s_addc_u32 s101, s101, 0
	v_readfirstlane_b32 s13, v64
	v_mfma_f32_16x16x32_f16 v[60:63], v[152:155], v[136:139], v[0:3]
	v_lshl_add_u64 v[250:251], v[66:67], 0, s[98:99]
	s_mov_b32 m0, s13
	v_readfirstlane_b32 s13, v108
	global_load_lds_dwordx4 v[250:251], off
	v_mfma_f32_16x16x32_f16 v[56:59], v[156:159], v[136:139], v[4:7]
	v_mfma_f32_16x16x32_f16 v[52:55], v[160:163], v[136:139], v[8:11]
	v_lshl_add_u64 v[250:251], v[68:69], 0, s[98:99]
	s_mov_b32 m0, s13
	v_readfirstlane_b32 s13, v109
	global_load_lds_dwordx4 v[250:251], off
	v_mfma_f32_16x16x32_f16 v[48:51], v[164:167], v[136:139], v[12:15]
	v_mfma_f32_16x16x32_f16 v[44:47], v[152:155], v[140:143], v[16:19]
	v_lshl_add_u64 v[250:251], v[70:71], 0, s[98:99]
	s_mov_b32 m0, s13
	v_readfirstlane_b32 s13, v110
	global_load_lds_dwordx4 v[250:251], off
	v_mfma_f32_16x16x32_f16 v[40:43], v[156:159], v[140:143], v[20:23]
	v_mfma_f32_16x16x32_f16 v[36:39], v[160:163], v[140:143], v[24:27]
	v_lshl_add_u64 v[250:251], v[72:73], 0, s[98:99]
	s_mov_b32 m0, s13
	v_readfirstlane_b32 s13, v111
	global_load_lds_dwordx4 v[250:251], off
	v_mfma_f32_16x16x32_f16 v[32:35], v[164:167], v[140:143], v[28:31]
	v_mfma_f32_16x16x32_f16 v[28:31], v[152:155], v[144:147], v[82:85]
	v_lshl_add_u64 v[250:251], v[74:75], 0, s[100:101]
	s_mov_b32 m0, s13
	v_readfirstlane_b32 s13, v112
	global_load_lds_dwordx4 v[250:251], off
	v_mfma_f32_16x16x32_f16 v[24:27], v[156:159], v[144:147], v[86:89]
	v_mfma_f32_16x16x32_f16 v[20:23], v[160:163], v[144:147], v[168:171]
	v_lshl_add_u64 v[250:251], v[76:77], 0, s[100:101]
	s_mov_b32 m0, s13
	v_readfirstlane_b32 s13, v113
	global_load_lds_dwordx4 v[250:251], off
	v_mfma_f32_16x16x32_f16 v[16:19], v[164:167], v[144:147], v[90:93]
	v_mfma_f32_16x16x32_f16 v[12:15], v[152:155], v[148:151], v[120:123]
	v_lshl_add_u64 v[250:251], v[78:79], 0, s[100:101]
	s_mov_b32 m0, s13
	v_readfirstlane_b32 s13, v114
	global_load_lds_dwordx4 v[250:251], off
	v_mfma_f32_16x16x32_f16 v[8:11], v[156:159], v[148:151], v[124:127]
	v_mfma_f32_16x16x32_f16 v[4:7], v[160:163], v[148:151], v[128:131]
	v_lshl_add_u64 v[250:251], v[80:81], 0, s[100:101]
	s_mov_b32 m0, s13
	s_nop 0
	global_load_lds_dwordx4 v[250:251], off
	v_mfma_f32_16x16x32_f16 v[0:3], v[164:167], v[148:151], v[94:97]
	s_branch .Lgp_oj_2

.Lgp_oj_2:
	s_add_u32 s84, s84, 0x100
	s_addc_u32 s85, s85, 0
	s_andn2_b64 vcc, exec, s[88:89]
	s_cbranch_vccz .LBB0_749
.LBB0_752:
	s_waitcnt vmcnt(8)
	s_barrier
	s_nop 1
	ds_read_b128 v[120:123], v115
	ds_read_b128 v[124:127], v115 offset:2048
	ds_read_b128 v[128:131], v115 offset:4096
	ds_read_b128 v[132:135], v115 offset:6144
	ds_read_b128 v[136:139], v116 offset:16384
	ds_read_b128 v[140:143], v116 offset:18432
	ds_read_b128 v[144:147], v116 offset:20480
	ds_read_b128 v[148:151], v116 offset:22528
	s_cmp_gt_u32 s11, 13
	s_cselect_b64 s[88:89], -1, 0
	s_waitcnt lgkmcnt(0)
	v_mfma_f32_16x16x32_f16 v[60:63], v[136:139], v[120:123], v[60:63]
	ds_read_b128 v[152:155], v117
	v_mfma_f32_16x16x32_f16 v[56:59], v[140:143], v[120:123], v[56:59]
	v_mfma_f32_16x16x32_f16 v[52:55], v[144:147], v[120:123], v[52:55]
	ds_read_b128 v[156:159], v117 offset:2048
	v_mfma_f32_16x16x32_f16 v[48:51], v[148:151], v[120:123], v[48:51]
	v_mfma_f32_16x16x32_f16 v[44:47], v[136:139], v[124:127], v[44:47]
	ds_read_b128 v[160:163], v117 offset:4096
	v_mfma_f32_16x16x32_f16 v[40:43], v[140:143], v[124:127], v[40:43]
	v_mfma_f32_16x16x32_f16 v[36:39], v[144:147], v[124:127], v[36:39]
	ds_read_b128 v[164:167], v117 offset:6144
	v_mfma_f32_16x16x32_f16 v[32:35], v[148:151], v[124:127], v[32:35]
	v_mfma_f32_16x16x32_f16 v[120:123], v[136:139], v[128:131], v[28:31]
	ds_read_b128 v[168:171], v118 offset:16384
	v_mfma_f32_16x16x32_f16 v[124:127], v[140:143], v[128:131], v[24:27]
	v_mfma_f32_16x16x32_f16 v[188:191], v[144:147], v[128:131], v[20:23]
	ds_read_b128 v[176:179], v118 offset:18432
	v_mfma_f32_16x16x32_f16 v[128:131], v[148:151], v[128:131], v[16:19]
	v_mfma_f32_16x16x32_f16 v[136:139], v[136:139], v[132:135], v[12:15]
	ds_read_b128 v[180:183], v118 offset:20480
	v_mfma_f32_16x16x32_f16 v[140:143], v[140:143], v[132:135], v[8:11]
	v_mfma_f32_16x16x32_f16 v[144:147], v[144:147], v[132:135], v[4:7]
	ds_read_b128 v[184:187], v118 offset:22528
	v_mfma_f32_16x16x32_f16 v[132:135], v[148:151], v[132:135], v[0:3]
	s_waitcnt lgkmcnt(0)
	s_barrier
	s_and_b64 vcc, exec, s[88:89]
	s_cbranch_vccnz .Lgp_es_2
	s_add_u32 s98, s84, s6
	s_addc_u32 s99, s85, s7
	s_add_u32 s100, s84, s8
	s_addc_u32 s101, s85, s9
	v_readfirstlane_b32 s13, v100
	v_mfma_f32_16x16x32_f16 v[0:3], v[168:171], v[152:155], v[60:63]
	v_lshl_add_u64 v[250:251], v[66:67], 0, s[98:99]
	s_mov_b32 m0, s13
	v_readfirstlane_b32 s13, v101
	global_load_lds_dwordx4 v[250:251], off
	v_mfma_f32_16x16x32_f16 v[4:7], v[176:179], v[152:155], v[56:59]
	v_mfma_f32_16x16x32_f16 v[8:11], v[180:183], v[152:155], v[52:55]
	v_lshl_add_u64 v[250:251], v[68:69], 0, s[98:99]
	s_mov_b32 m0, s13
	v_readfirstlane_b32 s13, v102
	global_load_lds_dwordx4 v[250:251], off
	v_mfma_f32_16x16x32_f16 v[12:15], v[184:187], v[152:155], v[48:51]
	v_mfma_f32_16x16x32_f16 v[16:19], v[168:171], v[156:159], v[44:47]
	v_lshl_add_u64 v[250:251], v[70:71], 0, s[98:99]
	s_mov_b32 m0, s13
	v_readfirstlane_b32 s13, v103
	global_load_lds_dwordx4 v[250:251], off
	v_mfma_f32_16x16x32_f16 v[20:23], v[176:179], v[156:159], v[40:43]
	v_mfma_f32_16x16x32_f16 v[24:27], v[180:183], v[156:159], v[36:39]
	v_lshl_add_u64 v[250:251], v[72:73], 0, s[98:99]
	s_mov_b32 m0, s13
	v_readfirstlane_b32 s13, v104
	global_load_lds_dwordx4 v[250:251], off
	v_mfma_f32_16x16x32_f16 v[28:31], v[184:187], v[156:159], v[32:35]
	v_mfma_f32_16x16x32_f16 v[32:35], v[168:171], v[160:163], v[120:123]
	v_lshl_add_u64 v[250:251], v[74:75], 0, s[100:101]
	s_mov_b32 m0, s13
	v_readfirstlane_b32 s13, v105
	global_load_lds_dwordx4 v[250:251], off
	v_mfma_f32_16x16x32_f16 v[36:39], v[176:179], v[160:163], v[124:127]
	v_mfma_f32_16x16x32_f16 v[40:43], v[180:183], v[160:163], v[188:191]
	v_lshl_add_u64 v[250:251], v[76:77], 0, s[100:101]
	s_mov_b32 m0, s13
	v_readfirstlane_b32 s13, v106
	global_load_lds_dwordx4 v[250:251], off
	v_mfma_f32_16x16x32_f16 v[44:47], v[184:187], v[160:163], v[128:131]
	v_mfma_f32_16x16x32_f16 v[48:51], v[168:171], v[164:167], v[136:139]
	v_lshl_add_u64 v[250:251], v[78:79], 0, s[100:101]
	s_mov_b32 m0, s13
	v_readfirstlane_b32 s13, v107
	global_load_lds_dwordx4 v[250:251], off
	v_mfma_f32_16x16x32_f16 v[52:55], v[176:179], v[164:167], v[140:143]
	v_mfma_f32_16x16x32_f16 v[56:59], v[180:183], v[164:167], v[144:147]
	v_lshl_add_u64 v[250:251], v[80:81], 0, s[100:101]
	s_mov_b32 m0, s13
	s_nop 0
	global_load_lds_dwordx4 v[250:251], off
	v_mfma_f32_16x16x32_f16 v[60:63], v[184:187], v[164:167], v[132:135]
	s_branch .Lgp_ej_2

.Lgp_ej_2:
	s_branch .LBB0_751
.LBB0_754:
	s_waitcnt vmcnt(0)
	s_barrier
	s_mov_b64 s[0:1], exec
	v_readlane_b32 s4, v254, 1
	v_readlane_b32 s5, v254, 2
	s_and_b64 s[4:5], s[0:1], s[4:5]
	s_mov_b64 exec, s[4:5]
	s_cbranch_execz .LBB0_806
	s_add_i32 s3, 0, 0x10000
	v_mov_b32_e32 v0, s3
	s_waitcnt vmcnt(0) expcnt(0) lgkmcnt(0)
	ds_read_b32 v2, v0
	s_add_i32 s3, 0, 0x10004
	v_mov_b32_e32 v0, s3
	ds_read_b32 v0, v0
	s_waitcnt lgkmcnt(1)
	v_cmp_ne_u32_e32 vcc, 0, v2
	s_cbranch_vccnz .LBB0_770
	s_add_u32 s4, s50, 0x1000
	s_addc_u32 s5, s51, 0
	s_add_u32 s6, s50, 0x1100
	s_addc_u32 s7, s51, 0
	s_add_u32 s8, s50, 0x1200
	v_readlane_b32 s3, v254, 0
	s_addc_u32 s9, s51, 0
	s_mul_i32 s3, s29, s3
	s_add_u32 s10, s50, 0x1300
	s_mul_i32 s3, s3, s28
	s_addc_u32 s11, s51, 0
	s_mov_b32 s34, 1
	v_mov_b32_e32 v16, 0
	s_branch .LBB0_758

.Lto_j_a2:
	s_mul_i32 s98, s98, 17
	s_add_u32 s98, s98, s99
	s_lshl_b32 s99, s98, 3
	s_or_b32 s99, s99, s90
	s_mul_hi_i32 s10, s98, 0x78787879
	s_lshr_b32 s11, s10, 31
	s_ashr_i32 s10, s10, 3
	s_add_i32 s10, s10, s11
	s_mul_i32 s11, s10, 0xffffffef
	s_add_i32 s11, s11, s98
	s_lshl_b32 s11, s11, 3
	s_or_b32 s12, s11, s90
	v_mov_b32_e32 v0, v174
	s_ashr_i32 s13, s12, 31
	s_lshl_b64 s[34:35], s[12:13], 18
	v_bfe_u32 v2, v0, 1, 3
	v_lshrrev_b32_e32 v3, 4, v0
	v_bfe_u32 v4, v0, 4, 2
	v_lshlrev_b32_e32 v5, 7, v0
	v_and_b32_e32 v6, 0x780, v5
	v_bitop3_b32 v3, v3, v2, 3 bitop3:0x6c
	v_bitop3_b32 v2, v4, v2, 4 bitop3:0x36
	s_add_u32 s34, s38, s34
	v_lshl_or_b32 v7, v3, 4, v6
	v_lshl_or_b32 v6, v2, 4, v6
	v_lshlrev_b32_e32 v2, 6, v0
	s_addc_u32 s35, s39, s35
	s_ashr_i32 s11, s10, 31
	v_lshlrev_b32_e32 v1, 8, v0
	v_and_b32_e32 v8, 0xffffe000, v2
	v_lshlrev_b32_e32 v2, 4, v0
	s_lshl_b64 s[84:85], s[10:11], 18
	v_and_b32_e32 v1, 0xfffff800, v1
	v_xor_b32_e32 v0, v2, v0
	s_movk_i32 s11, 0x70
	v_add_u32_e32 v100, 0, v2
	v_and_or_b32 v64, v0, s11, v1
	v_readfirstlane_b32 s11, v100
	v_add_u32_e32 v101, 0x1000, v100
	s_mov_b32 m0, s11
	v_readfirstlane_b32 s11, v101
	v_add_u32_e32 v102, 0x2000, v100
	global_load_lds_dwordx4 v64, s[34:35]
	v_add_u32_e32 v0, 0x10000, v64
	s_mov_b32 m0, s11
	v_readfirstlane_b32 s11, v102
	v_add_u32_e32 v103, 0x3000, v100
	global_load_lds_dwordx4 v0, s[34:35]
	v_add_u32_e32 v2, 0x20000, v64
	s_mov_b32 m0, s11
	v_readfirstlane_b32 s11, v103
	v_add_u32_e32 v104, 0x4000, v100
	s_add_u32 s88, s92, s84
	global_load_lds_dwordx4 v2, s[34:35]
	v_add_u32_e32 v4, 0x30000, v64
	s_mov_b32 m0, s11
	v_readfirstlane_b32 s11, v104
	v_add_u32_e32 v105, 0x5000, v100
	s_addc_u32 s89, s93, s85
	global_load_lds_dwordx4 v4, s[34:35]
	s_mov_b32 m0, s11
	v_readfirstlane_b32 s11, v105
	v_add_u32_e32 v106, 0x6000, v100
	global_load_lds_dwordx4 v64, s[88:89]
	s_mov_b32 m0, s11
	v_readfirstlane_b32 s11, v106
	v_add_u32_e32 v107, 0x7000, v100
	global_load_lds_dwordx4 v0, s[88:89]
	s_mov_b32 m0, s11
	v_readfirstlane_b32 s11, v107
	global_load_lds_dwordx4 v2, s[88:89]
	s_mov_b32 m0, s11
	s_mul_i32 s11, s10, 0x88
	global_load_lds_dwordx4 v4, s[88:89]
	s_sub_i32 s34, s99, s11
	s_ashr_i32 s35, s34, 31
	s_lshl_b64 s[34:35], s[34:35], 18
	s_add_u32 s34, s38, s34
	v_and_b32_e32 v9, 0x2000, v5
	v_mov_b32_e32 v1, v65
	v_mov_b32_e32 v3, v65
	v_mov_b32_e32 v5, v65
	s_addc_u32 s35, s39, s35
	v_lshl_add_u64 v[66:67], s[34:35], 0, v[64:65]
	v_lshl_add_u64 v[68:69], s[34:35], 0, v[0:1]
	v_lshl_add_u64 v[70:71], s[34:35], 0, v[2:3]
	v_lshl_add_u64 v[72:73], s[34:35], 0, v[4:5]
	s_add_u32 s34, s36, s84
	v_add_u32_e32 v8, 0, v8
	v_add_u32_e32 v9, 0, v9
	s_addc_u32 s35, s37, s85
	v_lshl_add_u64 v[74:75], s[34:35], 0, v[64:65]
	v_lshl_add_u64 v[76:77], s[34:35], 0, v[0:1]
	v_lshl_add_u64 v[78:79], s[34:35], 0, v[2:3]
	v_lshl_add_u64 v[80:81], s[34:35], 0, v[4:5]
	s_mov_b64 s[84:85], 0
	v_add_u32_e32 v64, 0x8000, v100
	v_add_u32_e32 v108, 0x9000, v100
	v_add_u32_e32 v109, 0xa000, v100
	v_add_u32_e32 v110, 0xb000, v100
	v_add_u32_e32 v111, 0xc000, v100
	v_add_u32_e32 v112, 0xd000, v100
	v_add_u32_e32 v113, 0xe000, v100
	v_add_u32_e32 v114, 0xf000, v100
	v_add_u32_e32 v115, v8, v7
	v_add_u32_e32 v116, v9, v7
	v_add_u32_e32 v117, v8, v6
	v_add_u32_e32 v118, v9, v6
	s_mov_b32 s11, 0
	v_mov_b32_e32 v0, 0
	v_mov_b32_e32 v2, v65
	v_mov_b32_e32 v8, 0
	v_mov_b32_e32 v9, v65
	v_mov_b32_e32 v10, v65
	v_mov_b32_e32 v11, v65
	v_mov_b32_e32 v4, 0
	v_mov_b32_e32 v6, v65
	v_mov_b32_e32 v7, v65
	v_mov_b32_e32 v12, 0
	v_mov_b32_e32 v13, v65
	v_mov_b32_e32 v14, v65
	v_mov_b32_e32 v15, v65
	v_mov_b32_e32 v16, 0
	v_mov_b32_e32 v17, v65
	v_mov_b32_e32 v18, v65
	v_mov_b32_e32 v19, v65
	v_mov_b32_e32 v24, 0
	v_mov_b32_e32 v25, v65
	v_mov_b32_e32 v26, v65
	v_mov_b32_e32 v27, v65
	v_mov_b32_e32 v20, 0
	v_mov_b32_e32 v21, v65
	v_mov_b32_e32 v22, v65
	v_mov_b32_e32 v23, v65
	v_mov_b32_e32 v28, 0
	v_mov_b32_e32 v29, v65
	v_mov_b32_e32 v30, v65
	v_mov_b32_e32 v31, v65
	v_mov_b32_e32 v32, 0
	v_mov_b32_e32 v33, v65
	v_mov_b32_e32 v34, v65
	v_mov_b32_e32 v35, v65
	v_mov_b32_e32 v40, 0
	v_mov_b32_e32 v41, v65
	v_mov_b32_e32 v42, v65
	v_mov_b32_e32 v43, v65
	v_mov_b32_e32 v36, 0
	v_mov_b32_e32 v37, v65
	v_mov_b32_e32 v38, v65
	v_mov_b32_e32 v39, v65
	v_mov_b32_e32 v44, 0
	v_mov_b32_e32 v45, v65
	v_mov_b32_e32 v46, v65
	v_mov_b32_e32 v47, v65
	v_mov_b32_e32 v48, 0
	v_mov_b32_e32 v49, v65
	v_mov_b32_e32 v50, v65
	v_mov_b32_e32 v51, v65
	v_mov_b32_e32 v56, 0
	v_mov_b32_e32 v57, v65
	v_mov_b32_e32 v58, v65
	v_mov_b32_e32 v59, v65
	v_mov_b32_e32 v52, 0
	v_mov_b32_e32 v53, v65
	v_mov_b32_e32 v54, v65
	v_mov_b32_e32 v55, v65
	v_mov_b32_e32 v60, 0
	v_mov_b32_e32 v61, v65
	v_mov_b32_e32 v62, v65
	v_mov_b32_e32 v63, v65
	s_mov_b64 s[98:99], s[0:1]
	s_mov_b64 s[100:101], s[4:5]
	v_readfirstlane_b32 s13, v64
	v_lshl_add_u64 v[250:251], v[66:67], 0, s[98:99]
	s_mov_b32 m0, s13
	v_readfirstlane_b32 s13, v108
	global_load_lds_dwordx4 v[250:251], off
	v_lshl_add_u64 v[250:251], v[68:69], 0, s[98:99]
	s_mov_b32 m0, s13
	v_readfirstlane_b32 s13, v109
	global_load_lds_dwordx4 v[250:251], off
	v_lshl_add_u64 v[250:251], v[70:71], 0, s[98:99]
	s_mov_b32 m0, s13
	v_readfirstlane_b32 s13, v110
	global_load_lds_dwordx4 v[250:251], off
	v_lshl_add_u64 v[250:251], v[72:73], 0, s[98:99]
	s_mov_b32 m0, s13
	v_readfirstlane_b32 s13, v111
	global_load_lds_dwordx4 v[250:251], off
	v_lshl_add_u64 v[250:251], v[74:75], 0, s[100:101]
	s_mov_b32 m0, s13
	v_readfirstlane_b32 s13, v112
	global_load_lds_dwordx4 v[250:251], off
	v_lshl_add_u64 v[250:251], v[76:77], 0, s[100:101]
	s_mov_b32 m0, s13
	v_readfirstlane_b32 s13, v113
	global_load_lds_dwordx4 v[250:251], off
	v_lshl_add_u64 v[250:251], v[78:79], 0, s[100:101]
	s_mov_b32 m0, s13
	v_readfirstlane_b32 s13, v114
	global_load_lds_dwordx4 v[250:251], off
	v_lshl_add_u64 v[250:251], v[80:81], 0, s[100:101]
	s_mov_b32 m0, s13
	s_nop 0
	global_load_lds_dwordx4 v[250:251], off
	s_branch .LBB0_884

.Lgp_og_3:
	s_barrier
	s_nop 1
	ds_read_b128 v[82:85], v115 offset:32768
	ds_read_b128 v[86:89], v115 offset:34816
	ds_read_b128 v[90:93], v115 offset:36864
	ds_read_b128 v[94:97], v115 offset:38912
	ds_read_b128 v[120:123], v116 offset:49152
	ds_read_b128 v[124:127], v116 offset:51200
	ds_read_b128 v[128:131], v116 offset:53248
	ds_read_b128 v[132:135], v116 offset:55296
	s_add_i32 s11, s11, 2
	s_waitcnt lgkmcnt(0)
	v_mfma_f32_16x16x32_f16 v[0:3], v[120:123], v[82:85], v[0:3]
	ds_read_b128 v[136:139], v117 offset:32768
	v_mfma_f32_16x16x32_f16 v[4:7], v[124:127], v[82:85], v[4:7]
	v_mfma_f32_16x16x32_f16 v[8:11], v[128:131], v[82:85], v[8:11]
	ds_read_b128 v[140:143], v117 offset:34816
	v_mfma_f32_16x16x32_f16 v[12:15], v[132:135], v[82:85], v[12:15]
	v_mfma_f32_16x16x32_f16 v[16:19], v[120:123], v[86:89], v[16:19]
	ds_read_b128 v[144:147], v117 offset:36864
	v_mfma_f32_16x16x32_f16 v[20:23], v[124:127], v[86:89], v[20:23]
	v_mfma_f32_16x16x32_f16 v[24:27], v[128:131], v[86:89], v[24:27]
	ds_read_b128 v[148:151], v117 offset:38912
	v_mfma_f32_16x16x32_f16 v[28:31], v[132:135], v[86:89], v[28:31]
	v_mfma_f32_16x16x32_f16 v[82:85], v[120:123], v[90:93], v[32:35]
	ds_read_b128 v[152:155], v118 offset:49152
	v_mfma_f32_16x16x32_f16 v[86:89], v[124:127], v[90:93], v[36:39]
	v_mfma_f32_16x16x32_f16 v[168:171], v[128:131], v[90:93], v[40:43]
	ds_read_b128 v[156:159], v118 offset:51200
	v_mfma_f32_16x16x32_f16 v[90:93], v[132:135], v[90:93], v[44:47]
	v_mfma_f32_16x16x32_f16 v[120:123], v[120:123], v[94:97], v[48:51]
	ds_read_b128 v[160:163], v118 offset:53248
	v_mfma_f32_16x16x32_f16 v[124:127], v[124:127], v[94:97], v[52:55]
	v_mfma_f32_16x16x32_f16 v[128:131], v[128:131], v[94:97], v[56:59]
	ds_read_b128 v[164:167], v118 offset:55296
	v_mfma_f32_16x16x32_f16 v[94:97], v[132:135], v[94:97], v[60:63]
	s_waitcnt lgkmcnt(0)
	s_barrier
	s_and_b64 vcc, exec, s[88:89]
	s_cbranch_vccnz .Lgp_os_3
	s_add_u32 s98, s84, s6
	s_addc_u32 s99, s85, s7
	s_add_u32 s98, s98, 0x80
	s_addc_u32 s99, s99, 0
	s_add_u32 s100, s84, s8
	s_addc_u32 s101, s85, s9
	s_add_u32 s100, s100, 0x80
	s_addc_u32 s101, s101, 0
	v_readfirstlane_b32 s13, v64
	v_mfma_f32_16x16x32_f16 v[60:63], v[152:155], v[136:139], v[0:3]
	v_lshl_add_u64 v[250:251], v[66:67], 0, s[98:99]
	s_mov_b32 m0, s13
	v_readfirstlane_b32 s13, v108
	global_load_lds_dwordx4 v[250:251], off
	v_mfma_f32_16x16x32_f16 v[52:55], v[156:159], v[136:139], v[4:7]
	v_mfma_f32_16x16x32_f16 v[56:59], v[160:163], v[136:139], v[8:11]
	v_lshl_add_u64 v[250:251], v[68:69], 0, s[98:99]
	s_mov_b32 m0, s13
	v_readfirstlane_b32 s13, v109
	global_load_lds_dwordx4 v[250:251], off
	v_mfma_f32_16x16x32_f16 v[48:51], v[164:167], v[136:139], v[12:15]
	v_mfma_f32_16x16x32_f16 v[44:47], v[152:155], v[140:143], v[16:19]
	v_lshl_add_u64 v[250:251], v[70:71], 0, s[98:99]
	s_mov_b32 m0, s13
	v_readfirstlane_b32 s13, v110
	global_load_lds_dwordx4 v[250:251], off
	v_mfma_f32_16x16x32_f16 v[36:39], v[156:159], v[140:143], v[20:23]
	v_mfma_f32_16x16x32_f16 v[40:43], v[160:163], v[140:143], v[24:27]
	v_lshl_add_u64 v[250:251], v[72:73], 0, s[98:99]
	s_mov_b32 m0, s13
	v_readfirstlane_b32 s13, v111
	global_load_lds_dwordx4 v[250:251], off
	v_mfma_f32_16x16x32_f16 v[32:35], v[164:167], v[140:143], v[28:31]
	v_mfma_f32_16x16x32_f16 v[28:31], v[152:155], v[144:147], v[82:85]
	v_lshl_add_u64 v[250:251], v[74:75], 0, s[100:101]
	s_mov_b32 m0, s13
	v_readfirstlane_b32 s13, v112
	global_load_lds_dwordx4 v[250:251], off
	v_mfma_f32_16x16x32_f16 v[20:23], v[156:159], v[144:147], v[86:89]
	v_mfma_f32_16x16x32_f16 v[24:27], v[160:163], v[144:147], v[168:171]
	v_lshl_add_u64 v[250:251], v[76:77], 0, s[100:101]
	s_mov_b32 m0, s13
	v_readfirstlane_b32 s13, v113
	global_load_lds_dwordx4 v[250:251], off
	v_mfma_f32_16x16x32_f16 v[16:19], v[164:167], v[144:147], v[90:93]
	v_mfma_f32_16x16x32_f16 v[12:15], v[152:155], v[148:151], v[120:123]
	v_lshl_add_u64 v[250:251], v[78:79], 0, s[100:101]
	s_mov_b32 m0, s13
	v_readfirstlane_b32 s13, v114
	global_load_lds_dwordx4 v[250:251], off
	v_mfma_f32_16x16x32_f16 v[4:7], v[156:159], v[148:151], v[124:127]
	v_mfma_f32_16x16x32_f16 v[8:11], v[160:163], v[148:151], v[128:131]
	v_lshl_add_u64 v[250:251], v[80:81], 0, s[100:101]
	s_mov_b32 m0, s13
	s_nop 0
	global_load_lds_dwordx4 v[250:251], off
	v_mfma_f32_16x16x32_f16 v[0:3], v[164:167], v[148:151], v[94:97]
	s_branch .Lgp_oj_3
.Lgp_os_3:
	v_mfma_f32_16x16x32_f16 v[60:63], v[152:155], v[136:139], v[0:3]
	v_mfma_f32_16x16x32_f16 v[52:55], v[156:159], v[136:139], v[4:7]
	v_mfma_f32_16x16x32_f16 v[56:59], v[160:163], v[136:139], v[8:11]
	v_mfma_f32_16x16x32_f16 v[48:51], v[164:167], v[136:139], v[12:15]
	v_mfma_f32_16x16x32_f16 v[44:47], v[152:155], v[140:143], v[16:19]
	v_mfma_f32_16x16x32_f16 v[36:39], v[156:159], v[140:143], v[20:23]
	v_mfma_f32_16x16x32_f16 v[40:43], v[160:163], v[140:143], v[24:27]
	v_mfma_f32_16x16x32_f16 v[32:35], v[164:167], v[140:143], v[28:31]
	v_mfma_f32_16x16x32_f16 v[28:31], v[152:155], v[144:147], v[82:85]
	v_mfma_f32_16x16x32_f16 v[20:23], v[156:159], v[144:147], v[86:89]
	v_mfma_f32_16x16x32_f16 v[24:27], v[160:163], v[144:147], v[168:171]
	v_mfma_f32_16x16x32_f16 v[16:19], v[164:167], v[144:147], v[90:93]
	v_mfma_f32_16x16x32_f16 v[12:15], v[152:155], v[148:151], v[120:123]
	v_mfma_f32_16x16x32_f16 v[4:7], v[156:159], v[148:151], v[124:127]
	v_mfma_f32_16x16x32_f16 v[8:11], v[160:163], v[148:151], v[128:131]
	v_mfma_f32_16x16x32_f16 v[0:3], v[164:167], v[148:151], v[94:97]

.LBB0_884:
	s_waitcnt vmcnt(8)
	s_barrier
	s_nop 1
	ds_read_b128 v[120:123], v115
	ds_read_b128 v[124:127], v115 offset:2048
	ds_read_b128 v[128:131], v115 offset:4096
	ds_read_b128 v[132:135], v115 offset:6144
	ds_read_b128 v[136:139], v116 offset:16384
	ds_read_b128 v[140:143], v116 offset:18432
	ds_read_b128 v[144:147], v116 offset:20480
	ds_read_b128 v[148:151], v116 offset:22528
	s_cmp_gt_u32 s11, 13
	s_cselect_b64 s[88:89], -1, 0
	s_waitcnt lgkmcnt(0)
	v_mfma_f32_16x16x32_f16 v[60:63], v[136:139], v[120:123], v[60:63]
	ds_read_b128 v[152:155], v117
	v_mfma_f32_16x16x32_f16 v[52:55], v[140:143], v[120:123], v[52:55]
	v_mfma_f32_16x16x32_f16 v[56:59], v[144:147], v[120:123], v[56:59]
	ds_read_b128 v[156:159], v117 offset:2048
	v_mfma_f32_16x16x32_f16 v[48:51], v[148:151], v[120:123], v[48:51]
	v_mfma_f32_16x16x32_f16 v[44:47], v[136:139], v[124:127], v[44:47]
	ds_read_b128 v[160:163], v117 offset:4096
	v_mfma_f32_16x16x32_f16 v[36:39], v[140:143], v[124:127], v[36:39]
	v_mfma_f32_16x16x32_f16 v[40:43], v[144:147], v[124:127], v[40:43]
	ds_read_b128 v[164:167], v117 offset:6144
	v_mfma_f32_16x16x32_f16 v[32:35], v[148:151], v[124:127], v[32:35]
	v_mfma_f32_16x16x32_f16 v[120:123], v[136:139], v[128:131], v[28:31]
	ds_read_b128 v[168:171], v118 offset:16384
	v_mfma_f32_16x16x32_f16 v[124:127], v[140:143], v[128:131], v[20:23]
	v_mfma_f32_16x16x32_f16 v[188:191], v[144:147], v[128:131], v[24:27]
	ds_read_b128 v[176:179], v118 offset:18432
	v_mfma_f32_16x16x32_f16 v[128:131], v[148:151], v[128:131], v[16:19]
	v_mfma_f32_16x16x32_f16 v[136:139], v[136:139], v[132:135], v[12:15]
	ds_read_b128 v[180:183], v118 offset:20480
	v_mfma_f32_16x16x32_f16 v[140:143], v[140:143], v[132:135], v[4:7]
	v_mfma_f32_16x16x32_f16 v[144:147], v[144:147], v[132:135], v[8:11]
	ds_read_b128 v[184:187], v118 offset:22528
	v_mfma_f32_16x16x32_f16 v[132:135], v[148:151], v[132:135], v[0:3]
	s_waitcnt lgkmcnt(0)
	s_barrier
	s_and_b64 vcc, exec, s[88:89]
	s_cbranch_vccnz .Lgp_es_3
	s_add_u32 s98, s84, s6
	s_addc_u32 s99, s85, s7
	s_add_u32 s100, s84, s8
	s_addc_u32 s101, s85, s9
	v_readfirstlane_b32 s13, v100
	v_mfma_f32_16x16x32_f16 v[0:3], v[168:171], v[152:155], v[60:63]
	v_lshl_add_u64 v[250:251], v[66:67], 0, s[98:99]
	s_mov_b32 m0, s13
	v_readfirstlane_b32 s13, v101
	global_load_lds_dwordx4 v[250:251], off
	v_mfma_f32_16x16x32_f16 v[4:7], v[176:179], v[152:155], v[52:55]
	v_mfma_f32_16x16x32_f16 v[8:11], v[180:183], v[152:155], v[56:59]
	v_lshl_add_u64 v[250:251], v[68:69], 0, s[98:99]
	s_mov_b32 m0, s13
	v_readfirstlane_b32 s13, v102
	global_load_lds_dwordx4 v[250:251], off
	v_mfma_f32_16x16x32_f16 v[12:15], v[184:187], v[152:155], v[48:51]
	v_mfma_f32_16x16x32_f16 v[16:19], v[168:171], v[156:159], v[44:47]
	v_lshl_add_u64 v[250:251], v[70:71], 0, s[98:99]
	s_mov_b32 m0, s13
	v_readfirstlane_b32 s13, v103
	global_load_lds_dwordx4 v[250:251], off
	v_mfma_f32_16x16x32_f16 v[20:23], v[176:179], v[156:159], v[36:39]
	v_mfma_f32_16x16x32_f16 v[24:27], v[180:183], v[156:159], v[40:43]
	v_lshl_add_u64 v[250:251], v[72:73], 0, s[98:99]
	s_mov_b32 m0, s13
	v_readfirstlane_b32 s13, v104
	global_load_lds_dwordx4 v[250:251], off
	v_mfma_f32_16x16x32_f16 v[28:31], v[184:187], v[156:159], v[32:35]
	v_mfma_f32_16x16x32_f16 v[32:35], v[168:171], v[160:163], v[120:123]
	v_lshl_add_u64 v[250:251], v[74:75], 0, s[100:101]
	s_mov_b32 m0, s13
	v_readfirstlane_b32 s13, v105
	global_load_lds_dwordx4 v[250:251], off
	v_mfma_f32_16x16x32_f16 v[36:39], v[176:179], v[160:163], v[124:127]
	v_mfma_f32_16x16x32_f16 v[40:43], v[180:183], v[160:163], v[188:191]
	v_lshl_add_u64 v[250:251], v[76:77], 0, s[100:101]
	s_mov_b32 m0, s13
	v_readfirstlane_b32 s13, v106
	global_load_lds_dwordx4 v[250:251], off
	v_mfma_f32_16x16x32_f16 v[44:47], v[184:187], v[160:163], v[128:131]
	v_mfma_f32_16x16x32_f16 v[48:51], v[168:171], v[164:167], v[136:139]
	v_lshl_add_u64 v[250:251], v[78:79], 0, s[100:101]
	s_mov_b32 m0, s13
	v_readfirstlane_b32 s13, v107
	global_load_lds_dwordx4 v[250:251], off
	v_mfma_f32_16x16x32_f16 v[52:55], v[176:179], v[164:167], v[140:143]
	v_mfma_f32_16x16x32_f16 v[56:59], v[180:183], v[164:167], v[144:147]
	v_lshl_add_u64 v[250:251], v[80:81], 0, s[100:101]
	s_mov_b32 m0, s13
	s_nop 0
	global_load_lds_dwordx4 v[250:251], off
	v_mfma_f32_16x16x32_f16 v[60:63], v[184:187], v[164:167], v[132:135]
	s_branch .Lgp_ej_3
.Lgp_es_3:
	v_mfma_f32_16x16x32_f16 v[0:3], v[168:171], v[152:155], v[60:63]
	v_mfma_f32_16x16x32_f16 v[4:7], v[176:179], v[152:155], v[52:55]
	v_mfma_f32_16x16x32_f16 v[8:11], v[180:183], v[152:155], v[56:59]
	v_mfma_f32_16x16x32_f16 v[12:15], v[184:187], v[152:155], v[48:51]
	v_mfma_f32_16x16x32_f16 v[16:19], v[168:171], v[156:159], v[44:47]
	v_mfma_f32_16x16x32_f16 v[20:23], v[176:179], v[156:159], v[36:39]
	v_mfma_f32_16x16x32_f16 v[24:27], v[180:183], v[156:159], v[40:43]
	v_mfma_f32_16x16x32_f16 v[28:31], v[184:187], v[156:159], v[32:35]
	v_mfma_f32_16x16x32_f16 v[32:35], v[168:171], v[160:163], v[120:123]
	v_mfma_f32_16x16x32_f16 v[36:39], v[176:179], v[160:163], v[124:127]
	v_mfma_f32_16x16x32_f16 v[40:43], v[180:183], v[160:163], v[188:191]
	v_mfma_f32_16x16x32_f16 v[44:47], v[184:187], v[160:163], v[128:131]
	v_mfma_f32_16x16x32_f16 v[48:51], v[168:171], v[164:167], v[136:139]
	v_mfma_f32_16x16x32_f16 v[52:55], v[176:179], v[164:167], v[140:143]
	v_mfma_f32_16x16x32_f16 v[56:59], v[180:183], v[164:167], v[144:147]
	v_mfma_f32_16x16x32_f16 v[60:63], v[184:187], v[164:167], v[132:135]
.Lgp_ej_3:
	s_branch .LBB0_883
.LBB0_886:
	s_waitcnt vmcnt(0)
	s_barrier
	s_mov_b64 s[0:1], exec
	v_readlane_b32 s4, v254, 1
	v_readlane_b32 s5, v254, 2
	s_and_b64 s[4:5], s[0:1], s[4:5]
	s_mov_b64 exec, s[4:5]
	s_cbranch_execz .LBB0_938
	s_add_i32 s3, 0, 0x10000
	v_mov_b32_e32 v0, s3
	s_waitcnt vmcnt(0) expcnt(0) lgkmcnt(0)
	ds_read_b32 v2, v0
	s_add_i32 s3, 0, 0x10004
	v_mov_b32_e32 v0, s3
	ds_read_b32 v0, v0
	s_waitcnt lgkmcnt(1)
	v_cmp_ne_u32_e32 vcc, 0, v2
	s_cbranch_vccnz .LBB0_902
	s_add_u32 s4, s50, 0x1000
	s_addc_u32 s5, s51, 0
	s_add_u32 s6, s50, 0x1100
	s_addc_u32 s7, s51, 0
	s_add_u32 s8, s50, 0x1200
	v_readlane_b32 s3, v254, 0
	s_addc_u32 s9, s51, 0
	s_mul_i32 s3, s29, s3
	s_add_u32 s10, s50, 0x1300
	s_mul_i32 s3, s3, s28
	s_addc_u32 s11, s51, 0
	s_mov_b32 s34, 1
	v_mov_b32_e32 v16, 0
	s_branch .LBB0_890

.Lto_j_b2:
	s_mul_i32 s98, s98, 17
	s_add_u32 s98, s98, s99
	s_lshl_b32 s99, s98, 3
	s_or_b32 s99, s99, s84
	s_mul_hi_i32 s10, s98, 0x78787879
	s_lshr_b32 s11, s10, 31
	s_ashr_i32 s91, s10, 3
	s_add_i32 s91, s91, s11
	v_mov_b32_e32 v0, v174
	s_mul_i32 s10, s91, 0xffffffef
	s_add_i32 s10, s10, s98
	v_bfe_u32 v2, v0, 1, 3
	v_lshrrev_b32_e32 v3, 4, v0
	s_waitcnt vmcnt(5)
	v_bfe_u32 v4, v0, 4, 2
	v_lshlrev_b32_e32 v5, 7, v0
	v_and_b32_e32 v6, 0x780, v5
	v_bitop3_b32 v3, v3, v2, 3 bitop3:0x6c
	v_bitop3_b32 v2, v4, v2, 4 bitop3:0x36
	s_lshl_b32 s10, s10, 3
	v_lshl_or_b32 v7, v3, 4, v6
	v_lshl_or_b32 v6, v2, 4, v6
	v_lshlrev_b32_e32 v2, 6, v0
	s_or_b32 s92, s10, s84
	v_lshrrev_b32_e32 v1, 3, v0
	v_and_b32_e32 v8, 0xffffe000, v2
	s_movk_i32 s93, 0x1600
	v_lshlrev_b32_e32 v2, 4, v0
	s_mul_i32 s10, s92, 0xb0000
	v_mul_lo_u32 v1, v1, s93
	v_xor_b32_e32 v0, v2, v0
	s_movk_i32 s93, 0x70
	v_add_u32_e32 v100, 0, v2
	s_mul_hi_i32 s11, s92, 0xb0000
	s_add_u32 s10, s42, s10
	v_and_or_b32 v64, v0, s93, v1
	v_readfirstlane_b32 s93, v100
	v_add_u32_e32 v101, 0x1000, v100
	s_addc_u32 s11, s43, s11
	s_mov_b32 m0, s93
	v_readfirstlane_b32 s93, v101
	v_add_u32_e32 v102, 0x2000, v100
	global_load_lds_dwordx4 v64, s[10:11]
	v_add_u32_e32 v0, 0x2c000, v64
	s_mov_b32 m0, s93
	v_readfirstlane_b32 s93, v102
	v_add_u32_e32 v103, 0x3000, v100
	global_load_lds_dwordx4 v0, s[10:11]
	v_add_u32_e32 v2, 0x58000, v64
	s_mov_b32 m0, s93
	v_readfirstlane_b32 s93, v103
	s_mul_i32 s35, s91, 0xb0000
	global_load_lds_dwordx4 v2, s[10:11]
	v_add_u32_e32 v4, 0x84000, v64
	s_mov_b32 m0, s93
	v_add_u32_e32 v104, 0x4000, v100
	s_mul_hi_i32 s34, s91, 0xb0000
	s_add_u32 s12, s88, s35
	global_load_lds_dwordx4 v4, s[10:11]
	v_readfirstlane_b32 s10, v104
	v_add_u32_e32 v105, 0x5000, v100
	s_addc_u32 s13, s89, s34
	s_mov_b32 m0, s10
	v_readfirstlane_b32 s10, v105
	v_add_u32_e32 v106, 0x6000, v100
	global_load_lds_dwordx4 v64, s[12:13]
	s_mov_b32 m0, s10
	v_readfirstlane_b32 s10, v106
	v_add_u32_e32 v107, 0x7000, v100
	global_load_lds_dwordx4 v0, s[12:13]
	s_mov_b32 m0, s10
	v_readfirstlane_b32 s10, v107
	global_load_lds_dwordx4 v2, s[12:13]
	s_mov_b32 m0, s10
	s_mul_i32 s10, s91, 0x88
	global_load_lds_dwordx4 v4, s[12:13]
	s_sub_i32 s10, s99, s10
	s_mul_hi_i32 s11, s10, 0xb0000
	s_mul_i32 s10, s10, 0xb0000
	s_add_u32 s10, s42, s10
	v_and_b32_e32 v9, 0x2000, v5
	v_mov_b32_e32 v1, v65
	v_mov_b32_e32 v3, v65
	v_mov_b32_e32 v5, v65
	s_addc_u32 s11, s43, s11
	v_lshl_add_u64 v[66:67], s[10:11], 0, v[64:65]
	v_lshl_add_u64 v[68:69], s[10:11], 0, v[0:1]
	v_lshl_add_u64 v[70:71], s[10:11], 0, v[2:3]
	v_lshl_add_u64 v[72:73], s[10:11], 0, v[4:5]
	s_add_u32 s10, s36, s35
	v_add_u32_e32 v8, 0, v8
	v_add_u32_e32 v9, 0, v9
	s_addc_u32 s11, s37, s34
	v_lshl_add_u64 v[74:75], s[10:11], 0, v[64:65]
	v_lshl_add_u64 v[76:77], s[10:11], 0, v[0:1]
	v_lshl_add_u64 v[78:79], s[10:11], 0, v[2:3]
	v_lshl_add_u64 v[80:81], s[10:11], 0, v[4:5]
	s_mov_b64 s[10:11], 0
	v_add_u32_e32 v64, 0x8000, v100
	v_add_u32_e32 v108, 0x9000, v100
	v_add_u32_e32 v109, 0xa000, v100
	v_add_u32_e32 v110, 0xb000, v100
	v_add_u32_e32 v111, 0xc000, v100
	v_add_u32_e32 v112, 0xd000, v100
	v_add_u32_e32 v113, 0xe000, v100
	v_add_u32_e32 v114, 0xf000, v100
	v_add_u32_e32 v115, v8, v7
	v_add_u32_e32 v116, v9, v7
	v_add_u32_e32 v117, v8, v6
	v_add_u32_e32 v118, v9, v6
	s_mov_b32 s93, 0
	v_mov_b32_e32 v0, 0
	v_mov_b32_e32 v2, v65
	v_mov_b32_e32 v4, 0
	v_mov_b32_e32 v6, v65
	v_mov_b32_e32 v7, v65
	v_mov_b32_e32 v8, 0
	v_mov_b32_e32 v9, v65
	v_mov_b32_e32 v10, v65
	v_mov_b32_e32 v11, v65
	v_mov_b32_e32 v12, 0
	v_mov_b32_e32 v13, v65
	v_mov_b32_e32 v14, v65
	v_mov_b32_e32 v15, v65
	v_mov_b32_e32 v16, 0
	v_mov_b32_e32 v17, v65
	v_mov_b32_e32 v18, v65
	v_mov_b32_e32 v19, v65
	v_mov_b32_e32 v20, 0
	v_mov_b32_e32 v21, v65
	v_mov_b32_e32 v22, v65
	v_mov_b32_e32 v23, v65
	v_mov_b32_e32 v24, 0
	v_mov_b32_e32 v25, v65
	v_mov_b32_e32 v26, v65
	v_mov_b32_e32 v27, v65
	v_mov_b32_e32 v28, 0
	v_mov_b32_e32 v29, v65
	v_mov_b32_e32 v30, v65
	v_mov_b32_e32 v31, v65
	v_mov_b32_e32 v32, 0
	v_mov_b32_e32 v33, v65
	v_mov_b32_e32 v34, v65
	v_mov_b32_e32 v35, v65
	v_mov_b32_e32 v36, 0
	v_mov_b32_e32 v37, v65
	v_mov_b32_e32 v38, v65
	v_mov_b32_e32 v39, v65
	v_mov_b32_e32 v40, 0
	v_mov_b32_e32 v41, v65
	v_mov_b32_e32 v42, v65
	v_mov_b32_e32 v43, v65
	v_mov_b32_e32 v44, 0
	v_mov_b32_e32 v45, v65
	v_mov_b32_e32 v46, v65
	v_mov_b32_e32 v47, v65
	v_mov_b32_e32 v48, 0
	v_mov_b32_e32 v49, v65
	v_mov_b32_e32 v50, v65
	v_mov_b32_e32 v51, v65
	v_mov_b32_e32 v52, 0
	v_mov_b32_e32 v53, v65
	s_waitcnt vmcnt(0)
	v_mov_b32_e32 v54, v65
	v_mov_b32_e32 v55, v65
	v_mov_b32_e32 v56, 0
	v_mov_b32_e32 v57, v65
	v_mov_b32_e32 v58, v65
	v_mov_b32_e32 v59, v65
	v_mov_b32_e32 v60, 0
	v_mov_b32_e32 v61, v65
	v_mov_b32_e32 v62, v65
	v_mov_b32_e32 v63, v65
	s_mov_b64 s[98:99], s[0:1]
	s_mov_b64 s[100:101], s[4:5]
	v_readfirstlane_b32 s34, v64
	v_lshl_add_u64 v[250:251], v[66:67], 0, s[98:99]
	s_mov_b32 m0, s34
	v_readfirstlane_b32 s34, v108
	global_load_lds_dwordx4 v[250:251], off
	v_lshl_add_u64 v[250:251], v[68:69], 0, s[98:99]
	s_mov_b32 m0, s34
	v_readfirstlane_b32 s34, v109
	global_load_lds_dwordx4 v[250:251], off
	v_lshl_add_u64 v[250:251], v[70:71], 0, s[98:99]
	s_mov_b32 m0, s34
	v_readfirstlane_b32 s34, v110
	global_load_lds_dwordx4 v[250:251], off
	v_lshl_add_u64 v[250:251], v[72:73], 0, s[98:99]
	s_mov_b32 m0, s34
	v_readfirstlane_b32 s34, v111
	global_load_lds_dwordx4 v[250:251], off
	v_lshl_add_u64 v[250:251], v[74:75], 0, s[100:101]
	s_mov_b32 m0, s34
	v_readfirstlane_b32 s34, v112
	global_load_lds_dwordx4 v[250:251], off
	v_lshl_add_u64 v[250:251], v[76:77], 0, s[100:101]
	s_mov_b32 m0, s34
	v_readfirstlane_b32 s34, v113
	global_load_lds_dwordx4 v[250:251], off
	v_lshl_add_u64 v[250:251], v[78:79], 0, s[100:101]
	s_mov_b32 m0, s34
	v_readfirstlane_b32 s34, v114
	global_load_lds_dwordx4 v[250:251], off
	v_lshl_add_u64 v[250:251], v[80:81], 0, s[100:101]
	s_mov_b32 m0, s34
	s_nop 0
	global_load_lds_dwordx4 v[250:251], off
	s_branch .LBB0_953

.Lgp_og_4:
	s_barrier
	s_nop 1
	ds_read_b128 v[82:85], v115 offset:32768
	ds_read_b128 v[86:89], v115 offset:34816
	ds_read_b128 v[90:93], v115 offset:36864
	ds_read_b128 v[94:97], v115 offset:38912
	ds_read_b128 v[120:123], v116 offset:49152
	ds_read_b128 v[124:127], v116 offset:51200
	ds_read_b128 v[128:131], v116 offset:53248
	ds_read_b128 v[132:135], v116 offset:55296
	s_add_i32 s93, s93, 2
	s_waitcnt lgkmcnt(0)
	v_mfma_f32_16x16x32_f16 v[0:3], v[120:123], v[82:85], v[0:3]
	ds_read_b128 v[136:139], v117 offset:32768
	v_mfma_f32_16x16x32_f16 v[4:7], v[124:127], v[82:85], v[4:7]
	v_mfma_f32_16x16x32_f16 v[8:11], v[128:131], v[82:85], v[8:11]
	ds_read_b128 v[140:143], v117 offset:34816
	v_mfma_f32_16x16x32_f16 v[12:15], v[132:135], v[82:85], v[12:15]
	v_mfma_f32_16x16x32_f16 v[16:19], v[120:123], v[86:89], v[16:19]
	ds_read_b128 v[144:147], v117 offset:36864
	v_mfma_f32_16x16x32_f16 v[20:23], v[124:127], v[86:89], v[20:23]
	v_mfma_f32_16x16x32_f16 v[24:27], v[128:131], v[86:89], v[24:27]
	ds_read_b128 v[148:151], v117 offset:38912
	v_mfma_f32_16x16x32_f16 v[28:31], v[132:135], v[86:89], v[28:31]
	v_mfma_f32_16x16x32_f16 v[82:85], v[120:123], v[90:93], v[32:35]
	ds_read_b128 v[152:155], v118 offset:49152
	v_mfma_f32_16x16x32_f16 v[86:89], v[124:127], v[90:93], v[36:39]
	v_mfma_f32_16x16x32_f16 v[168:171], v[128:131], v[90:93], v[40:43]
	ds_read_b128 v[156:159], v118 offset:51200
	v_mfma_f32_16x16x32_f16 v[90:93], v[132:135], v[90:93], v[44:47]
	v_mfma_f32_16x16x32_f16 v[120:123], v[120:123], v[94:97], v[48:51]
	ds_read_b128 v[160:163], v118 offset:53248
	v_mfma_f32_16x16x32_f16 v[124:127], v[124:127], v[94:97], v[52:55]
	v_mfma_f32_16x16x32_f16 v[128:131], v[128:131], v[94:97], v[56:59]
	ds_read_b128 v[164:167], v118 offset:55296
	v_mfma_f32_16x16x32_f16 v[94:97], v[132:135], v[94:97], v[60:63]
	s_waitcnt lgkmcnt(0)
	s_barrier
	s_and_b64 vcc, exec, s[12:13]
	s_cbranch_vccnz .Lgp_os_4
	s_add_u32 s98, s10, s6
	s_addc_u32 s99, s11, s7
	s_add_u32 s98, s98, 0x80
	s_addc_u32 s99, s99, 0
	s_add_u32 s100, s10, s8
	s_addc_u32 s101, s11, s9
	s_add_u32 s100, s100, 0x80
	s_addc_u32 s101, s101, 0
	v_readfirstlane_b32 s34, v64
	v_mfma_f32_16x16x32_f16 v[60:63], v[152:155], v[136:139], v[0:3]
	v_lshl_add_u64 v[250:251], v[66:67], 0, s[98:99]
	s_mov_b32 m0, s34
	v_readfirstlane_b32 s34, v108
	global_load_lds_dwordx4 v[250:251], off
	v_mfma_f32_16x16x32_f16 v[56:59], v[156:159], v[136:139], v[4:7]
	v_mfma_f32_16x16x32_f16 v[52:55], v[160:163], v[136:139], v[8:11]
	v_lshl_add_u64 v[250:251], v[68:69], 0, s[98:99]
	s_mov_b32 m0, s34
	v_readfirstlane_b32 s34, v109
	global_load_lds_dwordx4 v[250:251], off
	v_mfma_f32_16x16x32_f16 v[48:51], v[164:167], v[136:139], v[12:15]
	v_mfma_f32_16x16x32_f16 v[44:47], v[152:155], v[140:143], v[16:19]
	v_lshl_add_u64 v[250:251], v[70:71], 0, s[98:99]
	s_mov_b32 m0, s34
	v_readfirstlane_b32 s34, v110
	global_load_lds_dwordx4 v[250:251], off
	v_mfma_f32_16x16x32_f16 v[40:43], v[156:159], v[140:143], v[20:23]
	v_mfma_f32_16x16x32_f16 v[36:39], v[160:163], v[140:143], v[24:27]
	v_lshl_add_u64 v[250:251], v[72:73], 0, s[98:99]
	s_mov_b32 m0, s34
	v_readfirstlane_b32 s34, v111
	global_load_lds_dwordx4 v[250:251], off
	v_mfma_f32_16x16x32_f16 v[32:35], v[164:167], v[140:143], v[28:31]
	v_mfma_f32_16x16x32_f16 v[28:31], v[152:155], v[144:147], v[82:85]
	v_lshl_add_u64 v[250:251], v[74:75], 0, s[100:101]
	s_mov_b32 m0, s34
	v_readfirstlane_b32 s34, v112
	global_load_lds_dwordx4 v[250:251], off
	v_mfma_f32_16x16x32_f16 v[24:27], v[156:159], v[144:147], v[86:89]
	v_mfma_f32_16x16x32_f16 v[20:23], v[160:163], v[144:147], v[168:171]
	v_lshl_add_u64 v[250:251], v[76:77], 0, s[100:101]
	s_mov_b32 m0, s34
	v_readfirstlane_b32 s34, v113
	global_load_lds_dwordx4 v[250:251], off
	v_mfma_f32_16x16x32_f16 v[16:19], v[164:167], v[144:147], v[90:93]
	v_mfma_f32_16x16x32_f16 v[12:15], v[152:155], v[148:151], v[120:123]
	v_lshl_add_u64 v[250:251], v[78:79], 0, s[100:101]
	s_mov_b32 m0, s34
	v_readfirstlane_b32 s34, v114
	global_load_lds_dwordx4 v[250:251], off
	v_mfma_f32_16x16x32_f16 v[8:11], v[156:159], v[148:151], v[124:127]
	v_mfma_f32_16x16x32_f16 v[4:7], v[160:163], v[148:151], v[128:131]
	v_lshl_add_u64 v[250:251], v[80:81], 0, s[100:101]
	s_mov_b32 m0, s34
	s_nop 0
	global_load_lds_dwordx4 v[250:251], off
	v_mfma_f32_16x16x32_f16 v[0:3], v[164:167], v[148:151], v[94:97]
	s_branch .Lgp_oj_4

.LBB0_953:
	s_waitcnt vmcnt(8)
	s_barrier
	s_nop 1
	ds_read_b128 v[120:123], v115
	ds_read_b128 v[124:127], v115 offset:2048
	ds_read_b128 v[128:131], v115 offset:4096
	ds_read_b128 v[132:135], v115 offset:6144
	ds_read_b128 v[136:139], v116 offset:16384
	ds_read_b128 v[140:143], v116 offset:18432
	ds_read_b128 v[144:147], v116 offset:20480
	ds_read_b128 v[148:151], v116 offset:22528
	s_cmp_gt_u32 s93, 41
	s_cselect_b64 s[12:13], -1, 0
	s_waitcnt lgkmcnt(0)
	v_mfma_f32_16x16x32_f16 v[60:63], v[136:139], v[120:123], v[60:63]
	ds_read_b128 v[152:155], v117
	v_mfma_f32_16x16x32_f16 v[56:59], v[140:143], v[120:123], v[56:59]
	v_mfma_f32_16x16x32_f16 v[52:55], v[144:147], v[120:123], v[52:55]
	ds_read_b128 v[156:159], v117 offset:2048
	v_mfma_f32_16x16x32_f16 v[48:51], v[148:151], v[120:123], v[48:51]
	v_mfma_f32_16x16x32_f16 v[44:47], v[136:139], v[124:127], v[44:47]
	ds_read_b128 v[160:163], v117 offset:4096
	v_mfma_f32_16x16x32_f16 v[40:43], v[140:143], v[124:127], v[40:43]
	v_mfma_f32_16x16x32_f16 v[36:39], v[144:147], v[124:127], v[36:39]
	ds_read_b128 v[164:167], v117 offset:6144
	v_mfma_f32_16x16x32_f16 v[32:35], v[148:151], v[124:127], v[32:35]
	v_mfma_f32_16x16x32_f16 v[120:123], v[136:139], v[128:131], v[28:31]
	ds_read_b128 v[168:171], v118 offset:16384
	v_mfma_f32_16x16x32_f16 v[124:127], v[140:143], v[128:131], v[24:27]
	v_mfma_f32_16x16x32_f16 v[188:191], v[144:147], v[128:131], v[20:23]
	ds_read_b128 v[176:179], v118 offset:18432
	v_mfma_f32_16x16x32_f16 v[128:131], v[148:151], v[128:131], v[16:19]
	v_mfma_f32_16x16x32_f16 v[136:139], v[136:139], v[132:135], v[12:15]
	ds_read_b128 v[180:183], v118 offset:20480
	v_mfma_f32_16x16x32_f16 v[140:143], v[140:143], v[132:135], v[8:11]
	v_mfma_f32_16x16x32_f16 v[144:147], v[144:147], v[132:135], v[4:7]
	ds_read_b128 v[184:187], v118 offset:22528
	v_mfma_f32_16x16x32_f16 v[132:135], v[148:151], v[132:135], v[0:3]
	s_waitcnt lgkmcnt(0)
	s_barrier
	s_and_b64 vcc, exec, s[12:13]
	s_cbranch_vccnz .Lgp_es_4
	s_add_u32 s98, s10, s6
	s_addc_u32 s99, s11, s7
	s_add_u32 s100, s10, s8
	s_addc_u32 s101, s11, s9
	v_readfirstlane_b32 s34, v100
	v_mfma_f32_16x16x32_f16 v[0:3], v[168:171], v[152:155], v[60:63]
	v_lshl_add_u64 v[250:251], v[66:67], 0, s[98:99]
	s_mov_b32 m0, s34
	v_readfirstlane_b32 s34, v101
	global_load_lds_dwordx4 v[250:251], off
	v_mfma_f32_16x16x32_f16 v[4:7], v[176:179], v[152:155], v[56:59]
	v_mfma_f32_16x16x32_f16 v[8:11], v[180:183], v[152:155], v[52:55]
	v_lshl_add_u64 v[250:251], v[68:69], 0, s[98:99]
	s_mov_b32 m0, s34
	v_readfirstlane_b32 s34, v102
	global_load_lds_dwordx4 v[250:251], off
	v_mfma_f32_16x16x32_f16 v[12:15], v[184:187], v[152:155], v[48:51]
	v_mfma_f32_16x16x32_f16 v[16:19], v[168:171], v[156:159], v[44:47]
	v_lshl_add_u64 v[250:251], v[70:71], 0, s[98:99]
	s_mov_b32 m0, s34
	v_readfirstlane_b32 s34, v103
	global_load_lds_dwordx4 v[250:251], off
	v_mfma_f32_16x16x32_f16 v[20:23], v[176:179], v[156:159], v[40:43]
	v_mfma_f32_16x16x32_f16 v[24:27], v[180:183], v[156:159], v[36:39]
	v_lshl_add_u64 v[250:251], v[72:73], 0, s[98:99]
	s_mov_b32 m0, s34
	v_readfirstlane_b32 s34, v104
	global_load_lds_dwordx4 v[250:251], off
	v_mfma_f32_16x16x32_f16 v[28:31], v[184:187], v[156:159], v[32:35]
	v_mfma_f32_16x16x32_f16 v[32:35], v[168:171], v[160:163], v[120:123]
	v_lshl_add_u64 v[250:251], v[74:75], 0, s[100:101]
	s_mov_b32 m0, s34
	v_readfirstlane_b32 s34, v105
	global_load_lds_dwordx4 v[250:251], off
	v_mfma_f32_16x16x32_f16 v[36:39], v[176:179], v[160:163], v[124:127]
	v_mfma_f32_16x16x32_f16 v[40:43], v[180:183], v[160:163], v[188:191]
	v_lshl_add_u64 v[250:251], v[76:77], 0, s[100:101]
	s_mov_b32 m0, s34
	v_readfirstlane_b32 s34, v106
	global_load_lds_dwordx4 v[250:251], off
	v_mfma_f32_16x16x32_f16 v[44:47], v[184:187], v[160:163], v[128:131]
	v_mfma_f32_16x16x32_f16 v[48:51], v[168:171], v[164:167], v[136:139]
	v_lshl_add_u64 v[250:251], v[78:79], 0, s[100:101]
	s_mov_b32 m0, s34
	v_readfirstlane_b32 s34, v107
	global_load_lds_dwordx4 v[250:251], off
	v_mfma_f32_16x16x32_f16 v[52:55], v[176:179], v[164:167], v[140:143]
	v_mfma_f32_16x16x32_f16 v[56:59], v[180:183], v[164:167], v[144:147]
	v_lshl_add_u64 v[250:251], v[80:81], 0, s[100:101]
	s_mov_b32 m0, s34
	s_nop 0
	global_load_lds_dwordx4 v[250:251], off
	v_mfma_f32_16x16x32_f16 v[60:63], v[184:187], v[164:167], v[132:135]
	s_branch .Lgp_ej_4

.Lgp_ej_4:
	s_branch .LBB0_952
.LBB0_955:
	s_waitcnt vmcnt(0)
	s_barrier
	s_mov_b64 s[0:1], exec
	v_readlane_b32 s4, v254, 1
	v_readlane_b32 s5, v254, 2
	v_writelane_b32 v254, s96, 56
	s_and_b64 s[4:5], s[0:1], s[4:5]
	s_nop 0
	v_writelane_b32 v254, s97, 57
	s_mov_b64 exec, s[4:5]
	s_cbranch_execz .LBB0_1007
	s_add_i32 s3, 0, 0x10000
	v_mov_b32_e32 v0, s3
	s_waitcnt vmcnt(0) expcnt(0) lgkmcnt(0)
	ds_read_b32 v2, v0
	s_add_i32 s3, 0, 0x10004
	v_mov_b32_e32 v0, s3
	ds_read_b32 v0, v0
	s_waitcnt lgkmcnt(1)
	v_cmp_ne_u32_e32 vcc, 0, v2
	s_cbranch_vccnz .LBB0_971
	s_add_u32 s4, s50, 0x1000
	s_addc_u32 s5, s51, 0
	s_add_u32 s6, s50, 0x1100
	s_addc_u32 s7, s51, 0
	s_add_u32 s8, s50, 0x1200
	v_readlane_b32 s3, v254, 0
	s_addc_u32 s9, s51, 0
	s_mul_i32 s3, s29, s3
	s_add_u32 s10, s50, 0x1300
	s_mul_i32 s3, s3, s28
	s_addc_u32 s11, s51, 0
	s_mov_b32 s34, 1
	v_mov_b32_e32 v16, 0
	s_branch .LBB0_959

.Lto_j_a3:
	s_mul_i32 s98, s98, 17
	s_add_u32 s98, s98, s99
	s_lshl_b32 s99, s98, 3
	s_or_b32 s99, s99, s18
	s_mul_hi_i32 s6, s98, 0x78787879
	s_lshr_b32 s7, s6, 31
	s_ashr_i32 s6, s6, 3
	s_add_i32 s6, s6, s7
	s_mul_i32 s7, s6, 0xffffffef
	s_add_i32 s7, s7, s98
	s_lshl_b32 s7, s7, 3
	s_or_b32 s8, s7, s18
	v_mov_b32_e32 v0, v174
	s_ashr_i32 s9, s8, 31
	s_lshl_b64 s[10:11], s[8:9], 18
	v_bfe_u32 v2, v0, 1, 3
	v_lshrrev_b32_e32 v3, 4, v0
	v_bfe_u32 v4, v0, 4, 2
	v_lshlrev_b32_e32 v5, 7, v0
	v_and_b32_e32 v6, 0x780, v5
	v_bitop3_b32 v3, v3, v2, 3 bitop3:0x6c
	v_bitop3_b32 v2, v4, v2, 4 bitop3:0x36
	s_add_u32 s10, s38, s10
	v_lshl_or_b32 v7, v3, 4, v6
	v_lshl_or_b32 v6, v2, 4, v6
	v_lshlrev_b32_e32 v2, 6, v0
	s_addc_u32 s11, s39, s11
	s_ashr_i32 s7, s6, 31
	v_lshlrev_b32_e32 v1, 8, v0
	v_and_b32_e32 v8, 0xffffe000, v2
	v_lshlrev_b32_e32 v2, 4, v0
	s_lshl_b64 s[12:13], s[6:7], 18
	v_and_b32_e32 v1, 0xfffff800, v1
	v_xor_b32_e32 v0, v2, v0
	s_movk_i32 s7, 0x70
	v_add_u32_e32 v100, 0, v2
	v_and_or_b32 v64, v0, s7, v1
	v_readfirstlane_b32 s7, v100
	v_add_u32_e32 v101, 0x1000, v100
	s_mov_b32 m0, s7
	v_readfirstlane_b32 s7, v101
	v_add_u32_e32 v102, 0x2000, v100
	global_load_lds_dwordx4 v64, s[10:11]
	v_add_u32_e32 v0, 0x10000, v64
	s_mov_b32 m0, s7
	v_readfirstlane_b32 s7, v102
	v_add_u32_e32 v103, 0x3000, v100
	global_load_lds_dwordx4 v0, s[10:11]
	v_add_u32_e32 v2, 0x20000, v64
	s_mov_b32 m0, s7
	v_readfirstlane_b32 s7, v103
	v_add_u32_e32 v104, 0x4000, v100
	s_add_u32 s12, s36, s12
	global_load_lds_dwordx4 v2, s[10:11]
	v_add_u32_e32 v4, 0x30000, v64
	s_mov_b32 m0, s7
	v_readfirstlane_b32 s7, v104
	v_add_u32_e32 v105, 0x5000, v100
	s_addc_u32 s13, s37, s13
	global_load_lds_dwordx4 v4, s[10:11]
	s_mov_b32 m0, s7
	v_readfirstlane_b32 s7, v105
	v_add_u32_e32 v106, 0x6000, v100
	global_load_lds_dwordx4 v64, s[12:13]
	s_mov_b32 m0, s7
	v_readfirstlane_b32 s7, v106
	v_add_u32_e32 v107, 0x7000, v100
	global_load_lds_dwordx4 v0, s[12:13]
	s_mov_b32 m0, s7
	v_readfirstlane_b32 s7, v107
	global_load_lds_dwordx4 v2, s[12:13]
	s_mov_b32 m0, s7
	s_mul_i32 s7, s6, 0x88
	global_load_lds_dwordx4 v4, s[12:13]
	s_sub_i32 s10, s99, s7
	s_ashr_i32 s11, s10, 31
	s_lshl_b64 s[10:11], s[10:11], 18
	v_and_b32_e32 v9, 0x2000, v5
	s_add_u32 s10, s38, s10
	v_mov_b32_e32 v1, v65
	v_mov_b32_e32 v3, v65
	v_mov_b32_e32 v5, v65
	v_add_u32_e32 v8, 0, v8
	v_add_u32_e32 v9, 0, v9
	s_addc_u32 s11, s39, s11
	v_lshl_add_u64 v[66:67], s[12:13], 0, v[64:65]
	v_lshl_add_u64 v[68:69], s[12:13], 0, v[0:1]
	v_lshl_add_u64 v[70:71], s[12:13], 0, v[2:3]
	v_lshl_add_u64 v[72:73], s[12:13], 0, v[4:5]
	v_lshl_add_u64 v[74:75], s[10:11], 0, v[64:65]
	v_lshl_add_u64 v[76:77], s[10:11], 0, v[0:1]
	v_lshl_add_u64 v[78:79], s[10:11], 0, v[2:3]
	v_lshl_add_u64 v[80:81], s[10:11], 0, v[4:5]
	s_mov_b64 s[10:11], 0
	v_add_u32_e32 v64, 0x8000, v100
	v_add_u32_e32 v108, 0x9000, v100
	v_add_u32_e32 v109, 0xa000, v100
	v_add_u32_e32 v110, 0xb000, v100
	v_add_u32_e32 v111, 0xc000, v100
	v_add_u32_e32 v112, 0xd000, v100
	v_add_u32_e32 v113, 0xe000, v100
	v_add_u32_e32 v114, 0xf000, v100
	v_add_u32_e32 v115, v8, v7
	v_add_u32_e32 v116, v9, v7
	v_add_u32_e32 v117, v8, v6
	v_add_u32_e32 v118, v9, v6
	s_mov_b32 s7, 0
	v_mov_b32_e32 v0, 0
	v_mov_b32_e32 v2, v65
	v_mov_b32_e32 v4, 0
	v_mov_b32_e32 v6, v65
	v_mov_b32_e32 v7, v65
	v_mov_b32_e32 v8, 0
	v_mov_b32_e32 v9, v65
	v_mov_b32_e32 v10, v65
	v_mov_b32_e32 v11, v65
	v_mov_b32_e32 v12, 0
	v_mov_b32_e32 v13, v65
	v_mov_b32_e32 v14, v65
	v_mov_b32_e32 v15, v65
	v_mov_b32_e32 v16, 0
	v_mov_b32_e32 v17, v65
	v_mov_b32_e32 v18, v65
	v_mov_b32_e32 v19, v65
	v_mov_b32_e32 v20, 0
	v_mov_b32_e32 v21, v65
	v_mov_b32_e32 v22, v65
	v_mov_b32_e32 v23, v65
	v_mov_b32_e32 v24, 0
	v_mov_b32_e32 v25, v65
	v_mov_b32_e32 v26, v65
	v_mov_b32_e32 v27, v65
	v_mov_b32_e32 v28, 0
	v_mov_b32_e32 v29, v65
	v_mov_b32_e32 v30, v65
	v_mov_b32_e32 v31, v65
	v_mov_b32_e32 v32, 0
	v_mov_b32_e32 v33, v65
	v_mov_b32_e32 v34, v65
	v_mov_b32_e32 v35, v65
	v_mov_b32_e32 v36, 0
	v_mov_b32_e32 v37, v65
	v_mov_b32_e32 v38, v65
	v_mov_b32_e32 v39, v65
	v_mov_b32_e32 v40, 0
	v_mov_b32_e32 v41, v65
	v_mov_b32_e32 v42, v65
	v_mov_b32_e32 v43, v65
	v_mov_b32_e32 v44, 0
	v_mov_b32_e32 v45, v65
	v_mov_b32_e32 v46, v65
	v_mov_b32_e32 v47, v65
	v_mov_b32_e32 v48, 0
	v_mov_b32_e32 v49, v65
	v_mov_b32_e32 v50, v65
	v_mov_b32_e32 v51, v65
	v_mov_b32_e32 v52, 0
	v_mov_b32_e32 v53, v65
	v_mov_b32_e32 v54, v65
	v_mov_b32_e32 v55, v65
	v_mov_b32_e32 v56, 0
	v_mov_b32_e32 v57, v65
	v_mov_b32_e32 v58, v65
	v_mov_b32_e32 v59, v65
	v_mov_b32_e32 v60, 0
	v_mov_b32_e32 v61, v65
	v_mov_b32_e32 v62, v65
	v_mov_b32_e32 v63, v65
	s_mov_b64 s[98:99], s[0:1]
	v_readfirstlane_b32 s9, v64
	v_lshl_add_u64 v[250:251], v[74:75], 0, s[98:99]
	s_mov_b32 m0, s9
	v_readfirstlane_b32 s9, v108
	global_load_lds_dwordx4 v[250:251], off
	v_lshl_add_u64 v[250:251], v[76:77], 0, s[98:99]
	s_mov_b32 m0, s9
	v_readfirstlane_b32 s9, v109
	global_load_lds_dwordx4 v[250:251], off
	v_lshl_add_u64 v[250:251], v[78:79], 0, s[98:99]
	s_mov_b32 m0, s9
	v_readfirstlane_b32 s9, v110
	global_load_lds_dwordx4 v[250:251], off
	v_lshl_add_u64 v[250:251], v[80:81], 0, s[98:99]
	s_mov_b32 m0, s9
	v_readfirstlane_b32 s9, v111
	global_load_lds_dwordx4 v[250:251], off
	v_lshl_add_u64 v[250:251], v[66:67], 0, s[98:99]
	s_mov_b32 m0, s9
	v_readfirstlane_b32 s9, v112
	global_load_lds_dwordx4 v[250:251], off
	v_lshl_add_u64 v[250:251], v[68:69], 0, s[98:99]
	s_mov_b32 m0, s9
	v_readfirstlane_b32 s9, v113
	global_load_lds_dwordx4 v[250:251], off
	v_lshl_add_u64 v[250:251], v[70:71], 0, s[98:99]
	s_mov_b32 m0, s9
	v_readfirstlane_b32 s9, v114
	global_load_lds_dwordx4 v[250:251], off
	v_lshl_add_u64 v[250:251], v[72:73], 0, s[98:99]
	s_mov_b32 m0, s9
	s_nop 0
	global_load_lds_dwordx4 v[250:251], off
	s_branch .LBB0_1142

.Lgp_ej_5:
	s_branch .LBB0_1141
.LBB0_1144:
	s_waitcnt vmcnt(0)
	s_barrier
	s_mov_b64 s[0:1], exec
	v_readlane_b32 s4, v254, 1
	v_readlane_b32 s5, v254, 2
	s_and_b64 s[4:5], s[0:1], s[4:5]
	s_mov_b64 exec, s[4:5]
	s_cbranch_execz .LBB0_1196
	s_add_i32 s3, 0, 0x10000
	v_mov_b32_e32 v0, s3
	s_waitcnt vmcnt(0) expcnt(0) lgkmcnt(0)
	ds_read_b32 v2, v0
	s_add_i32 s3, 0, 0x10004
	v_mov_b32_e32 v0, s3
	ds_read_b32 v0, v0
	s_waitcnt lgkmcnt(1)
	v_cmp_ne_u32_e32 vcc, 0, v2
	s_cbranch_vccnz .LBB0_1160
	s_add_u32 s4, s50, 0x1000
	s_addc_u32 s5, s51, 0
	s_add_u32 s6, s50, 0x1100
	s_addc_u32 s7, s51, 0
	s_add_u32 s8, s50, 0x1200
	v_readlane_b32 s3, v254, 0
	s_addc_u32 s9, s51, 0
	s_mul_i32 s3, s29, s3
	s_add_u32 s10, s50, 0x1300
	s_mul_i32 s3, s3, s28
	s_addc_u32 s11, s51, 0
	s_mov_b32 s24, 1
	v_mov_b32_e32 v16, 0
	s_branch .LBB0_1148

.Lto_j_a4:
	s_mul_i32 s98, s98, 17
	s_add_u32 s98, s98, s99
	s_lshl_b32 s99, s98, 3
	s_or_b32 s99, s99, s20
	s_mul_hi_i32 s10, s98, 0x78787879
	s_lshr_b32 s11, s10, 31
	s_ashr_i32 s10, s10, 3
	s_add_i32 s10, s10, s11
	s_mul_i32 s11, s10, 0xffffffef
	s_add_i32 s11, s11, s98
	s_lshl_b32 s11, s11, 3
	v_mov_b32_e32 v0, v174
	s_or_b32 s12, s11, s20
	s_ashr_i32 s13, s12, 31
	v_bfe_u32 v2, v0, 1, 3
	v_lshrrev_b32_e32 v3, 4, v0
	v_bfe_u32 v4, v0, 4, 2
	v_lshlrev_b32_e32 v5, 7, v0
	v_and_b32_e32 v6, 0x780, v5
	v_bitop3_b32 v3, v3, v2, 3 bitop3:0x6c
	v_bitop3_b32 v2, v4, v2, 4 bitop3:0x36
	s_lshl_b64 s[16:17], s[12:13], 18
	v_lshl_or_b32 v7, v3, 4, v6
	v_lshl_or_b32 v6, v2, 4, v6
	v_lshlrev_b32_e32 v2, 6, v0
	s_add_u32 s16, s38, s16
	v_and_b32_e32 v8, 0xffffe000, v2
	v_lshlrev_b32_e32 v2, 4, v0
	s_addc_u32 s17, s39, s17
	s_ashr_i32 s11, s10, 31
	v_lshlrev_b32_e32 v1, 8, v0
	v_add_u32_e32 v100, 0, v2
	s_lshl_b64 s[18:19], s[10:11], 18
	v_and_b32_e32 v1, 0xfffff800, v1
	v_xor_b32_e32 v0, v2, v0
	v_readfirstlane_b32 s11, v100
	v_add_u32_e32 v101, 0x1000, v100
	v_and_or_b32 v64, v0, s27, v1
	s_mov_b32 m0, s11
	v_readfirstlane_b32 s11, v101
	v_add_u32_e32 v102, 0x2000, v100
	global_load_lds_dwordx4 v64, s[16:17]
	v_add_u32_e32 v0, 0x10000, v64
	s_mov_b32 m0, s11
	v_readfirstlane_b32 s11, v102
	v_add_u32_e32 v103, 0x3000, v100
	global_load_lds_dwordx4 v0, s[16:17]
	v_add_u32_e32 v2, 0x20000, v64
	s_mov_b32 m0, s11
	v_readfirstlane_b32 s11, v103
	v_add_u32_e32 v104, 0x4000, v100
	s_add_u32 s34, s24, s18
	global_load_lds_dwordx4 v2, s[16:17]
	v_add_u32_e32 v4, 0x30000, v64
	s_mov_b32 m0, s11
	v_readfirstlane_b32 s11, v104
	v_add_u32_e32 v105, 0x5000, v100
	s_addc_u32 s35, s25, s19
	global_load_lds_dwordx4 v4, s[16:17]
	s_mov_b32 m0, s11
	v_readfirstlane_b32 s11, v105
	v_add_u32_e32 v106, 0x6000, v100
	global_load_lds_dwordx4 v64, s[34:35]
	s_mov_b32 m0, s11
	v_readfirstlane_b32 s11, v106
	v_add_u32_e32 v107, 0x7000, v100
	global_load_lds_dwordx4 v0, s[34:35]
	s_mov_b32 m0, s11
	v_readfirstlane_b32 s11, v107
	global_load_lds_dwordx4 v2, s[34:35]
	s_mov_b32 m0, s11
	s_mul_i32 s11, s10, 0x88
	global_load_lds_dwordx4 v4, s[34:35]
	s_sub_i32 s16, s99, s11
	s_ashr_i32 s17, s16, 31
	s_lshl_b64 s[16:17], s[16:17], 18
	s_add_u32 s16, s38, s16
	v_and_b32_e32 v9, 0x2000, v5
	v_mov_b32_e32 v1, v65
	v_mov_b32_e32 v3, v65
	v_mov_b32_e32 v5, v65
	s_addc_u32 s17, s39, s17
	v_lshl_add_u64 v[66:67], s[16:17], 0, v[64:65]
	v_lshl_add_u64 v[68:69], s[16:17], 0, v[0:1]
	v_lshl_add_u64 v[70:71], s[16:17], 0, v[2:3]
	v_lshl_add_u64 v[72:73], s[16:17], 0, v[4:5]
	s_add_u32 s16, s36, s18
	v_add_u32_e32 v8, 0, v8
	v_add_u32_e32 v9, 0, v9
	s_addc_u32 s17, s37, s19
	v_lshl_add_u64 v[74:75], s[16:17], 0, v[64:65]
	v_lshl_add_u64 v[76:77], s[16:17], 0, v[0:1]
	v_lshl_add_u64 v[78:79], s[16:17], 0, v[2:3]
	v_lshl_add_u64 v[80:81], s[16:17], 0, v[4:5]
	s_mov_b64 s[16:17], 0
	v_add_u32_e32 v64, 0x8000, v100
	v_add_u32_e32 v108, 0x9000, v100
	v_add_u32_e32 v109, 0xa000, v100
	v_add_u32_e32 v110, 0xb000, v100
	v_add_u32_e32 v111, 0xc000, v100
	v_add_u32_e32 v112, 0xd000, v100
	v_add_u32_e32 v113, 0xe000, v100
	v_add_u32_e32 v114, 0xf000, v100
	v_add_u32_e32 v115, v8, v7
	v_add_u32_e32 v116, v9, v7
	v_add_u32_e32 v117, v8, v6
	v_add_u32_e32 v118, v9, v6
	s_mov_b32 s11, 0
	v_mov_b32_e32 v0, 0
	v_mov_b32_e32 v2, v65
	v_mov_b32_e32 v4, 0
	v_mov_b32_e32 v6, v65
	v_mov_b32_e32 v7, v65
	v_mov_b32_e32 v8, 0
	v_mov_b32_e32 v9, v65
	v_mov_b32_e32 v10, v65
	v_mov_b32_e32 v11, v65
	v_mov_b32_e32 v12, 0
	v_mov_b32_e32 v13, v65
	v_mov_b32_e32 v14, v65
	v_mov_b32_e32 v15, v65
	v_mov_b32_e32 v16, 0
	v_mov_b32_e32 v17, v65
	v_mov_b32_e32 v18, v65
	v_mov_b32_e32 v19, v65
	v_mov_b32_e32 v20, 0
	v_mov_b32_e32 v21, v65
	v_mov_b32_e32 v22, v65
	v_mov_b32_e32 v23, v65
	v_mov_b32_e32 v24, 0
	v_mov_b32_e32 v25, v65
	v_mov_b32_e32 v26, v65
	v_mov_b32_e32 v27, v65
	v_mov_b32_e32 v28, 0
	v_mov_b32_e32 v29, v65
	v_mov_b32_e32 v30, v65
	v_mov_b32_e32 v31, v65
	v_mov_b32_e32 v32, 0
	v_mov_b32_e32 v33, v65
	v_mov_b32_e32 v34, v65
	v_mov_b32_e32 v35, v65
	v_mov_b32_e32 v36, 0
	v_mov_b32_e32 v37, v65
	v_mov_b32_e32 v38, v65
	v_mov_b32_e32 v39, v65
	v_mov_b32_e32 v40, 0
	v_mov_b32_e32 v41, v65
	v_mov_b32_e32 v42, v65
	v_mov_b32_e32 v43, v65
	v_mov_b32_e32 v44, 0
	v_mov_b32_e32 v45, v65
	v_mov_b32_e32 v46, v65
	v_mov_b32_e32 v47, v65
	v_mov_b32_e32 v48, 0
	v_mov_b32_e32 v49, v65
	v_mov_b32_e32 v50, v65
	v_mov_b32_e32 v51, v65
	v_mov_b32_e32 v52, 0
	v_mov_b32_e32 v53, v65
	v_mov_b32_e32 v54, v65
	v_mov_b32_e32 v55, v65
	v_mov_b32_e32 v56, 0
	v_mov_b32_e32 v57, v65
	v_mov_b32_e32 v58, v65
	v_mov_b32_e32 v59, v65
	v_mov_b32_e32 v60, 0
	v_mov_b32_e32 v61, v65
	v_mov_b32_e32 v62, v65
	v_mov_b32_e32 v63, v65
	s_mov_b64 s[98:99], s[0:1]
	s_mov_b64 s[100:101], s[4:5]
	v_readfirstlane_b32 s13, v64
	v_lshl_add_u64 v[250:251], v[66:67], 0, s[98:99]
	s_mov_b32 m0, s13
	v_readfirstlane_b32 s13, v108
	global_load_lds_dwordx4 v[250:251], off
	v_lshl_add_u64 v[250:251], v[68:69], 0, s[98:99]
	s_mov_b32 m0, s13
	v_readfirstlane_b32 s13, v109
	global_load_lds_dwordx4 v[250:251], off
	v_lshl_add_u64 v[250:251], v[70:71], 0, s[98:99]
	s_mov_b32 m0, s13
	v_readfirstlane_b32 s13, v110
	global_load_lds_dwordx4 v[250:251], off
	v_lshl_add_u64 v[250:251], v[72:73], 0, s[98:99]
	s_mov_b32 m0, s13
	v_readfirstlane_b32 s13, v111
	global_load_lds_dwordx4 v[250:251], off
	v_lshl_add_u64 v[250:251], v[74:75], 0, s[100:101]
	s_mov_b32 m0, s13
	v_readfirstlane_b32 s13, v112
	global_load_lds_dwordx4 v[250:251], off
	v_lshl_add_u64 v[250:251], v[76:77], 0, s[100:101]
	s_mov_b32 m0, s13
	v_readfirstlane_b32 s13, v113
	global_load_lds_dwordx4 v[250:251], off
	v_lshl_add_u64 v[250:251], v[78:79], 0, s[100:101]
	s_mov_b32 m0, s13
	v_readfirstlane_b32 s13, v114
	global_load_lds_dwordx4 v[250:251], off
	v_lshl_add_u64 v[250:251], v[80:81], 0, s[100:101]
	s_mov_b32 m0, s13
	s_nop 0
	global_load_lds_dwordx4 v[250:251], off
	s_branch .LBB0_1593
.LBB0_1592:
	s_and_b64 vcc, exec, s[18:19]
	s_cbranch_vccnz .Lgp_ol_6
	s_waitcnt vmcnt(8)
	s_branch .Lgp_og_6

.Lgp_og_6:
	s_barrier
	s_nop 1
	ds_read_b128 v[82:85], v115 offset:32768
	ds_read_b128 v[86:89], v115 offset:34816
	ds_read_b128 v[90:93], v115 offset:36864
	ds_read_b128 v[94:97], v115 offset:38912
	ds_read_b128 v[120:123], v116 offset:49152
	ds_read_b128 v[124:127], v116 offset:51200
	ds_read_b128 v[128:131], v116 offset:53248
	ds_read_b128 v[132:135], v116 offset:55296
	s_add_i32 s11, s11, 2
	s_waitcnt lgkmcnt(0)
	v_mfma_f32_16x16x32_f16 v[0:3], v[120:123], v[82:85], v[0:3]
	ds_read_b128 v[136:139], v117 offset:32768
	v_mfma_f32_16x16x32_f16 v[4:7], v[124:127], v[82:85], v[4:7]
	v_mfma_f32_16x16x32_f16 v[8:11], v[128:131], v[82:85], v[8:11]
	ds_read_b128 v[140:143], v117 offset:34816
	v_mfma_f32_16x16x32_f16 v[12:15], v[132:135], v[82:85], v[12:15]
	v_mfma_f32_16x16x32_f16 v[16:19], v[120:123], v[86:89], v[16:19]
	ds_read_b128 v[144:147], v117 offset:36864
	v_mfma_f32_16x16x32_f16 v[20:23], v[124:127], v[86:89], v[20:23]
	v_mfma_f32_16x16x32_f16 v[24:27], v[128:131], v[86:89], v[24:27]
	ds_read_b128 v[148:151], v117 offset:38912
	v_mfma_f32_16x16x32_f16 v[28:31], v[132:135], v[86:89], v[28:31]
	v_mfma_f32_16x16x32_f16 v[82:85], v[120:123], v[90:93], v[32:35]
	ds_read_b128 v[152:155], v118 offset:49152
	v_mfma_f32_16x16x32_f16 v[86:89], v[124:127], v[90:93], v[36:39]
	v_mfma_f32_16x16x32_f16 v[168:171], v[128:131], v[90:93], v[40:43]
	ds_read_b128 v[156:159], v118 offset:51200
	v_mfma_f32_16x16x32_f16 v[90:93], v[132:135], v[90:93], v[44:47]
	v_mfma_f32_16x16x32_f16 v[120:123], v[120:123], v[94:97], v[48:51]
	ds_read_b128 v[160:163], v118 offset:53248
	v_mfma_f32_16x16x32_f16 v[124:127], v[124:127], v[94:97], v[52:55]
	v_mfma_f32_16x16x32_f16 v[128:131], v[128:131], v[94:97], v[56:59]
	ds_read_b128 v[164:167], v118 offset:55296
	v_mfma_f32_16x16x32_f16 v[94:97], v[132:135], v[94:97], v[60:63]
	s_waitcnt lgkmcnt(0)
	s_barrier
	s_and_b64 vcc, exec, s[18:19]
	s_cbranch_vccnz .Lgp_os_6
	s_add_u32 s98, s16, s6
	s_addc_u32 s99, s17, s7
	s_add_u32 s98, s98, 0x80
	s_addc_u32 s99, s99, 0
	s_add_u32 s100, s16, s8
	s_addc_u32 s101, s17, s9
	s_add_u32 s100, s100, 0x80
	s_addc_u32 s101, s101, 0
	v_readfirstlane_b32 s13, v64
	v_mfma_f32_16x16x32_f16 v[60:63], v[152:155], v[136:139], v[0:3]
	v_lshl_add_u64 v[250:251], v[66:67], 0, s[98:99]
	s_mov_b32 m0, s13
	v_readfirstlane_b32 s13, v108
	global_load_lds_dwordx4 v[250:251], off
	v_mfma_f32_16x16x32_f16 v[56:59], v[156:159], v[136:139], v[4:7]
	v_mfma_f32_16x16x32_f16 v[52:55], v[160:163], v[136:139], v[8:11]
	v_lshl_add_u64 v[250:251], v[68:69], 0, s[98:99]
	s_mov_b32 m0, s13
	v_readfirstlane_b32 s13, v109
	global_load_lds_dwordx4 v[250:251], off
	v_mfma_f32_16x16x32_f16 v[48:51], v[164:167], v[136:139], v[12:15]
	v_mfma_f32_16x16x32_f16 v[44:47], v[152:155], v[140:143], v[16:19]
	v_lshl_add_u64 v[250:251], v[70:71], 0, s[98:99]
	s_mov_b32 m0, s13
	v_readfirstlane_b32 s13, v110
	global_load_lds_dwordx4 v[250:251], off
	v_mfma_f32_16x16x32_f16 v[40:43], v[156:159], v[140:143], v[20:23]
	v_mfma_f32_16x16x32_f16 v[36:39], v[160:163], v[140:143], v[24:27]
	v_lshl_add_u64 v[250:251], v[72:73], 0, s[98:99]
	s_mov_b32 m0, s13
	v_readfirstlane_b32 s13, v111
	global_load_lds_dwordx4 v[250:251], off
	v_mfma_f32_16x16x32_f16 v[32:35], v[164:167], v[140:143], v[28:31]
	v_mfma_f32_16x16x32_f16 v[28:31], v[152:155], v[144:147], v[82:85]
	v_lshl_add_u64 v[250:251], v[74:75], 0, s[100:101]
	s_mov_b32 m0, s13
	v_readfirstlane_b32 s13, v112
	global_load_lds_dwordx4 v[250:251], off
	v_mfma_f32_16x16x32_f16 v[24:27], v[156:159], v[144:147], v[86:89]
	v_mfma_f32_16x16x32_f16 v[20:23], v[160:163], v[144:147], v[168:171]
	v_lshl_add_u64 v[250:251], v[76:77], 0, s[100:101]
	s_mov_b32 m0, s13
	v_readfirstlane_b32 s13, v113
	global_load_lds_dwordx4 v[250:251], off
	v_mfma_f32_16x16x32_f16 v[16:19], v[164:167], v[144:147], v[90:93]
	v_mfma_f32_16x16x32_f16 v[12:15], v[152:155], v[148:151], v[120:123]
	v_lshl_add_u64 v[250:251], v[78:79], 0, s[100:101]
	s_mov_b32 m0, s13
	v_readfirstlane_b32 s13, v114
	global_load_lds_dwordx4 v[250:251], off
	v_mfma_f32_16x16x32_f16 v[8:11], v[156:159], v[148:151], v[124:127]
	v_mfma_f32_16x16x32_f16 v[4:7], v[160:163], v[148:151], v[128:131]
	v_lshl_add_u64 v[250:251], v[80:81], 0, s[100:101]
	s_mov_b32 m0, s13
	s_nop 0
	global_load_lds_dwordx4 v[250:251], off
	v_mfma_f32_16x16x32_f16 v[0:3], v[164:167], v[148:151], v[94:97]
	s_branch .Lgp_oj_6

.Lgp_oj_6:
	s_add_u32 s16, s16, 0x100
	s_addc_u32 s17, s17, 0
	s_andn2_b64 vcc, exec, s[18:19]
	s_cbranch_vccz .LBB0_1590
.LBB0_1593:
	s_waitcnt vmcnt(8)
	s_barrier
	s_nop 1
	ds_read_b128 v[120:123], v115
	ds_read_b128 v[124:127], v115 offset:2048
	ds_read_b128 v[128:131], v115 offset:4096
	ds_read_b128 v[132:135], v115 offset:6144
	ds_read_b128 v[136:139], v116 offset:16384
	ds_read_b128 v[140:143], v116 offset:18432
	ds_read_b128 v[144:147], v116 offset:20480
	ds_read_b128 v[148:151], v116 offset:22528
	s_cmp_gt_u32 s11, 13
	s_cselect_b64 s[18:19], -1, 0
	s_waitcnt lgkmcnt(0)
	v_mfma_f32_16x16x32_f16 v[60:63], v[136:139], v[120:123], v[60:63]
	ds_read_b128 v[152:155], v117
	v_mfma_f32_16x16x32_f16 v[56:59], v[140:143], v[120:123], v[56:59]
	v_mfma_f32_16x16x32_f16 v[52:55], v[144:147], v[120:123], v[52:55]
	ds_read_b128 v[156:159], v117 offset:2048
	v_mfma_f32_16x16x32_f16 v[48:51], v[148:151], v[120:123], v[48:51]
	v_mfma_f32_16x16x32_f16 v[44:47], v[136:139], v[124:127], v[44:47]
	ds_read_b128 v[160:163], v117 offset:4096
	v_mfma_f32_16x16x32_f16 v[40:43], v[140:143], v[124:127], v[40:43]
	v_mfma_f32_16x16x32_f16 v[36:39], v[144:147], v[124:127], v[36:39]
	ds_read_b128 v[164:167], v117 offset:6144
	v_mfma_f32_16x16x32_f16 v[32:35], v[148:151], v[124:127], v[32:35]
	v_mfma_f32_16x16x32_f16 v[120:123], v[136:139], v[128:131], v[28:31]
	ds_read_b128 v[168:171], v118 offset:16384
	v_mfma_f32_16x16x32_f16 v[124:127], v[140:143], v[128:131], v[24:27]
	v_mfma_f32_16x16x32_f16 v[188:191], v[144:147], v[128:131], v[20:23]
	ds_read_b128 v[176:179], v118 offset:18432
	v_mfma_f32_16x16x32_f16 v[128:131], v[148:151], v[128:131], v[16:19]
	v_mfma_f32_16x16x32_f16 v[136:139], v[136:139], v[132:135], v[12:15]
	ds_read_b128 v[180:183], v118 offset:20480
	v_mfma_f32_16x16x32_f16 v[140:143], v[140:143], v[132:135], v[8:11]
	v_mfma_f32_16x16x32_f16 v[144:147], v[144:147], v[132:135], v[4:7]
	ds_read_b128 v[184:187], v118 offset:22528
	v_mfma_f32_16x16x32_f16 v[132:135], v[148:151], v[132:135], v[0:3]
	s_waitcnt lgkmcnt(0)
	s_barrier
	s_and_b64 vcc, exec, s[18:19]
	s_cbranch_vccnz .Lgp_es_6
	s_add_u32 s98, s16, s6
	s_addc_u32 s99, s17, s7
	s_add_u32 s100, s16, s8
	s_addc_u32 s101, s17, s9
	v_readfirstlane_b32 s13, v100
	v_mfma_f32_16x16x32_f16 v[0:3], v[168:171], v[152:155], v[60:63]
	v_lshl_add_u64 v[250:251], v[66:67], 0, s[98:99]
	s_mov_b32 m0, s13
	v_readfirstlane_b32 s13, v101
	global_load_lds_dwordx4 v[250:251], off
	v_mfma_f32_16x16x32_f16 v[4:7], v[176:179], v[152:155], v[56:59]
	v_mfma_f32_16x16x32_f16 v[8:11], v[180:183], v[152:155], v[52:55]
	v_lshl_add_u64 v[250:251], v[68:69], 0, s[98:99]
	s_mov_b32 m0, s13
	v_readfirstlane_b32 s13, v102
	global_load_lds_dwordx4 v[250:251], off
	v_mfma_f32_16x16x32_f16 v[12:15], v[184:187], v[152:155], v[48:51]
	v_mfma_f32_16x16x32_f16 v[16:19], v[168:171], v[156:159], v[44:47]
	v_lshl_add_u64 v[250:251], v[70:71], 0, s[98:99]
	s_mov_b32 m0, s13
	v_readfirstlane_b32 s13, v103
	global_load_lds_dwordx4 v[250:251], off
	v_mfma_f32_16x16x32_f16 v[20:23], v[176:179], v[156:159], v[40:43]
	v_mfma_f32_16x16x32_f16 v[24:27], v[180:183], v[156:159], v[36:39]
	v_lshl_add_u64 v[250:251], v[72:73], 0, s[98:99]
	s_mov_b32 m0, s13
	v_readfirstlane_b32 s13, v104
	global_load_lds_dwordx4 v[250:251], off
	v_mfma_f32_16x16x32_f16 v[28:31], v[184:187], v[156:159], v[32:35]
	v_mfma_f32_16x16x32_f16 v[32:35], v[168:171], v[160:163], v[120:123]
	v_lshl_add_u64 v[250:251], v[74:75], 0, s[100:101]
	s_mov_b32 m0, s13
	v_readfirstlane_b32 s13, v105
	global_load_lds_dwordx4 v[250:251], off
	v_mfma_f32_16x16x32_f16 v[36:39], v[176:179], v[160:163], v[124:127]
	v_mfma_f32_16x16x32_f16 v[40:43], v[180:183], v[160:163], v[188:191]
	v_lshl_add_u64 v[250:251], v[76:77], 0, s[100:101]
	s_mov_b32 m0, s13
	v_readfirstlane_b32 s13, v106
	global_load_lds_dwordx4 v[250:251], off
	v_mfma_f32_16x16x32_f16 v[44:47], v[184:187], v[160:163], v[128:131]
	v_mfma_f32_16x16x32_f16 v[48:51], v[168:171], v[164:167], v[136:139]
	v_lshl_add_u64 v[250:251], v[78:79], 0, s[100:101]
	s_mov_b32 m0, s13
	v_readfirstlane_b32 s13, v107
	global_load_lds_dwordx4 v[250:251], off
	v_mfma_f32_16x16x32_f16 v[52:55], v[176:179], v[164:167], v[140:143]
	v_mfma_f32_16x16x32_f16 v[56:59], v[180:183], v[164:167], v[144:147]
	v_lshl_add_u64 v[250:251], v[80:81], 0, s[100:101]
	s_mov_b32 m0, s13
	s_nop 0
	global_load_lds_dwordx4 v[250:251], off
	v_mfma_f32_16x16x32_f16 v[60:63], v[184:187], v[164:167], v[132:135]
	s_branch .Lgp_ej_6

.Lgp_ej_6:
	s_branch .LBB0_1592
.LBB0_1595:
	s_waitcnt vmcnt(0)
	s_barrier
	s_mov_b64 s[0:1], exec
	v_readlane_b32 s4, v254, 1
	v_readlane_b32 s5, v254, 2
	s_and_b64 s[4:5], s[0:1], s[4:5]
	s_mov_b64 exec, s[4:5]
	s_cbranch_execz .LBB0_1647
	s_add_i32 s3, 0, 0x10000
	v_mov_b32_e32 v0, s3
	s_waitcnt vmcnt(0) expcnt(0) lgkmcnt(0)
	ds_read_b32 v2, v0
	s_add_i32 s3, 0, 0x10004
	v_mov_b32_e32 v0, s3
	ds_read_b32 v0, v0
	s_waitcnt lgkmcnt(1)
	v_cmp_ne_u32_e32 vcc, 0, v2
	s_cbranch_vccnz .LBB0_1611
	s_add_u32 s4, s50, 0x1000
	s_addc_u32 s5, s51, 0
	s_add_u32 s6, s50, 0x1100
	s_addc_u32 s7, s51, 0
	s_add_u32 s8, s50, 0x1200
	v_readlane_b32 s3, v254, 0
	s_addc_u32 s9, s51, 0
	s_mul_i32 s3, s29, s3
	s_add_u32 s10, s50, 0x1300
	s_mul_i32 s3, s3, s28
	s_addc_u32 s11, s51, 0
	s_mov_b32 s20, 1
	v_mov_b32_e32 v16, 0
	s_branch .LBB0_1599

.Lto_j_b4:
	s_mul_i32 s98, s98, 17
	s_add_u32 s98, s98, s99
	s_lshl_b32 s99, s98, 3
	s_or_b32 s99, s99, s20
	s_mul_hi_i32 s10, s98, 0x78787879
	s_lshr_b32 s11, s10, 31
	s_ashr_i32 s10, s10, 3
	s_add_i32 s10, s10, s11
	s_mul_i32 s11, s10, 0xffffffef
	s_add_i32 s11, s11, s98
	s_lshl_b32 s11, s11, 3
	v_mov_b32_e32 v0, v174
	s_or_b32 s12, s11, s20
	s_ashr_i32 s13, s12, 31
	v_bfe_u32 v2, v0, 1, 3
	v_lshrrev_b32_e32 v3, 4, v0
	s_waitcnt vmcnt(5)
	v_bfe_u32 v4, v0, 4, 2
	v_lshlrev_b32_e32 v5, 7, v0
	v_and_b32_e32 v6, 0x780, v5
	v_bitop3_b32 v3, v3, v2, 3 bitop3:0x6c
	v_bitop3_b32 v2, v4, v2, 4 bitop3:0x36
	s_lshl_b64 s[16:17], s[12:13], 18
	v_lshl_or_b32 v7, v3, 4, v6
	v_lshl_or_b32 v6, v2, 4, v6
	v_lshlrev_b32_e32 v2, 6, v0
	s_add_u32 s16, s38, s16
	v_and_b32_e32 v8, 0xffffe000, v2
	v_lshlrev_b32_e32 v2, 4, v0
	s_addc_u32 s17, s39, s17
	s_ashr_i32 s11, s10, 31
	v_lshlrev_b32_e32 v1, 8, v0
	v_add_u32_e32 v100, 0, v2
	s_lshl_b64 s[18:19], s[10:11], 18
	v_and_b32_e32 v1, 0xfffff800, v1
	v_xor_b32_e32 v0, v2, v0
	v_readfirstlane_b32 s11, v100
	v_add_u32_e32 v101, 0x1000, v100
	v_and_or_b32 v64, v0, s25, v1
	s_mov_b32 m0, s11
	v_readfirstlane_b32 s11, v101
	v_add_u32_e32 v102, 0x2000, v100
	global_load_lds_dwordx4 v64, s[16:17]
	v_add_u32_e32 v0, 0x10000, v64
	s_mov_b32 m0, s11
	v_readfirstlane_b32 s11, v102
	v_add_u32_e32 v103, 0x3000, v100
	global_load_lds_dwordx4 v0, s[16:17]
	v_add_u32_e32 v2, 0x20000, v64
	s_mov_b32 m0, s11
	v_readfirstlane_b32 s11, v103
	v_add_u32_e32 v104, 0x4000, v100
	s_add_u32 s26, s70, s18
	global_load_lds_dwordx4 v2, s[16:17]
	v_add_u32_e32 v4, 0x30000, v64
	s_mov_b32 m0, s11
	v_readfirstlane_b32 s11, v104
	v_add_u32_e32 v105, 0x5000, v100
	s_addc_u32 s27, s71, s19
	global_load_lds_dwordx4 v4, s[16:17]
	s_mov_b32 m0, s11
	v_readfirstlane_b32 s11, v105
	v_add_u32_e32 v106, 0x6000, v100
	global_load_lds_dwordx4 v64, s[26:27]
	s_mov_b32 m0, s11
	v_readfirstlane_b32 s11, v106
	v_add_u32_e32 v107, 0x7000, v100
	global_load_lds_dwordx4 v0, s[26:27]
	s_mov_b32 m0, s11
	v_readfirstlane_b32 s11, v107
	global_load_lds_dwordx4 v2, s[26:27]
	s_mov_b32 m0, s11
	s_mul_i32 s11, s10, 0x88
	global_load_lds_dwordx4 v4, s[26:27]
	s_sub_i32 s16, s99, s11
	s_ashr_i32 s17, s16, 31
	s_lshl_b64 s[16:17], s[16:17], 18
	s_add_u32 s16, s38, s16
	v_and_b32_e32 v9, 0x2000, v5
	v_mov_b32_e32 v1, v65
	v_mov_b32_e32 v3, v65
	v_mov_b32_e32 v5, v65
	s_addc_u32 s17, s39, s17
	v_lshl_add_u64 v[66:67], s[16:17], 0, v[64:65]
	v_lshl_add_u64 v[68:69], s[16:17], 0, v[0:1]
	v_lshl_add_u64 v[70:71], s[16:17], 0, v[2:3]
	v_lshl_add_u64 v[72:73], s[16:17], 0, v[4:5]
	s_add_u32 s16, s36, s18
	v_add_u32_e32 v8, 0, v8
	v_add_u32_e32 v9, 0, v9
	s_addc_u32 s17, s37, s19
	v_lshl_add_u64 v[74:75], s[16:17], 0, v[64:65]
	v_lshl_add_u64 v[76:77], s[16:17], 0, v[0:1]
	v_lshl_add_u64 v[78:79], s[16:17], 0, v[2:3]
	v_lshl_add_u64 v[80:81], s[16:17], 0, v[4:5]
	s_mov_b64 s[16:17], 0
	v_add_u32_e32 v64, 0x8000, v100
	v_add_u32_e32 v108, 0x9000, v100
	v_add_u32_e32 v109, 0xa000, v100
	v_add_u32_e32 v110, 0xb000, v100
	v_add_u32_e32 v111, 0xc000, v100
	v_add_u32_e32 v112, 0xd000, v100
	v_add_u32_e32 v113, 0xe000, v100
	v_add_u32_e32 v114, 0xf000, v100
	v_add_u32_e32 v115, v8, v7
	v_add_u32_e32 v116, v9, v7
	v_add_u32_e32 v117, v8, v6
	v_add_u32_e32 v118, v9, v6
	s_mov_b32 s11, 0
	v_mov_b32_e32 v0, 0
	v_mov_b32_e32 v2, v65
	v_mov_b32_e32 v4, 0
	v_mov_b32_e32 v6, v65
	v_mov_b32_e32 v7, v65
	v_mov_b32_e32 v8, 0
	v_mov_b32_e32 v9, v65
	v_mov_b32_e32 v10, v65
	v_mov_b32_e32 v11, v65
	v_mov_b32_e32 v12, 0
	v_mov_b32_e32 v13, v65
	v_mov_b32_e32 v14, v65
	v_mov_b32_e32 v15, v65
	v_mov_b32_e32 v16, 0
	v_mov_b32_e32 v17, v65
	v_mov_b32_e32 v18, v65
	v_mov_b32_e32 v19, v65
	v_mov_b32_e32 v20, 0
	v_mov_b32_e32 v21, v65
	v_mov_b32_e32 v22, v65
	v_mov_b32_e32 v23, v65
	v_mov_b32_e32 v24, 0
	v_mov_b32_e32 v25, v65
	v_mov_b32_e32 v26, v65
	v_mov_b32_e32 v27, v65
	v_mov_b32_e32 v28, 0
	v_mov_b32_e32 v29, v65
	v_mov_b32_e32 v30, v65
	v_mov_b32_e32 v31, v65
	v_mov_b32_e32 v32, 0
	v_mov_b32_e32 v33, v65
	v_mov_b32_e32 v34, v65
	v_mov_b32_e32 v35, v65
	v_mov_b32_e32 v36, 0
	v_mov_b32_e32 v37, v65
	v_mov_b32_e32 v38, v65
	v_mov_b32_e32 v39, v65
	v_mov_b32_e32 v40, 0
	v_mov_b32_e32 v41, v65
	v_mov_b32_e32 v42, v65
	v_mov_b32_e32 v43, v65
	v_mov_b32_e32 v44, 0
	v_mov_b32_e32 v45, v65
	v_mov_b32_e32 v46, v65
	v_mov_b32_e32 v47, v65
	v_mov_b32_e32 v48, 0
	v_mov_b32_e32 v49, v65
	v_mov_b32_e32 v50, v65
	v_mov_b32_e32 v51, v65
	v_mov_b32_e32 v52, 0
	v_mov_b32_e32 v53, v65
	s_waitcnt vmcnt(0)
	v_mov_b32_e32 v54, v65
	v_mov_b32_e32 v55, v65
	v_mov_b32_e32 v56, 0
	v_mov_b32_e32 v57, v65
	v_mov_b32_e32 v58, v65
	v_mov_b32_e32 v59, v65
	v_mov_b32_e32 v60, 0
	v_mov_b32_e32 v61, v65
	v_mov_b32_e32 v62, v65
	v_mov_b32_e32 v63, v65
	s_mov_b64 s[98:99], s[0:1]
	s_mov_b64 s[100:101], s[4:5]
	v_readfirstlane_b32 s13, v64
	v_lshl_add_u64 v[250:251], v[66:67], 0, s[98:99]
	s_mov_b32 m0, s13
	v_readfirstlane_b32 s13, v108
	global_load_lds_dwordx4 v[250:251], off
	v_lshl_add_u64 v[250:251], v[68:69], 0, s[98:99]
	s_mov_b32 m0, s13
	v_readfirstlane_b32 s13, v109
	global_load_lds_dwordx4 v[250:251], off
	v_lshl_add_u64 v[250:251], v[70:71], 0, s[98:99]
	s_mov_b32 m0, s13
	v_readfirstlane_b32 s13, v110
	global_load_lds_dwordx4 v[250:251], off
	v_lshl_add_u64 v[250:251], v[72:73], 0, s[98:99]
	s_mov_b32 m0, s13
	v_readfirstlane_b32 s13, v111
	global_load_lds_dwordx4 v[250:251], off
	v_lshl_add_u64 v[250:251], v[74:75], 0, s[100:101]
	s_mov_b32 m0, s13
	v_readfirstlane_b32 s13, v112
	global_load_lds_dwordx4 v[250:251], off
	v_lshl_add_u64 v[250:251], v[76:77], 0, s[100:101]
	s_mov_b32 m0, s13
	v_readfirstlane_b32 s13, v113
	global_load_lds_dwordx4 v[250:251], off
	v_lshl_add_u64 v[250:251], v[78:79], 0, s[100:101]
	s_mov_b32 m0, s13
	v_readfirstlane_b32 s13, v114
	global_load_lds_dwordx4 v[250:251], off
	v_lshl_add_u64 v[250:251], v[80:81], 0, s[100:101]
	s_mov_b32 m0, s13
	s_nop 0
	global_load_lds_dwordx4 v[250:251], off
	s_branch .LBB0_1735

.Lgp_ej_7:
	s_branch .LBB0_1734
.LBB0_1737:
	s_waitcnt vmcnt(0)
	s_barrier
	s_mov_b64 s[0:1], exec
	v_readlane_b32 s4, v254, 1
	v_readlane_b32 s5, v254, 2
	s_and_b64 s[4:5], s[0:1], s[4:5]
	s_mov_b64 exec, s[4:5]
	s_cbranch_execz .LBB0_1789
	s_add_i32 s3, 0, 0x10000
	v_mov_b32_e32 v0, s3
	s_waitcnt vmcnt(0) expcnt(0) lgkmcnt(0)
	ds_read_b32 v2, v0
	s_add_i32 s3, 0, 0x10004
	v_mov_b32_e32 v0, s3
	ds_read_b32 v0, v0
	s_waitcnt lgkmcnt(1)
	v_cmp_ne_u32_e32 vcc, 0, v2
	s_cbranch_vccnz .LBB0_1753
	s_add_u32 s4, s50, 0x1000
	s_addc_u32 s5, s51, 0
	s_add_u32 s6, s50, 0x1100
	s_addc_u32 s7, s51, 0
	s_add_u32 s8, s50, 0x1200
	v_readlane_b32 s3, v254, 0
	s_addc_u32 s9, s51, 0
	s_mul_i32 s3, s29, s3
	s_add_u32 s10, s50, 0x1300
	s_mul_i32 s3, s3, s28
	s_addc_u32 s11, s51, 0
	s_mov_b32 s20, 1
	v_mov_b32_e32 v16, 0
	s_branch .LBB0_1741

.Lto_j_a5:
	s_mul_i32 s98, s98, 17
	s_add_u32 s98, s98, s99
	s_lshl_b32 s99, s98, 3
	s_or_b32 s99, s99, s20
	s_mul_hi_i32 s10, s98, 0x78787879
	s_lshr_b32 s11, s10, 31
	s_ashr_i32 s10, s10, 3
	s_add_i32 s10, s10, s11
	s_mul_i32 s11, s10, 0xffffffef
	s_add_i32 s11, s11, s98
	s_lshl_b32 s11, s11, 3
	v_mov_b32_e32 v0, v174
	s_or_b32 s12, s11, s20
	s_ashr_i32 s13, s12, 31
	v_bfe_u32 v2, v0, 1, 3
	v_lshrrev_b32_e32 v3, 4, v0
	v_bfe_u32 v4, v0, 4, 2
	v_lshlrev_b32_e32 v5, 7, v0
	v_and_b32_e32 v6, 0x780, v5
	v_bitop3_b32 v3, v3, v2, 3 bitop3:0x6c
	v_bitop3_b32 v2, v4, v2, 4 bitop3:0x36
	s_lshl_b64 s[16:17], s[12:13], 18
	v_lshl_or_b32 v7, v3, 4, v6
	v_lshl_or_b32 v6, v2, 4, v6
	v_lshlrev_b32_e32 v2, 6, v0
	s_add_u32 s16, s38, s16
	v_and_b32_e32 v8, 0xffffe000, v2
	v_lshlrev_b32_e32 v2, 4, v0
	s_addc_u32 s17, s39, s17
	s_ashr_i32 s11, s10, 31
	v_lshlrev_b32_e32 v1, 8, v0
	v_add_u32_e32 v100, 0, v2
	s_lshl_b64 s[18:19], s[10:11], 18
	v_and_b32_e32 v1, 0xfffff800, v1
	v_xor_b32_e32 v0, v2, v0
	v_readfirstlane_b32 s11, v100
	v_add_u32_e32 v101, 0x1000, v100
	v_and_or_b32 v64, v0, s25, v1
	s_mov_b32 m0, s11
	v_readfirstlane_b32 s11, v101
	v_add_u32_e32 v102, 0x2000, v100
	global_load_lds_dwordx4 v64, s[16:17]
	v_add_u32_e32 v0, 0x10000, v64
	s_mov_b32 m0, s11
	v_readfirstlane_b32 s11, v102
	v_add_u32_e32 v103, 0x3000, v100
	global_load_lds_dwordx4 v0, s[16:17]
	v_add_u32_e32 v2, 0x20000, v64
	s_mov_b32 m0, s11
	v_readfirstlane_b32 s11, v103
	v_add_u32_e32 v104, 0x4000, v100
	s_add_u32 s34, s22, s18
	global_load_lds_dwordx4 v2, s[16:17]
	v_add_u32_e32 v4, 0x30000, v64
	s_mov_b32 m0, s11
	v_readfirstlane_b32 s11, v104
	v_add_u32_e32 v105, 0x5000, v100
	s_addc_u32 s35, s23, s19
	global_load_lds_dwordx4 v4, s[16:17]
	s_mov_b32 m0, s11
	v_readfirstlane_b32 s11, v105
	v_add_u32_e32 v106, 0x6000, v100
	global_load_lds_dwordx4 v64, s[34:35]
	s_mov_b32 m0, s11
	v_readfirstlane_b32 s11, v106
	v_add_u32_e32 v107, 0x7000, v100
	global_load_lds_dwordx4 v0, s[34:35]
	s_mov_b32 m0, s11
	v_readfirstlane_b32 s11, v107
	global_load_lds_dwordx4 v2, s[34:35]
	s_mov_b32 m0, s11
	s_mul_i32 s11, s10, 0x88
	global_load_lds_dwordx4 v4, s[34:35]
	s_sub_i32 s16, s99, s11
	s_ashr_i32 s17, s16, 31
	s_lshl_b64 s[16:17], s[16:17], 18
	s_add_u32 s16, s38, s16
	v_and_b32_e32 v9, 0x2000, v5
	v_mov_b32_e32 v1, v65
	v_mov_b32_e32 v3, v65
	v_mov_b32_e32 v5, v65
	s_addc_u32 s17, s39, s17
	v_lshl_add_u64 v[66:67], s[16:17], 0, v[64:65]
	v_lshl_add_u64 v[68:69], s[16:17], 0, v[0:1]
	v_lshl_add_u64 v[70:71], s[16:17], 0, v[2:3]
	v_lshl_add_u64 v[72:73], s[16:17], 0, v[4:5]
	s_add_u32 s16, s36, s18
	v_add_u32_e32 v8, 0, v8
	v_add_u32_e32 v9, 0, v9
	s_addc_u32 s17, s37, s19
	v_lshl_add_u64 v[74:75], s[16:17], 0, v[64:65]
	v_lshl_add_u64 v[76:77], s[16:17], 0, v[0:1]
	v_lshl_add_u64 v[78:79], s[16:17], 0, v[2:3]
	v_lshl_add_u64 v[80:81], s[16:17], 0, v[4:5]
	s_mov_b64 s[16:17], 0
	v_add_u32_e32 v64, 0x8000, v100
	v_add_u32_e32 v108, 0x9000, v100
	v_add_u32_e32 v109, 0xa000, v100
	v_add_u32_e32 v110, 0xb000, v100
	v_add_u32_e32 v111, 0xc000, v100
	v_add_u32_e32 v112, 0xd000, v100
	v_add_u32_e32 v113, 0xe000, v100
	v_add_u32_e32 v114, 0xf000, v100
	v_add_u32_e32 v115, v8, v7
	v_add_u32_e32 v116, v9, v7
	v_add_u32_e32 v117, v8, v6
	v_add_u32_e32 v118, v9, v6
	s_mov_b32 s11, 0
	v_mov_b32_e32 v0, 0
	v_mov_b32_e32 v2, v65
	v_mov_b32_e32 v8, 0
	v_mov_b32_e32 v9, v65
	v_mov_b32_e32 v10, v65
	v_mov_b32_e32 v11, v65
	v_mov_b32_e32 v4, 0
	v_mov_b32_e32 v6, v65
	v_mov_b32_e32 v7, v65
	v_mov_b32_e32 v12, 0
	v_mov_b32_e32 v13, v65
	v_mov_b32_e32 v14, v65
	v_mov_b32_e32 v15, v65
	v_mov_b32_e32 v16, 0
	v_mov_b32_e32 v17, v65
	v_mov_b32_e32 v18, v65
	v_mov_b32_e32 v19, v65
	v_mov_b32_e32 v24, 0
	v_mov_b32_e32 v25, v65
	v_mov_b32_e32 v26, v65
	v_mov_b32_e32 v27, v65
	v_mov_b32_e32 v20, 0
	v_mov_b32_e32 v21, v65
	v_mov_b32_e32 v22, v65
	v_mov_b32_e32 v23, v65
	v_mov_b32_e32 v28, 0
	v_mov_b32_e32 v29, v65
	v_mov_b32_e32 v30, v65
	v_mov_b32_e32 v31, v65
	v_mov_b32_e32 v32, 0
	v_mov_b32_e32 v33, v65
	v_mov_b32_e32 v34, v65
	v_mov_b32_e32 v35, v65
	v_mov_b32_e32 v40, 0
	v_mov_b32_e32 v41, v65
	v_mov_b32_e32 v42, v65
	v_mov_b32_e32 v43, v65
	v_mov_b32_e32 v36, 0
	v_mov_b32_e32 v37, v65
	v_mov_b32_e32 v38, v65
	v_mov_b32_e32 v39, v65
	v_mov_b32_e32 v44, 0
	v_mov_b32_e32 v45, v65
	v_mov_b32_e32 v46, v65
	v_mov_b32_e32 v47, v65
	v_mov_b32_e32 v48, 0
	v_mov_b32_e32 v49, v65
	v_mov_b32_e32 v50, v65
	v_mov_b32_e32 v51, v65
	v_mov_b32_e32 v56, 0
	v_mov_b32_e32 v57, v65
	v_mov_b32_e32 v58, v65
	v_mov_b32_e32 v59, v65
	v_mov_b32_e32 v52, 0
	v_mov_b32_e32 v53, v65
	v_mov_b32_e32 v54, v65
	v_mov_b32_e32 v55, v65
	v_mov_b32_e32 v60, 0
	v_mov_b32_e32 v61, v65
	v_mov_b32_e32 v62, v65
	v_mov_b32_e32 v63, v65
	s_mov_b64 s[98:99], s[0:1]
	s_mov_b64 s[100:101], s[4:5]
	v_readfirstlane_b32 s13, v64
	v_lshl_add_u64 v[250:251], v[66:67], 0, s[98:99]
	s_mov_b32 m0, s13
	v_readfirstlane_b32 s13, v108
	global_load_lds_dwordx4 v[250:251], off
	v_lshl_add_u64 v[250:251], v[68:69], 0, s[98:99]
	s_mov_b32 m0, s13
	v_readfirstlane_b32 s13, v109
	global_load_lds_dwordx4 v[250:251], off
	v_lshl_add_u64 v[250:251], v[70:71], 0, s[98:99]
	s_mov_b32 m0, s13
	v_readfirstlane_b32 s13, v110
	global_load_lds_dwordx4 v[250:251], off
	v_lshl_add_u64 v[250:251], v[72:73], 0, s[98:99]
	s_mov_b32 m0, s13
	v_readfirstlane_b32 s13, v111
	global_load_lds_dwordx4 v[250:251], off
	v_lshl_add_u64 v[250:251], v[74:75], 0, s[100:101]
	s_mov_b32 m0, s13
	v_readfirstlane_b32 s13, v112
	global_load_lds_dwordx4 v[250:251], off
	v_lshl_add_u64 v[250:251], v[76:77], 0, s[100:101]
	s_mov_b32 m0, s13
	v_readfirstlane_b32 s13, v113
	global_load_lds_dwordx4 v[250:251], off
	v_lshl_add_u64 v[250:251], v[78:79], 0, s[100:101]
	s_mov_b32 m0, s13
	v_readfirstlane_b32 s13, v114
	global_load_lds_dwordx4 v[250:251], off
	v_lshl_add_u64 v[250:251], v[80:81], 0, s[100:101]
	s_mov_b32 m0, s13
	s_nop 0
	global_load_lds_dwordx4 v[250:251], off
	s_branch .LBB0_1867

.Lgp_og_8:
	s_barrier
	s_nop 1
	ds_read_b128 v[82:85], v115 offset:32768
	ds_read_b128 v[86:89], v115 offset:34816
	ds_read_b128 v[90:93], v115 offset:36864
	ds_read_b128 v[94:97], v115 offset:38912
	ds_read_b128 v[120:123], v116 offset:49152
	ds_read_b128 v[124:127], v116 offset:51200
	ds_read_b128 v[128:131], v116 offset:53248
	ds_read_b128 v[132:135], v116 offset:55296
	s_add_i32 s11, s11, 2
	s_waitcnt lgkmcnt(0)
	v_mfma_f32_16x16x32_f16 v[0:3], v[120:123], v[82:85], v[0:3]
	ds_read_b128 v[136:139], v117 offset:32768
	v_mfma_f32_16x16x32_f16 v[4:7], v[124:127], v[82:85], v[4:7]
	v_mfma_f32_16x16x32_f16 v[8:11], v[128:131], v[82:85], v[8:11]
	ds_read_b128 v[140:143], v117 offset:34816
	v_mfma_f32_16x16x32_f16 v[12:15], v[132:135], v[82:85], v[12:15]
	v_mfma_f32_16x16x32_f16 v[16:19], v[120:123], v[86:89], v[16:19]
	ds_read_b128 v[144:147], v117 offset:36864
	v_mfma_f32_16x16x32_f16 v[20:23], v[124:127], v[86:89], v[20:23]
	v_mfma_f32_16x16x32_f16 v[24:27], v[128:131], v[86:89], v[24:27]
	ds_read_b128 v[148:151], v117 offset:38912
	v_mfma_f32_16x16x32_f16 v[28:31], v[132:135], v[86:89], v[28:31]
	v_mfma_f32_16x16x32_f16 v[82:85], v[120:123], v[90:93], v[32:35]
	ds_read_b128 v[152:155], v118 offset:49152
	v_mfma_f32_16x16x32_f16 v[86:89], v[124:127], v[90:93], v[36:39]
	v_mfma_f32_16x16x32_f16 v[168:171], v[128:131], v[90:93], v[40:43]
	ds_read_b128 v[156:159], v118 offset:51200
	v_mfma_f32_16x16x32_f16 v[90:93], v[132:135], v[90:93], v[44:47]
	v_mfma_f32_16x16x32_f16 v[120:123], v[120:123], v[94:97], v[48:51]
	ds_read_b128 v[160:163], v118 offset:53248
	v_mfma_f32_16x16x32_f16 v[124:127], v[124:127], v[94:97], v[52:55]
	v_mfma_f32_16x16x32_f16 v[128:131], v[128:131], v[94:97], v[56:59]
	ds_read_b128 v[164:167], v118 offset:55296
	v_mfma_f32_16x16x32_f16 v[94:97], v[132:135], v[94:97], v[60:63]
	s_waitcnt lgkmcnt(0)
	s_barrier
	s_and_b64 vcc, exec, s[18:19]
	s_cbranch_vccnz .Lgp_os_8
	s_add_u32 s98, s16, s6
	s_addc_u32 s99, s17, s7
	s_add_u32 s98, s98, 0x80
	s_addc_u32 s99, s99, 0
	s_add_u32 s100, s16, s8
	s_addc_u32 s101, s17, s9
	s_add_u32 s100, s100, 0x80
	s_addc_u32 s101, s101, 0
	v_readfirstlane_b32 s13, v64
	v_mfma_f32_16x16x32_f16 v[60:63], v[152:155], v[136:139], v[0:3]
	v_lshl_add_u64 v[250:251], v[66:67], 0, s[98:99]
	s_mov_b32 m0, s13
	v_readfirstlane_b32 s13, v108
	global_load_lds_dwordx4 v[250:251], off
	v_mfma_f32_16x16x32_f16 v[52:55], v[156:159], v[136:139], v[4:7]
	v_mfma_f32_16x16x32_f16 v[56:59], v[160:163], v[136:139], v[8:11]
	v_lshl_add_u64 v[250:251], v[68:69], 0, s[98:99]
	s_mov_b32 m0, s13
	v_readfirstlane_b32 s13, v109
	global_load_lds_dwordx4 v[250:251], off
	v_mfma_f32_16x16x32_f16 v[48:51], v[164:167], v[136:139], v[12:15]
	v_mfma_f32_16x16x32_f16 v[44:47], v[152:155], v[140:143], v[16:19]
	v_lshl_add_u64 v[250:251], v[70:71], 0, s[98:99]
	s_mov_b32 m0, s13
	v_readfirstlane_b32 s13, v110
	global_load_lds_dwordx4 v[250:251], off
	v_mfma_f32_16x16x32_f16 v[36:39], v[156:159], v[140:143], v[20:23]
	v_mfma_f32_16x16x32_f16 v[40:43], v[160:163], v[140:143], v[24:27]
	v_lshl_add_u64 v[250:251], v[72:73], 0, s[98:99]
	s_mov_b32 m0, s13
	v_readfirstlane_b32 s13, v111
	global_load_lds_dwordx4 v[250:251], off
	v_mfma_f32_16x16x32_f16 v[32:35], v[164:167], v[140:143], v[28:31]
	v_mfma_f32_16x16x32_f16 v[28:31], v[152:155], v[144:147], v[82:85]
	v_lshl_add_u64 v[250:251], v[74:75], 0, s[100:101]
	s_mov_b32 m0, s13
	v_readfirstlane_b32 s13, v112
	global_load_lds_dwordx4 v[250:251], off
	v_mfma_f32_16x16x32_f16 v[20:23], v[156:159], v[144:147], v[86:89]
	v_mfma_f32_16x16x32_f16 v[24:27], v[160:163], v[144:147], v[168:171]
	v_lshl_add_u64 v[250:251], v[76:77], 0, s[100:101]
	s_mov_b32 m0, s13
	v_readfirstlane_b32 s13, v113
	global_load_lds_dwordx4 v[250:251], off
	v_mfma_f32_16x16x32_f16 v[16:19], v[164:167], v[144:147], v[90:93]
	v_mfma_f32_16x16x32_f16 v[12:15], v[152:155], v[148:151], v[120:123]
	v_lshl_add_u64 v[250:251], v[78:79], 0, s[100:101]
	s_mov_b32 m0, s13
	v_readfirstlane_b32 s13, v114
	global_load_lds_dwordx4 v[250:251], off
	v_mfma_f32_16x16x32_f16 v[4:7], v[156:159], v[148:151], v[124:127]
	v_mfma_f32_16x16x32_f16 v[8:11], v[160:163], v[148:151], v[128:131]
	v_lshl_add_u64 v[250:251], v[80:81], 0, s[100:101]
	s_mov_b32 m0, s13
	s_nop 0
	global_load_lds_dwordx4 v[250:251], off
	v_mfma_f32_16x16x32_f16 v[0:3], v[164:167], v[148:151], v[94:97]
	s_branch .Lgp_oj_8

.LBB0_1867:
	s_waitcnt vmcnt(8)
	s_barrier
	s_nop 1
	ds_read_b128 v[120:123], v115
	ds_read_b128 v[124:127], v115 offset:2048
	ds_read_b128 v[128:131], v115 offset:4096
	ds_read_b128 v[132:135], v115 offset:6144
	ds_read_b128 v[136:139], v116 offset:16384
	ds_read_b128 v[140:143], v116 offset:18432
	ds_read_b128 v[144:147], v116 offset:20480
	ds_read_b128 v[148:151], v116 offset:22528
	s_cmp_gt_u32 s11, 13
	s_cselect_b64 s[18:19], -1, 0
	s_waitcnt lgkmcnt(0)
	v_mfma_f32_16x16x32_f16 v[60:63], v[136:139], v[120:123], v[60:63]
	ds_read_b128 v[152:155], v117
	v_mfma_f32_16x16x32_f16 v[52:55], v[140:143], v[120:123], v[52:55]
	v_mfma_f32_16x16x32_f16 v[56:59], v[144:147], v[120:123], v[56:59]
	ds_read_b128 v[156:159], v117 offset:2048
	v_mfma_f32_16x16x32_f16 v[48:51], v[148:151], v[120:123], v[48:51]
	v_mfma_f32_16x16x32_f16 v[44:47], v[136:139], v[124:127], v[44:47]
	ds_read_b128 v[160:163], v117 offset:4096
	v_mfma_f32_16x16x32_f16 v[36:39], v[140:143], v[124:127], v[36:39]
	v_mfma_f32_16x16x32_f16 v[40:43], v[144:147], v[124:127], v[40:43]
	ds_read_b128 v[164:167], v117 offset:6144
	v_mfma_f32_16x16x32_f16 v[32:35], v[148:151], v[124:127], v[32:35]
	v_mfma_f32_16x16x32_f16 v[120:123], v[136:139], v[128:131], v[28:31]
	ds_read_b128 v[168:171], v118 offset:16384
	v_mfma_f32_16x16x32_f16 v[124:127], v[140:143], v[128:131], v[20:23]
	v_mfma_f32_16x16x32_f16 v[188:191], v[144:147], v[128:131], v[24:27]
	ds_read_b128 v[176:179], v118 offset:18432
	v_mfma_f32_16x16x32_f16 v[128:131], v[148:151], v[128:131], v[16:19]
	v_mfma_f32_16x16x32_f16 v[136:139], v[136:139], v[132:135], v[12:15]
	ds_read_b128 v[180:183], v118 offset:20480
	v_mfma_f32_16x16x32_f16 v[140:143], v[140:143], v[132:135], v[4:7]
	v_mfma_f32_16x16x32_f16 v[144:147], v[144:147], v[132:135], v[8:11]
	ds_read_b128 v[184:187], v118 offset:22528
	v_mfma_f32_16x16x32_f16 v[132:135], v[148:151], v[132:135], v[0:3]
	s_waitcnt lgkmcnt(0)
	s_barrier
	s_and_b64 vcc, exec, s[18:19]
	s_cbranch_vccnz .Lgp_es_8
	s_add_u32 s98, s16, s6
	s_addc_u32 s99, s17, s7
	s_add_u32 s100, s16, s8
	s_addc_u32 s101, s17, s9
	v_readfirstlane_b32 s13, v100
	v_mfma_f32_16x16x32_f16 v[0:3], v[168:171], v[152:155], v[60:63]
	v_lshl_add_u64 v[250:251], v[66:67], 0, s[98:99]
	s_mov_b32 m0, s13
	v_readfirstlane_b32 s13, v101
	global_load_lds_dwordx4 v[250:251], off
	v_mfma_f32_16x16x32_f16 v[4:7], v[176:179], v[152:155], v[52:55]
	v_mfma_f32_16x16x32_f16 v[8:11], v[180:183], v[152:155], v[56:59]
	v_lshl_add_u64 v[250:251], v[68:69], 0, s[98:99]
	s_mov_b32 m0, s13
	v_readfirstlane_b32 s13, v102
	global_load_lds_dwordx4 v[250:251], off
	v_mfma_f32_16x16x32_f16 v[12:15], v[184:187], v[152:155], v[48:51]
	v_mfma_f32_16x16x32_f16 v[16:19], v[168:171], v[156:159], v[44:47]
	v_lshl_add_u64 v[250:251], v[70:71], 0, s[98:99]
	s_mov_b32 m0, s13
	v_readfirstlane_b32 s13, v103
	global_load_lds_dwordx4 v[250:251], off
	v_mfma_f32_16x16x32_f16 v[20:23], v[176:179], v[156:159], v[36:39]
	v_mfma_f32_16x16x32_f16 v[24:27], v[180:183], v[156:159], v[40:43]
	v_lshl_add_u64 v[250:251], v[72:73], 0, s[98:99]
	s_mov_b32 m0, s13
	v_readfirstlane_b32 s13, v104
	global_load_lds_dwordx4 v[250:251], off
	v_mfma_f32_16x16x32_f16 v[28:31], v[184:187], v[156:159], v[32:35]
	v_mfma_f32_16x16x32_f16 v[32:35], v[168:171], v[160:163], v[120:123]
	v_lshl_add_u64 v[250:251], v[74:75], 0, s[100:101]
	s_mov_b32 m0, s13
	v_readfirstlane_b32 s13, v105
	global_load_lds_dwordx4 v[250:251], off
	v_mfma_f32_16x16x32_f16 v[36:39], v[176:179], v[160:163], v[124:127]
	v_mfma_f32_16x16x32_f16 v[40:43], v[180:183], v[160:163], v[188:191]
	v_lshl_add_u64 v[250:251], v[76:77], 0, s[100:101]
	s_mov_b32 m0, s13
	v_readfirstlane_b32 s13, v106
	global_load_lds_dwordx4 v[250:251], off
	v_mfma_f32_16x16x32_f16 v[44:47], v[184:187], v[160:163], v[128:131]
	v_mfma_f32_16x16x32_f16 v[48:51], v[168:171], v[164:167], v[136:139]
	v_lshl_add_u64 v[250:251], v[78:79], 0, s[100:101]
	s_mov_b32 m0, s13
	v_readfirstlane_b32 s13, v107
	global_load_lds_dwordx4 v[250:251], off
	v_mfma_f32_16x16x32_f16 v[52:55], v[176:179], v[164:167], v[140:143]
	v_mfma_f32_16x16x32_f16 v[56:59], v[180:183], v[164:167], v[144:147]
	v_lshl_add_u64 v[250:251], v[80:81], 0, s[100:101]
	s_mov_b32 m0, s13
	s_nop 0
	global_load_lds_dwordx4 v[250:251], off
	v_mfma_f32_16x16x32_f16 v[60:63], v[184:187], v[164:167], v[132:135]
	s_branch .Lgp_ej_8

.Lgp_ej_8:
	s_branch .LBB0_1866
.LBB0_1869:
	s_waitcnt vmcnt(0)
	s_barrier
	s_mov_b64 s[0:1], exec
	v_readlane_b32 s4, v254, 1
	v_readlane_b32 s5, v254, 2
	s_and_b64 s[4:5], s[0:1], s[4:5]
	s_mov_b64 exec, s[4:5]
	s_cbranch_execz .LBB0_1921
	s_add_i32 s3, 0, 0x10000
	v_mov_b32_e32 v0, s3
	s_waitcnt vmcnt(0) expcnt(0) lgkmcnt(0)
	ds_read_b32 v2, v0
	s_add_i32 s3, 0, 0x10004
	v_mov_b32_e32 v0, s3
	ds_read_b32 v0, v0
	s_waitcnt lgkmcnt(1)
	v_cmp_ne_u32_e32 vcc, 0, v2
	s_cbranch_vccnz .LBB0_1885
	s_add_u32 s4, s50, 0x1000
	s_addc_u32 s5, s51, 0
	s_add_u32 s6, s50, 0x1100
	s_addc_u32 s7, s51, 0
	s_add_u32 s8, s50, 0x1200
	v_readlane_b32 s3, v254, 0
	s_addc_u32 s9, s51, 0
	s_mul_i32 s3, s29, s3
	s_add_u32 s10, s50, 0x1300
	s_mul_i32 s3, s3, s28
	s_addc_u32 s11, s51, 0
	s_mov_b32 s20, 1
	v_mov_b32_e32 v16, 0
	s_branch .LBB0_1873

.Lto_j_b5:
	s_mul_i32 s98, s98, 17
	s_add_u32 s98, s98, s99
	s_lshl_b32 s99, s98, 3
	s_or_b32 s99, s99, s13
	s_mul_hi_i32 s8, s98, 0x78787879
	s_lshr_b32 s9, s8, 31
	s_ashr_i32 s20, s8, 3
	s_add_i32 s20, s20, s9
	v_mov_b32_e32 v0, v174
	s_mul_i32 s8, s20, 0xffffffef
	s_add_i32 s8, s8, s98
	v_bfe_u32 v2, v0, 1, 3
	v_lshrrev_b32_e32 v3, 4, v0
	s_waitcnt vmcnt(5)
	v_bfe_u32 v4, v0, 4, 2
	v_lshlrev_b32_e32 v5, 7, v0
	v_and_b32_e32 v6, 0x780, v5
	v_bitop3_b32 v3, v3, v2, 3 bitop3:0x6c
	v_bitop3_b32 v2, v4, v2, 4 bitop3:0x36
	s_lshl_b32 s8, s8, 3
	v_lshl_or_b32 v7, v3, 4, v6
	v_lshl_or_b32 v6, v2, 4, v6
	v_lshlrev_b32_e32 v2, 6, v0
	s_or_b32 s21, s8, s13
	v_and_b32_e32 v8, 0xffffe000, v2
	v_lshlrev_b32_e32 v2, 4, v0
	s_mul_i32 s8, s21, 0xb0000
	v_lshrrev_b32_e32 v1, 3, v0
	v_add_u32_e32 v100, 0, v2
	s_mul_hi_i32 s9, s21, 0xb0000
	s_add_u32 s8, s42, s8
	v_mul_lo_u32 v1, v1, s18
	v_xor_b32_e32 v0, v2, v0
	v_readfirstlane_b32 s24, v100
	v_add_u32_e32 v101, 0x1000, v100
	s_addc_u32 s9, s43, s9
	v_and_or_b32 v64, v0, s19, v1
	s_mov_b32 m0, s24
	v_readfirstlane_b32 s24, v101
	v_add_u32_e32 v102, 0x2000, v100
	global_load_lds_dwordx4 v64, s[8:9]
	v_add_u32_e32 v0, 0x2c000, v64
	s_mov_b32 m0, s24
	v_readfirstlane_b32 s24, v102
	v_add_u32_e32 v103, 0x3000, v100
	global_load_lds_dwordx4 v0, s[8:9]
	v_add_u32_e32 v2, 0x58000, v64
	s_mov_b32 m0, s24
	v_readfirstlane_b32 s24, v103
	s_mul_i32 s23, s20, 0xb0000
	global_load_lds_dwordx4 v2, s[8:9]
	v_add_u32_e32 v4, 0x84000, v64
	s_mov_b32 m0, s24
	v_add_u32_e32 v104, 0x4000, v100
	s_mul_hi_i32 s22, s20, 0xb0000
	s_add_u32 s10, s88, s23
	global_load_lds_dwordx4 v4, s[8:9]
	v_readfirstlane_b32 s8, v104
	v_add_u32_e32 v105, 0x5000, v100
	s_addc_u32 s11, s89, s22
	s_mov_b32 m0, s8
	v_readfirstlane_b32 s8, v105
	v_add_u32_e32 v106, 0x6000, v100
	global_load_lds_dwordx4 v64, s[10:11]
	s_mov_b32 m0, s8
	v_readfirstlane_b32 s8, v106
	v_add_u32_e32 v107, 0x7000, v100
	global_load_lds_dwordx4 v0, s[10:11]
	s_mov_b32 m0, s8
	v_readfirstlane_b32 s8, v107
	global_load_lds_dwordx4 v2, s[10:11]
	s_mov_b32 m0, s8
	s_mul_i32 s8, s20, 0x88
	global_load_lds_dwordx4 v4, s[10:11]
	s_sub_i32 s8, s99, s8
	s_mul_hi_i32 s9, s8, 0xb0000
	s_mul_i32 s8, s8, 0xb0000
	s_add_u32 s8, s42, s8
	v_and_b32_e32 v9, 0x2000, v5
	v_mov_b32_e32 v1, v65
	v_mov_b32_e32 v3, v65
	v_mov_b32_e32 v5, v65
	s_addc_u32 s9, s43, s9
	v_lshl_add_u64 v[66:67], s[8:9], 0, v[64:65]
	v_lshl_add_u64 v[68:69], s[8:9], 0, v[0:1]
	v_lshl_add_u64 v[70:71], s[8:9], 0, v[2:3]
	v_lshl_add_u64 v[72:73], s[8:9], 0, v[4:5]
	s_add_u32 s8, s36, s23
	v_add_u32_e32 v8, 0, v8
	v_add_u32_e32 v9, 0, v9
	s_addc_u32 s9, s37, s22
	v_lshl_add_u64 v[74:75], s[8:9], 0, v[64:65]
	v_lshl_add_u64 v[76:77], s[8:9], 0, v[0:1]
	v_lshl_add_u64 v[78:79], s[8:9], 0, v[2:3]
	v_lshl_add_u64 v[80:81], s[8:9], 0, v[4:5]
	s_mov_b64 s[8:9], 0
	v_add_u32_e32 v64, 0x8000, v100
	v_add_u32_e32 v108, 0x9000, v100
	v_add_u32_e32 v109, 0xa000, v100
	v_add_u32_e32 v110, 0xb000, v100
	v_add_u32_e32 v111, 0xc000, v100
	v_add_u32_e32 v112, 0xd000, v100
	v_add_u32_e32 v113, 0xe000, v100
	v_add_u32_e32 v114, 0xf000, v100
	v_add_u32_e32 v115, v8, v7
	v_add_u32_e32 v116, v9, v7
	v_add_u32_e32 v117, v8, v6
	v_add_u32_e32 v118, v9, v6
	s_mov_b32 s22, 0
	v_mov_b32_e32 v0, 0
	v_mov_b32_e32 v2, v65
	v_mov_b32_e32 v4, 0
	v_mov_b32_e32 v6, v65
	v_mov_b32_e32 v7, v65
	v_mov_b32_e32 v8, 0
	v_mov_b32_e32 v9, v65
	v_mov_b32_e32 v10, v65
	v_mov_b32_e32 v11, v65
	v_mov_b32_e32 v12, 0
	v_mov_b32_e32 v13, v65
	v_mov_b32_e32 v14, v65
	v_mov_b32_e32 v15, v65
	v_mov_b32_e32 v16, 0
	v_mov_b32_e32 v17, v65
	v_mov_b32_e32 v18, v65
	v_mov_b32_e32 v19, v65
	v_mov_b32_e32 v20, 0
	v_mov_b32_e32 v21, v65
	v_mov_b32_e32 v22, v65
	v_mov_b32_e32 v23, v65
	v_mov_b32_e32 v24, 0
	v_mov_b32_e32 v25, v65
	v_mov_b32_e32 v26, v65
	v_mov_b32_e32 v27, v65
	v_mov_b32_e32 v28, 0
	v_mov_b32_e32 v29, v65
	v_mov_b32_e32 v30, v65
	v_mov_b32_e32 v31, v65
	v_mov_b32_e32 v32, 0
	v_mov_b32_e32 v33, v65
	v_mov_b32_e32 v34, v65
	v_mov_b32_e32 v35, v65
	v_mov_b32_e32 v36, 0
	v_mov_b32_e32 v37, v65
	v_mov_b32_e32 v38, v65
	v_mov_b32_e32 v39, v65
	v_mov_b32_e32 v40, 0
	v_mov_b32_e32 v41, v65
	v_mov_b32_e32 v42, v65
	v_mov_b32_e32 v43, v65
	v_mov_b32_e32 v44, 0
	v_mov_b32_e32 v45, v65
	v_mov_b32_e32 v46, v65
	v_mov_b32_e32 v47, v65
	v_mov_b32_e32 v48, 0
	v_mov_b32_e32 v49, v65
	v_mov_b32_e32 v50, v65
	v_mov_b32_e32 v51, v65
	v_mov_b32_e32 v52, 0
	v_mov_b32_e32 v53, v65
	s_waitcnt vmcnt(0)
	v_mov_b32_e32 v54, v65
	v_mov_b32_e32 v55, v65
	v_mov_b32_e32 v56, 0
	v_mov_b32_e32 v57, v65
	v_mov_b32_e32 v58, v65
	v_mov_b32_e32 v59, v65
	v_mov_b32_e32 v60, 0
	v_mov_b32_e32 v61, v65
	v_mov_b32_e32 v62, v65
	v_mov_b32_e32 v63, v65
	s_mov_b64 s[98:99], s[0:1]
	s_mov_b64 s[100:101], s[2:3]
	v_readfirstlane_b32 s23, v64
	v_lshl_add_u64 v[250:251], v[66:67], 0, s[98:99]
	s_mov_b32 m0, s23
	v_readfirstlane_b32 s23, v108
	global_load_lds_dwordx4 v[250:251], off
	v_lshl_add_u64 v[250:251], v[68:69], 0, s[98:99]
	s_mov_b32 m0, s23
	v_readfirstlane_b32 s23, v109
	global_load_lds_dwordx4 v[250:251], off
	v_lshl_add_u64 v[250:251], v[70:71], 0, s[98:99]
	s_mov_b32 m0, s23
	v_readfirstlane_b32 s23, v110
	global_load_lds_dwordx4 v[250:251], off
	v_lshl_add_u64 v[250:251], v[72:73], 0, s[98:99]
	s_mov_b32 m0, s23
	v_readfirstlane_b32 s23, v111
	global_load_lds_dwordx4 v[250:251], off
	v_lshl_add_u64 v[250:251], v[74:75], 0, s[100:101]
	s_mov_b32 m0, s23
	v_readfirstlane_b32 s23, v112
	global_load_lds_dwordx4 v[250:251], off
	v_lshl_add_u64 v[250:251], v[76:77], 0, s[100:101]
	s_mov_b32 m0, s23
	v_readfirstlane_b32 s23, v113
	global_load_lds_dwordx4 v[250:251], off
	v_lshl_add_u64 v[250:251], v[78:79], 0, s[100:101]
	s_mov_b32 m0, s23
	v_readfirstlane_b32 s23, v114
	global_load_lds_dwordx4 v[250:251], off
	v_lshl_add_u64 v[250:251], v[80:81], 0, s[100:101]
	s_mov_b32 m0, s23
	s_nop 0
	global_load_lds_dwordx4 v[250:251], off
	s_branch .LBB0_1936
.LBB0_1935:
	s_and_b64 vcc, exec, s[10:11]
	s_cbranch_vccnz .Lgp_ol_9
	s_waitcnt vmcnt(8)
	s_branch .Lgp_og_9

.Lgp_og_9:
	s_barrier
	s_nop 1
	ds_read_b128 v[82:85], v115 offset:32768
	ds_read_b128 v[86:89], v115 offset:34816
	ds_read_b128 v[90:93], v115 offset:36864
	ds_read_b128 v[94:97], v115 offset:38912
	ds_read_b128 v[120:123], v116 offset:49152
	ds_read_b128 v[124:127], v116 offset:51200
	ds_read_b128 v[128:131], v116 offset:53248
	ds_read_b128 v[132:135], v116 offset:55296
	s_add_i32 s22, s22, 2
	s_waitcnt lgkmcnt(0)
	v_mfma_f32_16x16x32_f16 v[0:3], v[120:123], v[82:85], v[0:3]
	ds_read_b128 v[136:139], v117 offset:32768
	v_mfma_f32_16x16x32_f16 v[4:7], v[124:127], v[82:85], v[4:7]
	v_mfma_f32_16x16x32_f16 v[8:11], v[128:131], v[82:85], v[8:11]
	ds_read_b128 v[140:143], v117 offset:34816
	v_mfma_f32_16x16x32_f16 v[12:15], v[132:135], v[82:85], v[12:15]
	v_mfma_f32_16x16x32_f16 v[16:19], v[120:123], v[86:89], v[16:19]
	ds_read_b128 v[144:147], v117 offset:36864
	v_mfma_f32_16x16x32_f16 v[20:23], v[124:127], v[86:89], v[20:23]
	v_mfma_f32_16x16x32_f16 v[24:27], v[128:131], v[86:89], v[24:27]
	ds_read_b128 v[148:151], v117 offset:38912
	v_mfma_f32_16x16x32_f16 v[28:31], v[132:135], v[86:89], v[28:31]
	v_mfma_f32_16x16x32_f16 v[82:85], v[120:123], v[90:93], v[32:35]
	ds_read_b128 v[152:155], v118 offset:49152
	v_mfma_f32_16x16x32_f16 v[86:89], v[124:127], v[90:93], v[36:39]
	v_mfma_f32_16x16x32_f16 v[168:171], v[128:131], v[90:93], v[40:43]
	ds_read_b128 v[156:159], v118 offset:51200
	v_mfma_f32_16x16x32_f16 v[90:93], v[132:135], v[90:93], v[44:47]
	v_mfma_f32_16x16x32_f16 v[120:123], v[120:123], v[94:97], v[48:51]
	ds_read_b128 v[160:163], v118 offset:53248
	v_mfma_f32_16x16x32_f16 v[124:127], v[124:127], v[94:97], v[52:55]
	v_mfma_f32_16x16x32_f16 v[128:131], v[128:131], v[94:97], v[56:59]
	ds_read_b128 v[164:167], v118 offset:55296
	v_mfma_f32_16x16x32_f16 v[94:97], v[132:135], v[94:97], v[60:63]
	s_waitcnt lgkmcnt(0)
	s_barrier
	s_and_b64 vcc, exec, s[10:11]
	s_cbranch_vccnz .Lgp_os_9
	s_add_u32 s98, s8, s4
	s_addc_u32 s99, s9, s5
	s_add_u32 s98, s98, 0x80
	s_addc_u32 s99, s99, 0
	s_add_u32 s100, s8, s6
	s_addc_u32 s101, s9, s7
	s_add_u32 s100, s100, 0x80
	s_addc_u32 s101, s101, 0
	v_readfirstlane_b32 s23, v64
	v_mfma_f32_16x16x32_f16 v[60:63], v[152:155], v[136:139], v[0:3]
	v_lshl_add_u64 v[250:251], v[66:67], 0, s[98:99]
	s_mov_b32 m0, s23
	v_readfirstlane_b32 s23, v108
	global_load_lds_dwordx4 v[250:251], off
	v_mfma_f32_16x16x32_f16 v[56:59], v[156:159], v[136:139], v[4:7]
	v_mfma_f32_16x16x32_f16 v[52:55], v[160:163], v[136:139], v[8:11]
	v_lshl_add_u64 v[250:251], v[68:69], 0, s[98:99]
	s_mov_b32 m0, s23
	v_readfirstlane_b32 s23, v109
	global_load_lds_dwordx4 v[250:251], off
	v_mfma_f32_16x16x32_f16 v[48:51], v[164:167], v[136:139], v[12:15]
	v_mfma_f32_16x16x32_f16 v[44:47], v[152:155], v[140:143], v[16:19]
	v_lshl_add_u64 v[250:251], v[70:71], 0, s[98:99]
	s_mov_b32 m0, s23
	v_readfirstlane_b32 s23, v110
	global_load_lds_dwordx4 v[250:251], off
	v_mfma_f32_16x16x32_f16 v[40:43], v[156:159], v[140:143], v[20:23]
	v_mfma_f32_16x16x32_f16 v[36:39], v[160:163], v[140:143], v[24:27]
	v_lshl_add_u64 v[250:251], v[72:73], 0, s[98:99]
	s_mov_b32 m0, s23
	v_readfirstlane_b32 s23, v111
	global_load_lds_dwordx4 v[250:251], off
	v_mfma_f32_16x16x32_f16 v[32:35], v[164:167], v[140:143], v[28:31]
	v_mfma_f32_16x16x32_f16 v[28:31], v[152:155], v[144:147], v[82:85]
	v_lshl_add_u64 v[250:251], v[74:75], 0, s[100:101]
	s_mov_b32 m0, s23
	v_readfirstlane_b32 s23, v112
	global_load_lds_dwordx4 v[250:251], off
	v_mfma_f32_16x16x32_f16 v[24:27], v[156:159], v[144:147], v[86:89]
	v_mfma_f32_16x16x32_f16 v[20:23], v[160:163], v[144:147], v[168:171]
	v_lshl_add_u64 v[250:251], v[76:77], 0, s[100:101]
	s_mov_b32 m0, s23
	v_readfirstlane_b32 s23, v113
	global_load_lds_dwordx4 v[250:251], off
	v_mfma_f32_16x16x32_f16 v[16:19], v[164:167], v[144:147], v[90:93]
	v_mfma_f32_16x16x32_f16 v[12:15], v[152:155], v[148:151], v[120:123]
	v_lshl_add_u64 v[250:251], v[78:79], 0, s[100:101]
	s_mov_b32 m0, s23
	v_readfirstlane_b32 s23, v114
	global_load_lds_dwordx4 v[250:251], off
	v_mfma_f32_16x16x32_f16 v[8:11], v[156:159], v[148:151], v[124:127]
	v_mfma_f32_16x16x32_f16 v[4:7], v[160:163], v[148:151], v[128:131]
	v_lshl_add_u64 v[250:251], v[80:81], 0, s[100:101]
	s_mov_b32 m0, s23
	s_nop 0
	global_load_lds_dwordx4 v[250:251], off
	v_mfma_f32_16x16x32_f16 v[0:3], v[164:167], v[148:151], v[94:97]
	s_branch .Lgp_oj_9

.Lgp_oj_9:
	s_add_u32 s8, s8, 0x100
	s_addc_u32 s9, s9, 0
	s_andn2_b64 vcc, exec, s[10:11]
	s_cbranch_vccz .LBB0_1933
.LBB0_1936:
	s_waitcnt vmcnt(8)
	s_barrier
	s_nop 1
	ds_read_b128 v[120:123], v115
	ds_read_b128 v[124:127], v115 offset:2048
	ds_read_b128 v[128:131], v115 offset:4096
	ds_read_b128 v[132:135], v115 offset:6144
	ds_read_b128 v[136:139], v116 offset:16384
	ds_read_b128 v[140:143], v116 offset:18432
	ds_read_b128 v[144:147], v116 offset:20480
	ds_read_b128 v[148:151], v116 offset:22528
	s_cmp_gt_u32 s22, 41
	s_cselect_b64 s[10:11], -1, 0
	s_waitcnt lgkmcnt(0)
	v_mfma_f32_16x16x32_f16 v[60:63], v[136:139], v[120:123], v[60:63]
	ds_read_b128 v[152:155], v117
	v_mfma_f32_16x16x32_f16 v[56:59], v[140:143], v[120:123], v[56:59]
	v_mfma_f32_16x16x32_f16 v[52:55], v[144:147], v[120:123], v[52:55]
	ds_read_b128 v[156:159], v117 offset:2048
	v_mfma_f32_16x16x32_f16 v[48:51], v[148:151], v[120:123], v[48:51]
	v_mfma_f32_16x16x32_f16 v[44:47], v[136:139], v[124:127], v[44:47]
	ds_read_b128 v[160:163], v117 offset:4096
	v_mfma_f32_16x16x32_f16 v[40:43], v[140:143], v[124:127], v[40:43]
	v_mfma_f32_16x16x32_f16 v[36:39], v[144:147], v[124:127], v[36:39]
	ds_read_b128 v[164:167], v117 offset:6144
	v_mfma_f32_16x16x32_f16 v[32:35], v[148:151], v[124:127], v[32:35]
	v_mfma_f32_16x16x32_f16 v[120:123], v[136:139], v[128:131], v[28:31]
	ds_read_b128 v[168:171], v118 offset:16384
	v_mfma_f32_16x16x32_f16 v[124:127], v[140:143], v[128:131], v[24:27]
	v_mfma_f32_16x16x32_f16 v[188:191], v[144:147], v[128:131], v[20:23]
	ds_read_b128 v[176:179], v118 offset:18432
	v_mfma_f32_16x16x32_f16 v[128:131], v[148:151], v[128:131], v[16:19]
	v_mfma_f32_16x16x32_f16 v[136:139], v[136:139], v[132:135], v[12:15]
	ds_read_b128 v[180:183], v118 offset:20480
	v_mfma_f32_16x16x32_f16 v[140:143], v[140:143], v[132:135], v[8:11]
	v_mfma_f32_16x16x32_f16 v[144:147], v[144:147], v[132:135], v[4:7]
	ds_read_b128 v[184:187], v118 offset:22528
	v_mfma_f32_16x16x32_f16 v[132:135], v[148:151], v[132:135], v[0:3]
	s_waitcnt lgkmcnt(0)
	s_barrier
	s_and_b64 vcc, exec, s[10:11]
	s_cbranch_vccnz .Lgp_es_9
	s_add_u32 s98, s8, s4
	s_addc_u32 s99, s9, s5
	s_add_u32 s100, s8, s6
	s_addc_u32 s101, s9, s7
	v_readfirstlane_b32 s23, v100
	v_mfma_f32_16x16x32_f16 v[0:3], v[168:171], v[152:155], v[60:63]
	v_lshl_add_u64 v[250:251], v[66:67], 0, s[98:99]
	s_mov_b32 m0, s23
	v_readfirstlane_b32 s23, v101
	global_load_lds_dwordx4 v[250:251], off
	v_mfma_f32_16x16x32_f16 v[4:7], v[176:179], v[152:155], v[56:59]
	v_mfma_f32_16x16x32_f16 v[8:11], v[180:183], v[152:155], v[52:55]
	v_lshl_add_u64 v[250:251], v[68:69], 0, s[98:99]
	s_mov_b32 m0, s23
	v_readfirstlane_b32 s23, v102
	global_load_lds_dwordx4 v[250:251], off
	v_mfma_f32_16x16x32_f16 v[12:15], v[184:187], v[152:155], v[48:51]
	v_mfma_f32_16x16x32_f16 v[16:19], v[168:171], v[156:159], v[44:47]
	v_lshl_add_u64 v[250:251], v[70:71], 0, s[98:99]
	s_mov_b32 m0, s23
	v_readfirstlane_b32 s23, v103
	global_load_lds_dwordx4 v[250:251], off
	v_mfma_f32_16x16x32_f16 v[20:23], v[176:179], v[156:159], v[40:43]
	v_mfma_f32_16x16x32_f16 v[24:27], v[180:183], v[156:159], v[36:39]
	v_lshl_add_u64 v[250:251], v[72:73], 0, s[98:99]
	s_mov_b32 m0, s23
	v_readfirstlane_b32 s23, v104
	global_load_lds_dwordx4 v[250:251], off
	v_mfma_f32_16x16x32_f16 v[28:31], v[184:187], v[156:159], v[32:35]
	v_mfma_f32_16x16x32_f16 v[32:35], v[168:171], v[160:163], v[120:123]
	v_lshl_add_u64 v[250:251], v[74:75], 0, s[100:101]
	s_mov_b32 m0, s23
	v_readfirstlane_b32 s23, v105
	global_load_lds_dwordx4 v[250:251], off
	v_mfma_f32_16x16x32_f16 v[36:39], v[176:179], v[160:163], v[124:127]
	v_mfma_f32_16x16x32_f16 v[40:43], v[180:183], v[160:163], v[188:191]
	v_lshl_add_u64 v[250:251], v[76:77], 0, s[100:101]
	s_mov_b32 m0, s23
	v_readfirstlane_b32 s23, v106
	global_load_lds_dwordx4 v[250:251], off
	v_mfma_f32_16x16x32_f16 v[44:47], v[184:187], v[160:163], v[128:131]
	v_mfma_f32_16x16x32_f16 v[48:51], v[168:171], v[164:167], v[136:139]
	v_lshl_add_u64 v[250:251], v[78:79], 0, s[100:101]
	s_mov_b32 m0, s23
	v_readfirstlane_b32 s23, v107
	global_load_lds_dwordx4 v[250:251], off
	v_mfma_f32_16x16x32_f16 v[52:55], v[176:179], v[164:167], v[140:143]
	v_mfma_f32_16x16x32_f16 v[56:59], v[180:183], v[164:167], v[144:147]
	v_lshl_add_u64 v[250:251], v[80:81], 0, s[100:101]
	s_mov_b32 m0, s23
	s_nop 0
	global_load_lds_dwordx4 v[250:251], off
	v_mfma_f32_16x16x32_f16 v[60:63], v[184:187], v[164:167], v[132:135]
	s_branch .Lgp_ej_9

.Lgp_ej_9:
	s_branch .LBB0_1935
.LBB0_1938:
	s_waitcnt vmcnt(0)
	s_barrier
	s_mov_b64 s[0:1], exec
	v_readlane_b32 s2, v254, 1
	v_readlane_b32 s3, v254, 2
	s_and_b64 s[2:3], s[0:1], s[2:3]
	s_mov_b64 exec, s[2:3]
	s_cbranch_execz .LBB0_1990
	s_add_i32 s2, 0, 0x10000
	v_mov_b32_e32 v0, s2
	s_waitcnt vmcnt(0) expcnt(0) lgkmcnt(0)
	ds_read_b32 v2, v0
	s_add_i32 s2, 0, 0x10004
	v_mov_b32_e32 v0, s2
	ds_read_b32 v0, v0
	s_waitcnt lgkmcnt(1)
	v_cmp_ne_u32_e32 vcc, 0, v2
	s_cbranch_vccnz .LBB0_1954
	v_readlane_b32 s2, v254, 0
	s_mul_i32 s15, s29, s2
	s_add_u32 s2, s50, 0x1000
	s_addc_u32 s3, s51, 0
	s_add_u32 s4, s50, 0x1100
	s_addc_u32 s5, s51, 0
	s_add_u32 s6, s50, 0x1200
	s_addc_u32 s7, s51, 0
	s_add_u32 s8, s50, 0x1300
	s_mul_i32 s15, s15, s28
	s_addc_u32 s9, s51, 0
	s_mov_b32 s18, 1
	v_mov_b32_e32 v16, 0
	s_branch .LBB0_1942
